# 64-bit VALU moves split into 32-bit pairs (instruction selection)
# speedup vs baseline: 1.0067x; 1.0051x over previous
; #define LAS __attribute__((address_space(3)))
; __global__ void __launch_bounds__(NTHREADS, 2) fwd_megakernel(Args a) {
;     ...
;     volatile LAS unsigned* bst = (volatile LAS unsigned*)(ldsl + 131072 + 512);
;     if (tid < 2) bst[tid] = 0u;
;     unsigned* barw = (unsigned*)(ws + WS_CTL);
;     if (bx == 0) for (int i = tid; i < XCD_BAR_WORDS; i += NTHREADS) barw[i] = 0u;
.LBB0_2:
	s_load_dword s4, s[0:1], 0xc8
	s_load_dwordx16 s[16:31], s[0:1], 0x80
	v_cmp_gt_u32_e32 vcc, 2, v222
	s_waitcnt lgkmcnt(0)
	v_writelane_b32 v254, s4, 1
	s_and_saveexec_b64 s[4:5], vcc
	v_mov_b32_e32 v1, 0x20200
	v_lshl_add_u32 v1, v222, 2, v1
	v_mov_b32_e32 v2, 0
	ds_write_b32 v1, v2
	s_or_b64 exec, exec, s[4:5]
	s_add_u32 s90, s30, 0x1bbc0000
	s_addc_u32 s91, s31, 0
	s_cmp_lg_u32 s2, 0
	s_mov_b32 s6, 0
	s_cbranch_scc1 .LBB0_12
	v_sub_u32_e32 v1, 0xd7f, v222
	v_lshrrev_b32_e32 v2, 9, v1
	v_add_u32_e32 v1, 2, v2
	v_add_u32_e32 v223, 0x200, v222
	v_and_b32_e32 v3, 14, v1
	v_mov_b32_e32 v1, v2
	s_mov_b64 s[8:9], 0
	s_mov_b32 s7, 1
	v_mov_b32_e32 v5, 0
	s_mov_b32 s12, s6
	v_mov_b32_e32 v6, v222
	v_mov_b32_e32 v7, v223
	s_branch .LBB0_7

; #define LAS __attribute__((address_space(3)))
; __global__ void __launch_bounds__(NTHREADS, 2) fwd_megakernel(Args a) {
;     ...
;         for (int it = bx; it < 192; it += G) {
;             LAS float* sl = (LAS float*)ldsl;
;             LAS float* part = sl + 5 * 1024;
;             for (int i = tid; i < 5 * 1024; i += NTHREADS) { const float cv = (i < 4096) ? a.c[i] : a.c_ctx[i - 4096]; sl[i] = cv / (1.0f + __expf(-cv)); }
;             __syncthreads();
;             const int l = it / 96, n = (it % 96) * 64 + lane; const float* wp = a.ada_w + (size_t)l * DMODEL * NMOD6 + n;
;             float acc[5] = {0.f, 0.f, 0.f, 0.f, 0.f};
; #pragma unroll 32
;             for (int k = wave * 128; k < wave * 128 + 128; ++k) { const float w = wp[(size_t)k * NMOD6];
; #pragma unroll
;                 for (int s = 0; s < 5; ++s) acc[s] += sl[s * 1024 + k] * w; }
.LBB0_15:
	s_mov_b64 s[52:53], 0
	v_mov_b32_e32 v7, v2
	v_mov_b32_e32 v14, v12
	v_mov_b32_e32 v15, v13
	v_mov_b32_e32 v16, v10
	v_mov_b32_e32 v17, v11
	v_mov_b32_e32 v18, v222

; __global__ void __launch_bounds__(NTHREADS, 2) fwd_megakernel(Args a) {
;     ...
;             for (int s = 0; s < 5; ++s) part[(wave * 5 + s) * 64 + lane] = acc[s];
;             __syncthreads();
;             if (tid < 320) { const int s = tid / 64, ln = tid % 64; float t = a.ada_b[l * NMOD6 + (it % 96) * 64 + ln];
; #pragma unroll
;                 for (int w = 0; w < 8; ++w) t += part[(w * 5 + s) * 64 + ln];
;                 MOD[(size_t)(l * 5 + s) * NMOD6 + (it % 96) * 64 + ln] = t; }
.LBB0_24:
	v_add_u32_e32 v14, s15, v1
	ds_write2st64_b32 v14, v20, v21 offset0:80 offset1:81
	ds_write2st64_b32 v14, v18, v19 offset0:82 offset1:83
	ds_write_b32 v14, v7 offset:21504
	s_waitcnt lgkmcnt(0)
	s_barrier
	s_and_saveexec_b64 s[54:55], s[8:9]
	s_cbranch_execz .LBB0_14
	s_add_i32 s64, s64, s52
	v_or_b32_e32 v14, s64, v4
	v_ashrrev_i32_e32 v15, 31, v14
	v_lshl_add_u64 v[14:15], v[14:15], 2, s[46:47]
	global_load_dword v7, v[14:15], off
	ds_read2st64_b32 v[14:15], v5 offset0:80 offset1:85
	ds_read2st64_b32 v[16:17], v5 offset0:90 offset1:95
	ds_read2st64_b32 v[18:19], v5 offset0:100 offset1:105
	ds_read2st64_b32 v[20:21], v5 offset0:110 offset1:115
	v_mov_b32_e32 v24, s68
	v_mov_b32_e32 v25, s69
	s_waitcnt vmcnt(0)
	v_mad_u64_u32 v[22:23], s[64:65], s53, 5, v[6:7]
	s_waitcnt lgkmcnt(3)
	v_add_f32_e32 v7, v7, v14
	v_add_f32_e32 v7, v7, v15
	s_waitcnt lgkmcnt(2)
	v_add_f32_e32 v7, v7, v16
	v_add_f32_e32 v7, v7, v17
	s_waitcnt lgkmcnt(1)
	v_add_f32_e32 v7, v7, v18
	s_ashr_i32 s53, s52, 31
	v_mad_i64_i32 v[22:23], s[64:65], v22, s57, v[24:25]
	v_add_f32_e32 v7, v7, v19
	v_lshl_add_u64 v[22:23], s[52:53], 2, v[22:23]
	s_waitcnt lgkmcnt(0)
	v_add_f32_e32 v7, v7, v20
	v_add_f32_e32 v7, v7, v21
	v_lshl_add_u64 v[14:15], v[22:23], 0, v[8:9]
	global_store_dword v[14:15], v7, off
	s_branch .LBB0_14

; __device__ __forceinline__ void norm_mod_phase(const float* lat, long lat_bs, const float* cx, long ctx_bs, const float* modl, int shoff, int scoff, bf16* XN, int skip_ctx, int gw, int NGW, float* xcopy, const float* part, int nkc, const float* pgate) {
;     int t_ = threadIdx.x; asm volatile("" : "+v"(t_)); const int lane = t_ & 63;
;     f32x4 vn[4]; int sn = 0;
;     { if (gw < MROWS) { const float* src = row_src(gw, lat, lat_bs, cx, ctx_bs, sn); const f32x4* xr = (const f32x4*)src + lane;
; #pragma unroll
;         for (int j = 0; j < 4; ++j) vn[j] = xr[64 * j]; } }
;     for (int row = gw; row < MROWS; row += NGW) {
;         const int s = sn; f32x4 v[4]; float ss = 0.f;
; #pragma unroll
;         for (int j = 0; j < 4; ++j) v[j] = vn[j];
;         if (row + NGW < MROWS) { const float* srcn = row_src(row + NGW, lat, lat_bs, cx, ctx_bs, sn); const f32x4* xr = (const f32x4*)srcn + lane;
; #pragma unroll
;             for (int j = 0; j < 4; ++j) vn[j] = xr[64 * j]; }
.LBB0_112:
	s_lshl_b64 s[0:1], s[12:13], 12
	v_and_b32_e32 v16, 63, v0
	s_add_u32 s0, s10, s0
	s_addc_u32 s1, s11, s1
	v_lshlrev_b32_e32 v17, 4, v16
	global_load_dwordx4 v[12:15], v17, s[0:1]
	global_load_dwordx4 v[8:11], v17, s[0:1] offset:1024
	global_load_dwordx4 v[4:7], v17, s[0:1] offset:2048
	global_load_dwordx4 v[0:3], v17, s[0:1] offset:3072
	v_mbcnt_lo_u32_b32 v17, -1, 0
	v_mbcnt_hi_u32_b32 v17, -1, v17
	v_and_b32_e32 v18, 64, v17
	v_xor_b32_e32 v19, 1, v17
	v_add_u32_e32 v18, 64, v18
	v_xor_b32_e32 v20, 2, v17
	v_cmp_lt_i32_e32 vcc, v19, v18
	v_xor_b32_e32 v21, 4, v17
	v_xor_b32_e32 v22, 8, v17
	v_cndmask_b32_e32 v19, v17, v19, vcc
	v_cmp_lt_i32_e32 vcc, v20, v18
	s_ashr_i32 s39, s38, 31
	v_xor_b32_e32 v23, 16, v17
	v_cndmask_b32_e32 v20, v17, v20, vcc
	v_cmp_lt_i32_e32 vcc, v21, v18
	s_lshl_b64 s[12:13], s[38:39], 11
	v_xor_b32_e32 v24, 32, v17
	v_cndmask_b32_e32 v21, v17, v21, vcc
	v_cmp_lt_i32_e32 vcc, v22, v18
	s_add_u32 s12, s30, s12
	v_mov_b32_e32 v33, 0
	v_cndmask_b32_e32 v22, v17, v22, vcc
	v_cmp_lt_i32_e32 vcc, v23, v18
	v_lshlrev_b32_e32 v32, 3, v16
	s_addc_u32 s13, s31, s13
	v_cndmask_b32_e32 v23, v17, v23, vcc
	v_cmp_lt_i32_e32 vcc, v24, v18
	s_mov_b64 s[44:45], 0xb3c0000
	v_lshlrev_b32_e32 v38, 2, v19
	v_cndmask_b32_e32 v17, v17, v24, vcc
	v_lshl_add_u64 v[18:19], s[12:13], 0, v[32:33]
	v_lshlrev_b32_e32 v39, 2, v20
	v_lshlrev_b32_e32 v40, 2, v21
	v_lshlrev_b32_e32 v41, 2, v22
	v_lshlrev_b32_e32 v42, 2, v23
	v_lshlrev_b32_e32 v43, 2, v17
	s_ashr_i32 s43, s42, 31
	v_lshlrev_b32_e32 v32, 4, v16
	v_lshl_add_u64 v[34:35], v[18:19], 0, s[44:45]
	s_mov_b32 s9, 0
	v_mov_b32_e32 v36, 0x358637bd
	s_mov_b32 s0, 0xf800000
	v_mov_b32_e32 v37, 0x260
	s_mov_b64 s[10:11], 0x1000
	s_movk_i32 s1, 0x1000
	s_movk_i32 s3, 0x7fff
	s_mov_b32 s14, 0xffff0000
	s_mov_b32 s15, s38
	s_lshl_b64 s[12:13], s[42:43], 11
	s_waitcnt vmcnt(3)
	v_mov_b32_e32 v18, v14
	v_mov_b32_e32 v19, v15
	s_waitcnt vmcnt(2)
	v_mov_b32_e32 v22, v10
	v_mov_b32_e32 v23, v11
	s_waitcnt vmcnt(1)
	v_mov_b32_e32 v26, v6
	v_mov_b32_e32 v27, v7
	s_waitcnt vmcnt(0)
	v_mov_b32_e32 v30, v2
	v_mov_b32_e32 v31, v3
	v_mov_b32_e32 v16, v12
	v_mov_b32_e32 v17, v13
	v_mov_b32_e32 v20, v8
	v_mov_b32_e32 v21, v9
	v_mov_b32_e32 v24, v4
	v_mov_b32_e32 v25, v5
	v_mov_b32_e32 v28, v0
	v_mov_b32_e32 v29, v1
	s_branch .LBB0_115

; __device__ __forceinline__ unsigned pk2(float lo, float hi) { return f2bf(lo) | (f2bf(hi) << 16); }
; __device__ __forceinline__ void norm_mod_phase(const float* lat, long lat_bs, const float* cx, long ctx_bs, const float* modl, int shoff, int scoff, bf16* XN, int skip_ctx, int gw, int NGW, float* xcopy, const float* part, int nkc, const float* pgate) {
;     ...
;         for (int j = 0; j < 4; ++j) ss += (v[j].x * v[j].x + v[j].y * v[j].y) + (v[j].z * v[j].z + v[j].w * v[j].w);
;         if (xcopy && s == 4) {
;             const int b_ = row / TPB, cr = b_ * CTXL + (row - b_ * TPB); const f32x4* gp = (const f32x4*)(pgate + 4 * NMOD6) + lane;
;             f32x4 sm[4];
; #pragma unroll
;             for (int j = 0; j < 4; ++j) sm[j] = (f32x4){0.f, 0.f, 0.f, 0.f};
;             for (int kc = 0; kc < nkc; ++kc) { const f32x4* pp = (const f32x4*)(part + ((size_t)kc * 1024 + cr) * DMODEL) + lane;
; #pragma unroll
;                 for (int j = 0; j < 4; ++j) sm[j] += pp[64 * j]; }
;             f32x4* xc = (f32x4*)(xcopy + (size_t)row * DMODEL) + lane; ss = 0.f;
; #pragma unroll
;             for (int j = 0; j < 4; ++j) { v[j] += gp[64 * j] * sm[j]; xc[64 * j] = v[j]; ss += (v[j].x * v[j].x + v[j].y * v[j].y) + (v[j].z * v[j].z + v[j].w * v[j].w); } }
;         const float rstd = 1.0f / sqrtf(wave_sum(ss) * (1.0f / DMODEL) + EPS);
;         const f32x4* sh = (const f32x4*)(modl + s * NMOD6 + shoff) + lane; const f32x4* sc = (const f32x4*)(modl + s * NMOD6 + scoff) + lane;
;         v2u* o8 = (v2u*)(XN + (size_t)row * DMODEL) + lane;
; #pragma unroll
;         for (int j = 0; j < 4; ++j) { const f32x4 a = sh[64 * j], m = sc[64 * j]; const f32x4 y = v[j] * rstd * (m + 1.0f) + a; v2u w; w.x = pk2(y.x, y.y); w.y = pk2(y.z, y.w); o8[64 * j] = w; }
.Lnorm1_join:
	v_mul_f32_e32 v56, v0, v0
	v_mul_f32_e32 v58, v1, v1
	v_mul_f32_e32 v54, v2, v2
	v_mul_f32_e32 v52, v3, v3
	v_add_f32_e32 v56, v56, v58
	v_add_f32_e32 v57, v57, v59
	v_add_f32_e32 v52, v54, v52
	v_add_f32_e32 v53, v55, v53
	v_add_f32_e32 v48, 1.0, v48
	v_add_f32_e32 v49, 1.0, v49
	v_add_f32_e32 v52, v56, v52
	v_add_f32_e32 v53, v57, v53
	v_add_f32_e32 v50, 1.0, v50
	v_add_f32_e32 v51, 1.0, v51
	v_add_f32_e32 v52, v52, v53
	ds_bpermute_b32 v53, v38, v52
	s_waitcnt lgkmcnt(0)
	v_add_f32_e32 v52, v52, v53
	ds_bpermute_b32 v53, v39, v52
	s_waitcnt lgkmcnt(0)
	v_add_f32_e32 v52, v52, v53
	ds_bpermute_b32 v53, v40, v52
	s_waitcnt lgkmcnt(0)
	v_add_f32_e32 v52, v52, v53
	ds_bpermute_b32 v53, v41, v52
	s_waitcnt lgkmcnt(0)
	v_add_f32_e32 v52, v52, v53
	ds_bpermute_b32 v53, v42, v52
	s_waitcnt lgkmcnt(0)
	v_add_f32_e32 v52, v52, v53
	ds_bpermute_b32 v53, v43, v52
	s_waitcnt lgkmcnt(0)
	v_add_f32_e32 v52, v52, v53
	v_fmamk_f32 v52, v52, 0x3a800000, v36
	v_mul_f32_e32 v53, 0x4f800000, v52
	v_cmp_gt_f32_e32 vcc, s0, v52
	s_nop 1
	v_cndmask_b32_e32 v52, v52, v53, vcc
	v_sqrt_f32_e32 v53, v52
	s_nop 0
	v_add_u32_e32 v54, -1, v53
	v_add_u32_e32 v55, 1, v53
	v_fma_f32 v56, -v54, v53, v52
	v_fma_f32 v57, -v55, v53, v52
	v_cmp_ge_f32_e64 s[4:5], 0, v56
	s_nop 1
	v_cndmask_b32_e64 v53, v53, v54, s[4:5]
	v_cmp_lt_f32_e64 s[4:5], 0, v57
	s_nop 1
	v_cndmask_b32_e64 v53, v53, v55, s[4:5]
	v_mul_f32_e32 v54, 0x37800000, v53
	v_cndmask_b32_e32 v53, v53, v54, vcc
	v_cmp_class_f32_e32 vcc, v52, v37
	s_nop 1
	v_cndmask_b32_e32 v54, v53, v52, vcc
	v_div_scale_f32 v55, s[4:5], v54, v54, 1.0
	v_rcp_f32_e32 v56, v55
	v_div_scale_f32 v57, vcc, 1.0, v54, 1.0
	v_lshl_add_u64 v[52:53], v[60:61], 0, s[10:11]
	v_fma_f32 v58, -v55, v56, 1.0
	v_fmac_f32_e32 v56, v58, v56
	v_mul_f32_e32 v58, v57, v56
	v_fma_f32 v59, -v55, v58, v57
	v_fmac_f32_e32 v58, v59, v56
	v_fma_f32 v55, -v55, v58, v57
	v_div_fmas_f32 v55, v55, v56, v58
	v_div_fixup_f32 v54, v55, v54, 1.0
	v_mul_f32_e32 v12, v12, v54
	v_mul_f32_e32 v13, v13, v54
	v_mul_f32_e32 v14, v14, v54
	v_mul_f32_e32 v15, v15, v54
	v_fma_f32 v12, v48, v12, v44
	v_fma_f32 v13, v49, v13, v45
	v_fma_f32 v14, v50, v14, v46
	v_fma_f32 v15, v51, v15, v47
	v_bfe_u32 v44, v12, 16, 1
	v_bfe_u32 v45, v13, 16, 1
	v_add3_u32 v12, v12, v44, s3
	v_lshrrev_b32_e32 v12, 16, v12
	v_add3_u32 v13, v13, v45, s3
	v_and_or_b32 v12, v13, s14, v12
	v_bfe_u32 v13, v14, 16, 1
	v_add3_u32 v13, v14, v13, s3
	v_bfe_u32 v14, v15, 16, 1
	v_lshrrev_b32_e32 v13, 16, v13
	v_add3_u32 v14, v15, v14, s3
	v_and_or_b32 v13, v14, s14, v13
	global_store_dwordx2 v[34:35], v[12:13], off
	v_mul_f32_e32 v8, v8, v54
	v_mul_f32_e32 v9, v9, v54
	v_mul_f32_e32 v10, v10, v54
	v_mul_f32_e32 v11, v11, v54
	v_mul_f32_e32 v4, v4, v54
	v_mul_f32_e32 v5, v5, v54
	v_mul_f32_e32 v6, v6, v54
	v_mul_f32_e32 v7, v7, v54
	s_andn2_b64 vcc, exec, s[46:47]
	s_mov_b32 s4, s44
	v_add_f32_e32 v14, 1.0, v118
	v_add_f32_e32 v15, 1.0, v119
	v_add_f32_e32 v12, 1.0, v116
	v_add_f32_e32 v13, 1.0, v117
	v_fma_f32 v10, v14, v10, v122
	v_fma_f32 v11, v15, v11, v123
	v_fma_f32 v8, v12, v8, v120
	v_fma_f32 v9, v13, v9, v121
	v_bfe_u32 v14, v10, 16, 1
	v_bfe_u32 v12, v8, 16, 1
	v_bfe_u32 v13, v9, 16, 1
	v_bfe_u32 v15, v11, 16, 1
	v_add3_u32 v8, v8, v12, s3
	v_add3_u32 v10, v10, v14, s3
	v_add3_u32 v9, v9, v13, s3
	v_add3_u32 v11, v11, v15, s3
	v_lshrrev_b32_e32 v8, 16, v8
	v_lshrrev_b32_e32 v10, 16, v10
	v_and_or_b32 v8, v9, s14, v8
	v_and_or_b32 v9, v11, s14, v10
	global_store_dwordx2 v[34:35], v[8:9], off offset:512
	s_nop 0
	v_add_f32_e32 v10, 1.0, v102
	v_add_f32_e32 v11, 1.0, v103
	v_add_f32_e32 v8, 1.0, v100
	v_add_f32_e32 v9, 1.0, v101
	v_fma_f32 v6, v6, v10, v106
	v_fma_f32 v7, v7, v11, v107
	v_fma_f32 v4, v4, v8, v104
	v_fma_f32 v5, v5, v9, v105
	v_bfe_u32 v10, v6, 16, 1
	v_bfe_u32 v8, v4, 16, 1
	v_bfe_u32 v9, v5, 16, 1
	v_bfe_u32 v11, v7, 16, 1
	v_add3_u32 v4, v4, v8, s3
	v_add3_u32 v6, v6, v10, s3
	v_add3_u32 v5, v5, v9, s3
	v_add3_u32 v7, v7, v11, s3
	v_lshrrev_b32_e32 v4, 16, v4
	v_lshrrev_b32_e32 v6, 16, v6
	v_and_or_b32 v4, v5, s14, v4
	v_and_or_b32 v5, v7, s14, v6
	global_store_dwordx2 v[34:35], v[4:5], off offset:1024
	v_mul_f32_e32 v52, v0, v54
	v_mul_f32_e32 v53, v1, v54
	v_mul_f32_e32 v55, v3, v54
	v_mul_f32_e32 v54, v2, v54
	s_waitcnt vmcnt(3)
	v_mov_b32_e32 v0, v28
	v_mov_b32_e32 v1, v29
	v_mov_b32_e32 v4, v24
	v_mov_b32_e32 v5, v25
	v_mov_b32_e32 v8, v20
	v_mov_b32_e32 v9, v21
	v_mov_b32_e32 v12, v16
	v_mov_b32_e32 v13, v17
	v_mov_b32_e32 v2, v30
	v_mov_b32_e32 v3, v31
	v_mov_b32_e32 v6, v26
	v_mov_b32_e32 v7, v27
	v_mov_b32_e32 v10, v22
	v_mov_b32_e32 v11, v23
	v_mov_b32_e32 v14, v18
	v_mov_b32_e32 v15, v19
	v_add_f32_e32 v46, 1.0, v110
	v_add_f32_e32 v47, 1.0, v111
	v_add_f32_e32 v44, 1.0, v108
	v_add_f32_e32 v45, 1.0, v109
	v_fma_f32 v46, v54, v46, v114
	v_fma_f32 v47, v55, v47, v115
	v_fma_f32 v44, v52, v44, v112
	v_fma_f32 v45, v53, v45, v113
	v_bfe_u32 v50, v46, 16, 1
	v_bfe_u32 v48, v44, 16, 1
	v_bfe_u32 v49, v45, 16, 1
	v_bfe_u32 v51, v47, 16, 1
	v_add3_u32 v44, v44, v48, s3
	v_add3_u32 v46, v46, v50, s3
	v_add3_u32 v45, v45, v49, s3
	v_add3_u32 v47, v47, v51, s3
	v_lshrrev_b32_e32 v44, 16, v44
	v_lshrrev_b32_e32 v46, 16, v46
	v_and_or_b32 v44, v45, s14, v44
	v_and_or_b32 v45, v47, s14, v46
	global_store_dwordx2 v[34:35], v[44:45], off offset:1536
	v_lshl_add_u64 v[34:35], v[34:35], 0, s[12:13]
	s_cbranch_vccz .LBB0_120

; __device__ __forceinline__ unsigned xb_ld(unsigned* p)              { return __hip_atomic_load(p, __ATOMIC_RELAXED, __HIP_MEMORY_SCOPE_AGENT); }
; __device__ __forceinline__ unsigned xb_add(unsigned* p, unsigned v) { return __hip_atomic_fetch_add(p, v, __ATOMIC_RELAXED, __HIP_MEMORY_SCOPE_AGENT); }
; #define XB_SPIN(cond, bar) do { unsigned _sp = 0; while (cond) { __builtin_amdgcn_s_sleep(1); \
;     if ((++_sp & 255u) == 0u) { if (xb_ld(&(bar)[XB_TMO])) break; if (_sp > XB_SPIN_CAP) { atomicAdd(&(bar)[XB_TMO], 1u); break; } } } } while (0)
; __device__ __forceinline__ void xcd_barrier(const XcdBarrier& b) {
;     ...
;             const unsigned og = xb_add(&bar[XB_TOP], 1u);
;             const unsigned tg = og / nx;
;             if (og + 1u == (tg + 1u) * nx) xb_add(&bar[XB_TOPGEN], 1u);
;             else XB_SPIN(xb_ld(&bar[XB_TOPGEN]) == tg, bar);
.LBB0_155:
	s_or_b64 exec, exec, s[12:13]
	v_cvt_f32_u32_e32 v3, v0
	s_waitcnt vmcnt(0)
	v_readfirstlane_b32 s0, v2
	s_add_u32 s12, s30, 0x1bbc3500
	s_addc_u32 s13, s31, 0
	v_rcp_iflag_f32_e32 v3, v3
	v_add_u32_e32 v1, s0, v1
	v_add_u32_e32 v4, 1, v1
	s_mov_b64 s[44:45], -1
	v_mul_f32_e32 v2, 0x4f7ffffe, v3
	v_cvt_u32_f32_e32 v2, v2
	v_sub_u32_e32 v3, 0, v0
	v_mul_lo_u32 v3, v3, v2
	v_mul_hi_u32 v3, v2, v3
	v_add_u32_e32 v2, v2, v3
	v_mul_hi_u32 v2, v1, v2
	v_mul_lo_u32 v3, v2, v0
	v_sub_u32_e32 v1, v1, v3
	v_add_u32_e32 v5, 1, v2
	v_cmp_ge_u32_e32 vcc, v1, v0
	v_sub_u32_e32 v3, v1, v0
	s_nop 0
	v_cndmask_b32_e32 v2, v2, v5, vcc
	v_cndmask_b32_e32 v1, v1, v3, vcc
	v_add_u32_e32 v3, 1, v2
	v_cmp_ge_u32_e32 vcc, v1, v0
	s_nop 1
	v_cndmask_b32_e32 v2, v2, v3, vcc
	v_mul_lo_u32 v1, v0, v2
	v_add_u32_e32 v0, v1, v0
	v_cmp_ne_u32_e32 vcc, v4, v0
	v_mov_b32_e32 v0, s12
	v_mov_b32_e32 v1, s13
	s_and_saveexec_b64 s[10:11], vcc
	s_cbranch_execz .LBB0_167
	v_mov_b32_e32 v0, 0
	global_load_dword v1, v0, s[12:13] sc1
	s_mov_b64 s[48:49], 0
	s_waitcnt vmcnt(0)
	v_cmp_eq_u32_e32 vcc, v1, v2
	s_and_saveexec_b64 s[46:47], vcc
	s_cbranch_execz .LBB0_166
	s_add_u32 s44, s30, 0x1bbc0200
	s_addc_u32 s45, s31, 0
	s_mov_b32 s0, 1
	s_branch .LBB0_159

; __device__ __forceinline__ unsigned xb_ld(unsigned* p)              { return __hip_atomic_load(p, __ATOMIC_RELAXED, __HIP_MEMORY_SCOPE_AGENT); }
; #define XB_SPIN(cond, bar) do { unsigned _sp = 0; while (cond) { __builtin_amdgcn_s_sleep(1); \
;     if ((++_sp & 255u) == 0u) { if (xb_ld(&(bar)[XB_TMO])) break; if (_sp > XB_SPIN_CAP) { atomicAdd(&(bar)[XB_TMO], 1u); break; } } } } while (0)
; __device__ __forceinline__ void xcd_barrier(const XcdBarrier& b) {
;     ...
;             else XB_SPIN(xb_ld(&bar[XB_TOPGEN]) == tg, bar);
.LBB0_166:
	s_or_b64 exec, exec, s[46:47]
	v_mov_b32_e32 v0, s44
	v_mov_b32_e32 v1, s45
	s_orn2_b64 s[44:45], s[48:49], exec

; __device__ __forceinline__ unsigned xb_ld(unsigned* p)              { return __hip_atomic_load(p, __ATOMIC_RELAXED, __HIP_MEMORY_SCOPE_AGENT); }
; __device__ __forceinline__ unsigned xb_add(unsigned* p, unsigned v) { return __hip_atomic_fetch_add(p, v, __ATOMIC_RELAXED, __HIP_MEMORY_SCOPE_AGENT); }
; #define XB_SPIN(cond, bar) do { unsigned _sp = 0; while (cond) { __builtin_amdgcn_s_sleep(1); \
;     if ((++_sp & 255u) == 0u) { if (xb_ld(&(bar)[XB_TMO])) break; if (_sp > XB_SPIN_CAP) { atomicAdd(&(bar)[XB_TMO], 1u); break; } } } } while (0)
; __device__ __forceinline__ void xcd_barrier(const XcdBarrier& b) {
;     ...
;             const unsigned og = xb_add(&bar[XB_TOP], 1u);
;             const unsigned tg = og / nx;
;             if (og + 1u == (tg + 1u) * nx) xb_add(&bar[XB_TOPGEN], 1u);
;             else XB_SPIN(xb_ld(&bar[XB_TOPGEN]) == tg, bar);
.LBB0_231:
	s_or_b64 exec, exec, s[12:13]
	v_cvt_f32_u32_e32 v3, v0
	s_waitcnt vmcnt(0)
	v_readfirstlane_b32 s0, v2
	s_add_u32 s12, s30, 0x1bbc3500
	s_addc_u32 s13, s31, 0
	v_rcp_iflag_f32_e32 v3, v3
	v_add_u32_e32 v1, s0, v1
	v_add_u32_e32 v4, 1, v1
	s_mov_b64 s[48:49], -1
	v_mul_f32_e32 v2, 0x4f7ffffe, v3
	v_cvt_u32_f32_e32 v2, v2
	v_sub_u32_e32 v3, 0, v0
	v_mul_lo_u32 v3, v3, v2
	v_mul_hi_u32 v3, v2, v3
	v_add_u32_e32 v2, v2, v3
	v_mul_hi_u32 v2, v1, v2
	v_mul_lo_u32 v3, v2, v0
	v_sub_u32_e32 v1, v1, v3
	v_add_u32_e32 v5, 1, v2
	v_cmp_ge_u32_e32 vcc, v1, v0
	v_sub_u32_e32 v3, v1, v0
	s_nop 0
	v_cndmask_b32_e32 v2, v2, v5, vcc
	v_cndmask_b32_e32 v1, v1, v3, vcc
	v_add_u32_e32 v3, 1, v2
	v_cmp_ge_u32_e32 vcc, v1, v0
	s_nop 1
	v_cndmask_b32_e32 v2, v2, v3, vcc
	v_mul_lo_u32 v1, v0, v2
	v_add_u32_e32 v0, v1, v0
	v_cmp_ne_u32_e32 vcc, v4, v0
	v_mov_b32_e32 v0, s12
	v_mov_b32_e32 v1, s13
	s_and_saveexec_b64 s[10:11], vcc
	s_cbranch_execz .LBB0_243
	v_mov_b32_e32 v0, 0
	global_load_dword v1, v0, s[12:13] sc1
	s_mov_b64 s[52:53], 0
	s_waitcnt vmcnt(0)
	v_cmp_eq_u32_e32 vcc, v1, v2
	s_and_saveexec_b64 s[50:51], vcc
	s_cbranch_execz .LBB0_242
	s_add_u32 s48, s30, 0x1bbc0200
	s_addc_u32 s49, s31, 0
	s_mov_b32 s0, 1
	s_branch .LBB0_235

; __device__ __forceinline__ unsigned xb_ld(unsigned* p)              { return __hip_atomic_load(p, __ATOMIC_RELAXED, __HIP_MEMORY_SCOPE_AGENT); }
; #define XB_SPIN(cond, bar) do { unsigned _sp = 0; while (cond) { __builtin_amdgcn_s_sleep(1); \
;     if ((++_sp & 255u) == 0u) { if (xb_ld(&(bar)[XB_TMO])) break; if (_sp > XB_SPIN_CAP) { atomicAdd(&(bar)[XB_TMO], 1u); break; } } } } while (0)
; __device__ __forceinline__ void xcd_barrier(const XcdBarrier& b) {
;     ...
;             else XB_SPIN(xb_ld(&bar[XB_TOPGEN]) == tg, bar);
.LBB0_242:
	s_or_b64 exec, exec, s[50:51]
	v_mov_b32_e32 v0, s48
	v_mov_b32_e32 v1, s49
	s_orn2_b64 s[48:49], s[52:53], exec

; __device__ __forceinline__ unsigned xb_ld(unsigned* p)              { return __hip_atomic_load(p, __ATOMIC_RELAXED, __HIP_MEMORY_SCOPE_AGENT); }
; __device__ __forceinline__ unsigned xb_add(unsigned* p, unsigned v) { return __hip_atomic_fetch_add(p, v, __ATOMIC_RELAXED, __HIP_MEMORY_SCOPE_AGENT); }
; #define XB_SPIN(cond, bar) do { unsigned _sp = 0; while (cond) { __builtin_amdgcn_s_sleep(1); \
;     if ((++_sp & 255u) == 0u) { if (xb_ld(&(bar)[XB_TMO])) break; if (_sp > XB_SPIN_CAP) { atomicAdd(&(bar)[XB_TMO], 1u); break; } } } } while (0)
; __device__ __forceinline__ void xcd_barrier(const XcdBarrier& b) {
;     ...
;             const unsigned og = xb_add(&bar[XB_TOP], 1u);
;             const unsigned tg = og / nx;
;             if (og + 1u == (tg + 1u) * nx) xb_add(&bar[XB_TOPGEN], 1u);
;             else XB_SPIN(xb_ld(&bar[XB_TOPGEN]) == tg, bar);
.LBB0_296:
	s_or_b64 exec, exec, s[10:11]
	v_cvt_f32_u32_e32 v3, v0
	s_waitcnt vmcnt(0)
	v_readfirstlane_b32 s0, v2
	s_add_u32 s10, s30, 0x1bbc3500
	s_addc_u32 s11, s31, 0
	v_rcp_iflag_f32_e32 v3, v3
	v_add_u32_e32 v1, s0, v1
	v_add_u32_e32 v4, 1, v1
	s_mov_b64 s[48:49], -1
	v_mul_f32_e32 v2, 0x4f7ffffe, v3
	v_cvt_u32_f32_e32 v2, v2
	v_sub_u32_e32 v3, 0, v0
	v_mul_lo_u32 v3, v3, v2
	v_mul_hi_u32 v3, v2, v3
	v_add_u32_e32 v2, v2, v3
	v_mul_hi_u32 v2, v1, v2
	v_mul_lo_u32 v3, v2, v0
	v_sub_u32_e32 v1, v1, v3
	v_add_u32_e32 v5, 1, v2
	v_cmp_ge_u32_e32 vcc, v1, v0
	v_sub_u32_e32 v3, v1, v0
	s_nop 0
	v_cndmask_b32_e32 v2, v2, v5, vcc
	v_cndmask_b32_e32 v1, v1, v3, vcc
	v_add_u32_e32 v3, 1, v2
	v_cmp_ge_u32_e32 vcc, v1, v0
	s_nop 1
	v_cndmask_b32_e32 v2, v2, v3, vcc
	v_mul_lo_u32 v1, v0, v2
	v_add_u32_e32 v0, v1, v0
	v_cmp_ne_u32_e32 vcc, v4, v0
	v_mov_b32_e32 v0, s10
	v_mov_b32_e32 v1, s11
	s_and_saveexec_b64 s[8:9], vcc
	s_cbranch_execz .LBB0_308
	v_mov_b32_e32 v0, 0
	global_load_dword v1, v0, s[10:11] sc1
	s_mov_b64 s[54:55], 0
	s_waitcnt vmcnt(0)
	v_cmp_eq_u32_e32 vcc, v1, v2
	s_and_saveexec_b64 s[52:53], vcc
	s_cbranch_execz .LBB0_307
	s_add_u32 s48, s30, 0x1bbc0200
	s_addc_u32 s49, s31, 0
	s_mov_b32 s0, 1
	s_branch .LBB0_300

; __device__ __forceinline__ unsigned xb_ld(unsigned* p)              { return __hip_atomic_load(p, __ATOMIC_RELAXED, __HIP_MEMORY_SCOPE_AGENT); }
; #define XB_SPIN(cond, bar) do { unsigned _sp = 0; while (cond) { __builtin_amdgcn_s_sleep(1); \
;     if ((++_sp & 255u) == 0u) { if (xb_ld(&(bar)[XB_TMO])) break; if (_sp > XB_SPIN_CAP) { atomicAdd(&(bar)[XB_TMO], 1u); break; } } } } while (0)
; __device__ __forceinline__ void xcd_barrier(const XcdBarrier& b) {
;     ...
;             else XB_SPIN(xb_ld(&bar[XB_TOPGEN]) == tg, bar);
.LBB0_307:
	s_or_b64 exec, exec, s[52:53]
	v_mov_b32_e32 v0, s48
	v_mov_b32_e32 v1, s49
	s_orn2_b64 s[48:49], s[54:55], exec

; #define WAIT_BAR(N) asm volatile("s_waitcnt vmcnt(" #N ") lgkmcnt(0)\n\ts_barrier":::"memory")
;   #define DMA_K(t,slot) glds16(ksrc+(long)KROW(t)*PK,(unsigned)__builtin_amdgcn_readfirstlane(kdst+(slot)))
;   #define DMA_V(t,slot) do{ glds16(vsrc+(long)KROW(t)*PV,(unsigned)__builtin_amdgcn_readfirstlane(vdst+2*(slot))); if(MODE==2)glds16(vsrc+(long)KROW(t)*PV+64,(unsigned)__builtin_amdgcn_readfirstlane(vdst+2*(slot)+SLOTB)); }while(0)
; template<int MODE,int THRL> __device__ __forceinline__ void attn_unit(const bf16*Qw0,int PQ,const bf16*__restrict__ Kh,int PK,const bf16*__restrict__ Vh,int PV,bf16*Ow0,int PO,int NT,int nabase,int nar0,const float*rpbh,char*shm,int&rot,bool pre,bool hasn,long dKn,long dVn){
;     ...
;   if(!pre){ DMA_K(0,rot);DMA_V(0,rot);DMA_K(1,NXT(rot)); }
;   bf16x8 qr[4];
;   #pragma unroll
;   for(int d0=0;d0<4;++d0)qr[d0]=*reinterpret_cast<const bf16x8*>(&Qw[(long)r32*PQ+d0*16+hi*8]);
;   float mhat=0.f,l_reg=0.f;constexpr int ND=(MODE==2)?4:2; f32x16 o[4];o[0]=f32x16{};o[1]=f32x16{};o[2]=f32x16{};o[3]=f32x16{};f32x16 negm=f32x16{};asm volatile("":"+v"(negm));
;     ...
;   bool resc=false;
;     ...
;   f32x16 pA0,pA1,pB0,pB1;
;   int sl_prev=rot,sl_cur=rot,sl_next=NXT(rot);
;   bool pfnow=false;
;     ...
;   if(!pre){ DMA_K(2,NXT(sl_next)); }
;   if(pre){WAIT_BAR(0);}else if(MODE==2){WAIT_BAR(4);}else{WAIT_BAR(3);}
.LBB0_322:
	s_and_b32 s12, s77, 31
	s_lshl_b32 s6, s13, 6
	s_mul_hi_i32 s58, s15, 0x2100
	s_mulk_i32 s15, 0x2100
	s_lshl_b32 s59, s12, 8
	s_add_u32 s15, s15, s59
	s_addc_u32 s59, s58, 0
	s_add_u32 s58, s15, 0x100
	s_addc_u32 s59, s59, 0
	s_mul_i32 s15, s59, 0x1200
	s_mul_hi_u32 s62, s58, 0x1200
	s_add_i32 s62, s62, s15
	s_mul_i32 s15, s58, 0x1200
	s_add_u32 s15, s44, s15
	s_addc_u32 s62, s45, s62
	s_lshl_b32 s76, s6, 1
	s_add_u32 s15, s15, s76
	v_and_b32_e32 v236, 31, v34
	s_addc_u32 s63, s62, 0
	s_mul_i32 s62, s56, 0x24000
	v_mul_u32_u24_e32 v1, 0x900, v236
	v_lshrrev_b32_e32 v237, 5, v234
	s_mul_hi_i32 s64, s56, 0x24000
	s_add_u32 s62, s15, s62
	v_lshlrev_b32_e32 v1, 1, v1
	s_addc_u32 s63, s63, s64
	v_lshl_or_b32 v1, v237, 4, v1
	global_load_dwordx4 v[142:145], v1, s[62:63]
	global_load_dwordx4 v[138:141], v1, s[62:63] offset:32
	global_load_dwordx4 v[134:137], v1, s[62:63] offset:64
	global_load_dwordx4 v[130:133], v1, s[62:63] offset:96
	v_mov_b32_e32 v2, v0
	v_mov_b32_e32 v3, v0
	v_mov_b32_e32 v4, v0
	v_mov_b32_e32 v5, v0
	v_mov_b32_e32 v6, v0
	v_mov_b32_e32 v7, v0
	v_mov_b32_e32 v8, v0
	v_mov_b32_e32 v9, v0
	v_mov_b32_e32 v10, v0
	v_mov_b32_e32 v11, v0
	v_mov_b32_e32 v12, v0
	v_mov_b32_e32 v13, v0
	v_mov_b32_e32 v14, v0
	v_mov_b32_e32 v15, v0
	v_mov_b32_e32 v1, v0
	v_mov_b32_e32 v16, v14
	v_mov_b32_e32 v17, v15
	s_cmpk_lg_i32 s14, 0x4000
	v_mov_b32_e32 v14, v12
	v_mov_b32_e32 v15, v13
	v_mov_b32_e32 v12, v10
	v_mov_b32_e32 v13, v11
	v_mov_b32_e32 v10, v8
	v_mov_b32_e32 v11, v9
	v_mov_b32_e32 v8, v6
	v_mov_b32_e32 v9, v7
	v_mov_b32_e32 v6, v4
	v_mov_b32_e32 v7, v5
	v_mov_b32_e32 v4, v2
	v_mov_b32_e32 v5, v3
	v_mov_b32_e32 v2, v0
	v_mov_b32_e32 v3, v1
	s_cselect_b32 s62, s57, 0
	s_andn2_b64 vcc, exec, s[4:5]
	s_mov_b64 s[4:5], -1
	s_cbranch_vccnz .LBB0_324
	s_add_i32 s57, s62, 0x2000
	s_cmpk_lg_i32 s62, 0x4000
	s_cselect_b32 s4, s57, 0
	v_lshl_add_u64 v[18:19], v[214:215], 0, s[52:53]
	s_add_i32 s4, s4, s78
	s_mov_b32 s5, m0
	s_mov_b32 m0, s4
	s_nop 0
	global_load_lds_dwordx4 v[18:19], off
	s_mov_b32 m0, s5
	s_waitcnt vmcnt(3) lgkmcnt(0)
	s_barrier
	s_mov_b64 s[4:5], 0

; __device__ __forceinline__ void na_mfload(u32x4_t*mf,const unsigned*mfh,int t,int nabase,int r,int chalf,int lane){
;   const int dr=nabase+t-4-r+7; const u32x4_t*p=(const u32x4_t*)(mfh+(size_t)(((dr*2+chalf)*64+lane)*16));
;   #pragma unroll
;   for(int i=0;i<4;++i)mf[i]=p[i];
; }
.LBB0_347:
	s_and_b32 s64, s74, 31
	s_ashr_i32 s57, s56, 31
	s_lshl_b32 s66, s64, 2
	s_lshl_b32 s70, s64, 13
	s_cmp_gt_u32 s66, 4
	s_cselect_b32 s65, 0, 0
	s_cselect_b32 s64, s66, 4
	v_med3_u32 v82, s66, 4, v232
	v_cmp_lt_u64_e32 vcc, s[64:65], v[224:225]
	v_readfirstlane_b32 s83, v82
	v_lshlrev_b32_e32 v82, 11, v82
	s_and_b64 s[66:67], vcc, exec
	s_cselect_b32 s64, s64, 0x78
	s_add_i32 s66, s15, 0x2000
	v_or_b32_e32 v82, s73, v82
	s_cmpk_lg_i32 s15, 0x4000
	v_add_u32_e32 v82, 0x2800, v82
	s_cselect_b32 s84, s66, 0
	v_add_u32_e32 v82, v82, v198
	s_lshl_b32 s66, s72, 11
	v_subrev_u32_e32 v82, s66, v82
	s_mul_hi_u32 s65, s64, 0x48000
	s_mul_i32 s64, s64, 0x48000
	v_subrev_u32_e32 v208, s70, v82
	s_mov_b32 s85, 3
	v_mov_b32_e32 v210, v214
	v_mov_b32_e32 v211, v215
	v_mov_b32_e32 v212, v228
	v_mov_b32_e32 v213, v229

; #define WAIT_BAR(N) asm volatile("s_waitcnt vmcnt(" #N ") lgkmcnt(0)\n\ts_barrier":::"memory")
;   #define DMA_K(t,slot) glds16(ksrc+(long)KROW(t)*PK,(unsigned)__builtin_amdgcn_readfirstlane(kdst+(slot)))
;   #define DMA_V(t,slot) do{ glds16(vsrc+(long)KROW(t)*PV,(unsigned)__builtin_amdgcn_readfirstlane(vdst+2*(slot))); if(MODE==2)glds16(vsrc+(long)KROW(t)*PV+64,(unsigned)__builtin_amdgcn_readfirstlane(vdst+2*(slot)+SLOTB)); }while(0)
; template<int MODE,int THRL> __device__ __forceinline__ void attn_unit(const bf16*Qw0,int PQ,const bf16*__restrict__ Kh,int PK,const bf16*__restrict__ Vh,int PV,bf16*Ow0,int PO,int NT,int nabase,int nar0,const float*rpbh,char*shm,int&rot,bool pre,bool hasn,long dKn,long dVn){
;     ...
;   if(!pre){ DMA_K(0,rot);DMA_V(0,rot);DMA_K(1,NXT(rot)); }
;   bf16x8 qr[4];
;   #pragma unroll
;   for(int d0=0;d0<4;++d0)qr[d0]=*reinterpret_cast<const bf16x8*>(&Qw[(long)r32*PQ+d0*16+hi*8]);
;   float mhat=0.f,l_reg=0.f;constexpr int ND=(MODE==2)?4:2; f32x16 o[4];o[0]=f32x16{};o[1]=f32x16{};o[2]=f32x16{};o[3]=f32x16{};f32x16 negm=f32x16{};asm volatile("":"+v"(negm));
;     ...
;   bool resc=false;
;     ...
;   f32x16 pA0,pA1,pB0,pB1;
;   int sl_prev=rot,sl_cur=rot,sl_next=NXT(rot);
;   bool pfnow=false;
;     ...
;   if(!pre){ DMA_K(2,NXT(sl_next)); }
;   if(pre){WAIT_BAR(0);}else if(MODE==2){WAIT_BAR(4);}else{WAIT_BAR(3);}
.LBB0_482:
	v_and_b32_e32 v213, 31, v34
	s_mul_i32 s67, s66, 0x24000
	v_mul_u32_u24_e32 v0, 0x900, v213
	v_lshrrev_b32_e32 v214, 5, v211
	s_mul_hi_i32 s52, s66, 0x24000
	s_add_u32 s78, s78, s67
	v_lshlrev_b32_e32 v0, 1, v0
	s_addc_u32 s79, s79, s52
	v_lshl_or_b32 v0, v214, 4, v0
	global_load_dwordx4 v[148:151], v0, s[78:79]
	global_load_dwordx4 v[140:143], v0, s[78:79] offset:32
	global_load_dwordx4 v[132:135], v0, s[78:79] offset:64
	global_load_dwordx4 v[128:131], v0, s[78:79] offset:96
	v_mov_b32_e32 v2, v1
	v_mov_b32_e32 v3, v1
	v_mov_b32_e32 v4, v1
	v_mov_b32_e32 v5, v1
	v_mov_b32_e32 v6, v1
	v_mov_b32_e32 v7, v1
	v_mov_b32_e32 v8, v1
	v_mov_b32_e32 v9, v1
	v_mov_b32_e32 v10, v1
	v_mov_b32_e32 v11, v1
	v_mov_b32_e32 v12, v1
	v_mov_b32_e32 v13, v1
	v_mov_b32_e32 v14, v1
	v_mov_b32_e32 v15, v1
	v_mov_b32_e32 v0, v1
	v_mov_b32_e32 v16, v14
	v_mov_b32_e32 v17, v15
	s_cmpk_lg_i32 s82, 0x4000
	v_mov_b32_e32 v14, v12
	v_mov_b32_e32 v15, v13
	v_mov_b32_e32 v12, v10
	v_mov_b32_e32 v13, v11
	v_mov_b32_e32 v10, v8
	v_mov_b32_e32 v11, v9
	v_mov_b32_e32 v8, v6
	v_mov_b32_e32 v9, v7
	v_mov_b32_e32 v6, v4
	v_mov_b32_e32 v7, v5
	v_mov_b32_e32 v4, v2
	v_mov_b32_e32 v5, v3
	v_mov_b32_e32 v2, v0
	v_mov_b32_e32 v3, v1
	s_cselect_b32 s43, s43, 0
	s_andn2_b64 vcc, exec, s[10:11]
	s_mov_b64 s[10:11], -1
	s_cbranch_vccnz .LBB0_484
	s_add_i32 s52, s43, 0x2000
	s_cmpk_lg_i32 s43, 0x4000
	s_cselect_b32 s10, s52, 0
	v_lshl_add_u64 v[18:19], v[204:205], 0, s[56:57]
	s_add_i32 s10, s10, s15
	s_mov_b32 s11, m0
	s_mov_b32 m0, s10
	s_nop 0
	global_load_lds_dwordx4 v[18:19], off
	s_mov_b32 m0, s11
	s_waitcnt vmcnt(3) lgkmcnt(0)
	s_barrier
	s_mov_b64 s[10:11], 0

; #define WAIT_BAR(N) asm volatile("s_waitcnt vmcnt(" #N ") lgkmcnt(0)\n\ts_barrier":::"memory")
;   #define DMA_K(t,slot) glds16(ksrc+(long)KROW(t)*PK,(unsigned)__builtin_amdgcn_readfirstlane(kdst+(slot)))
;   #define DMA_V(t,slot) do{ glds16(vsrc+(long)KROW(t)*PV,(unsigned)__builtin_amdgcn_readfirstlane(vdst+2*(slot))); if(MODE==2)glds16(vsrc+(long)KROW(t)*PV+64,(unsigned)__builtin_amdgcn_readfirstlane(vdst+2*(slot)+SLOTB)); }while(0)
;   #define CMASK(P0,P1,t) do{ if(MODE==1&&(t)>=4)na_apply(P0,P1,mf,na_rowok((t),nabase,nar)); }while(0)
;   #define START(P0,P1) do{ const float rm=rowmax(P0,P1); resc=false; \
;     { const float dl=rm; mhat=fadd_s(mhat,dl); \
;       _Pragma("unroll") for(int r=0;r<16;++r){P0[r]=fsub_s(P0[r],dl);P1[r]=fsub_s(P1[r],dl);} \
;       _Pragma("unroll") for(int r=0;r<16;++r)negm[r]=-mhat; asm volatile("":"+v"(negm)); } \
;     _Pragma("unroll") for(int r=0;r<16;++r)P0[r]=__builtin_amdgcn_exp2f(P0[r]); }while(0)
;   #define ROT() do{sl_prev=sl_cur;sl_cur=sl_next;sl_next=(sl_next==(NSLOT-1)*SLOTB)?0:sl_next+SLOTB;}while(0)
; template<int MODE,int THRL> __device__ __forceinline__ void attn_unit(const bf16*Qw0,int PQ,const bf16*__restrict__ Kh,int PK,const bf16*__restrict__ Vh,int PV,bf16*Ow0,int PO,int NT,int nabase,int nar0,const float*rpbh,char*shm,int&rot,bool pre,bool hasn,long dKn,long dVn){
;     ...
;   float mhat=0.f,l_reg=0.f;constexpr int ND=(MODE==2)?4:2; f32x16 o[4];o[0]=f32x16{};o[1]=f32x16{};o[2]=f32x16{};o[3]=f32x16{};f32x16 negm=f32x16{};asm volatile("":"+v"(negm));
;     ...
;   qkt(pA0,pA1,Kbase+sl_cur,qr,negm,r32,hi);asm volatile("s_nop 15\n\ts_nop 7":"+v"(pA0),"+v"(pA1));CMASK(pA0,pA1,0);
;   START(pA0,pA1);
;   _Pragma("unroll") for(int r=0;r<16;++r)pA1[r]=__builtin_amdgcn_exp2f(pA1[r]);
;   WAIT_BAR(0);
;   DMA_K(3,sl_cur);DMA_V(1,sl_next);
;   ROT();
;   kload8(kf,kp0+sl_cur);
;   if(MODE==2){WAIT_BAR(3);}else{WAIT_BAR(2);}
.LBB0_486:
	v_lshlrev_b32_e32 v0, 10, v214
	v_lshlrev_b32_e32 v35, 4, v213
	v_add3_u32 v44, s82, v0, v35
	ds_read_b128 v[36:39], v44
	ds_read_b128 v[40:43], v44 offset:512
	v_or_b32_e32 v221, v0, v35
	s_add_i32 s10, s15, s82
	s_waitcnt vmcnt(3) lgkmcnt(1)
	v_mfma_f32_32x32x16_bf16 v[18:33], v[36:39], v[148:151], v[2:17]
	v_lshl_add_u64 v[196:197], v[206:207], 0, s[54:55]
	s_and_b32 s3, s3, 0x3fffffc0
	s_lshl_b32 s3, s3, 2
	s_add_i32 s3, s3, 0x12000
	s_mov_b32 s86, 1
	v_lshlrev_b32_e32 v224, 4, v214
	v_lshl_add_u32 v218, v213, 2, s3
	s_waitcnt lgkmcnt(0)
	v_mfma_f32_32x32x16_bf16 v[2:17], v[40:43], v[148:151], v[2:17]
	ds_read_b128 v[36:39], v44 offset:2048
	ds_read_b128 v[40:43], v44 offset:2560
	s_waitcnt vmcnt(2) lgkmcnt(1)
	v_mfma_f32_32x32x16_bf16 v[18:33], v[36:39], v[140:143], v[18:33]
	s_waitcnt lgkmcnt(0)
	v_mfma_f32_32x32x16_bf16 v[2:17], v[40:43], v[140:143], v[2:17]
	ds_read_b128 v[36:39], v44 offset:4096
	ds_read_b128 v[40:43], v44 offset:4608
	s_waitcnt vmcnt(1) lgkmcnt(1)
	v_mfma_f32_32x32x16_bf16 v[18:33], v[36:39], v[132:135], v[18:33]
	s_waitcnt lgkmcnt(0)
	v_mfma_f32_32x32x16_bf16 v[2:17], v[40:43], v[132:135], v[2:17]
	ds_read_b128 v[36:39], v44 offset:6144
	ds_read_b128 v[40:43], v44 offset:6656
	s_waitcnt vmcnt(0) lgkmcnt(1)
	v_mfma_f32_32x32x16_bf16 v[18:33], v[36:39], v[128:131], v[18:33]
	v_lshlrev_b32_e32 v36, 1, v34
	v_lshlrev_b32_e32 v34, 4, v34
	v_and_b32_e32 v34, 0xc0, v34
	v_lshl_or_b32 v217, v214, 8, v34
	v_and_b32_e32 v216, 32, v36
	v_or3_b32 v220, v216, v215, v217
	s_waitcnt lgkmcnt(0)
	v_mfma_f32_32x32x16_bf16 v[2:17], v[40:43], v[128:131], v[2:17]
	s_nop 15
	s_nop 7
	s_nop 0
	v_max3_f32 v0, v18, v19, v2
	v_max3_f32 v34, v20, v21, v3
	s_nop 0
	v_max3_f32 v0, v0, v4, v5
	v_max3_f32 v34, v34, v24, v25
	s_nop 0
	v_max3_f32 v0, v0, v22, v23
	v_max3_f32 v34, v34, v8, v9
	s_nop 0
	v_max3_f32 v0, v0, v6, v7
	v_max3_f32 v34, v34, v28, v29
	s_nop 0
	v_max3_f32 v0, v0, v26, v27
	v_max3_f32 v34, v34, v12, v13
	s_nop 0
	v_max3_f32 v0, v0, v10, v11
	v_max3_f32 v34, v34, v32, v33
	s_nop 0
	v_max3_f32 v0, v0, v30, v31
	v_max3_f32 v34, v34, v16, v17
	s_nop 0
	v_max3_f32 v0, v0, v14, v15
	s_nop 0
	v_max_f32_e32 v0, v0, v34
	s_nop 0
	v_mov_b32_e32 v34, v0
	s_nop 1
	v_permlane32_swap_b32_e32 v0, v34
	v_max_f32_e32 v0, v0, v34
	s_nop 0
	v_max_f32_e32 v0, s100, v0
	v_add_f32_e32 v219, v1, v0
	v_sub_f32_e32 v2, v2, v0
	v_sub_f32_e32 v3, v3, v0
	v_sub_f32_e32 v18, v18, v0
	v_sub_f32_e32 v19, v19, v0
	v_sub_f32_e32 v20, v20, v0
	s_nop 0
	v_xor_b32_e32 v48, 0x80000000, v219
	v_mov_b32_e32 v49, v48
	v_mov_b32_e32 v50, v48
	v_mov_b32_e32 v51, v48
	v_mov_b32_e32 v52, v48
	v_mov_b32_e32 v53, v48
	v_mov_b32_e32 v54, v48
	v_mov_b32_e32 v55, v48
	v_mov_b32_e32 v56, v48
	v_mov_b32_e32 v57, v48
	v_mov_b32_e32 v58, v48
	v_mov_b32_e32 v59, v48
	v_mov_b32_e32 v60, v48
	v_mov_b32_e32 v61, v48
	v_mov_b32_e32 v62, v48
	v_mov_b32_e32 v63, v48
	s_waitcnt vmcnt(0) lgkmcnt(0)
	s_barrier
	v_sub_f32_e32 v4, v4, v0
	v_sub_f32_e32 v21, v21, v0
	v_sub_f32_e32 v5, v5, v0
	v_sub_f32_e32 v22, v22, v0
	v_sub_f32_e32 v6, v6, v0
	v_sub_f32_e32 v23, v23, v0
	v_sub_f32_e32 v7, v7, v0
	v_sub_f32_e32 v24, v24, v0
	v_sub_f32_e32 v8, v8, v0
	v_sub_f32_e32 v25, v25, v0
	v_sub_f32_e32 v9, v9, v0
	v_sub_f32_e32 v26, v26, v0
	v_sub_f32_e32 v10, v10, v0
	v_sub_f32_e32 v27, v27, v0
	v_sub_f32_e32 v11, v11, v0
	v_sub_f32_e32 v28, v28, v0
	v_sub_f32_e32 v12, v12, v0
	v_sub_f32_e32 v29, v29, v0
	v_sub_f32_e32 v13, v13, v0
	v_sub_f32_e32 v30, v30, v0
	v_sub_f32_e32 v14, v14, v0
	v_sub_f32_e32 v31, v31, v0
	v_sub_f32_e32 v15, v15, v0
	v_sub_f32_e32 v32, v32, v0
	v_sub_f32_e32 v16, v16, v0
	v_sub_f32_e32 v33, v33, v0
	v_sub_f32_e32 v0, v17, v0
	v_exp_f32_e32 v64, v2
	v_exp_f32_e32 v65, v3
	v_lshl_add_u64 v[2:3], v[204:205], 0, s[58:59]
	s_mov_b32 s11, m0
	s_mov_b32 m0, s10
	s_nop 0
	global_load_lds_dwordx4 v[2:3], off
	s_mov_b32 m0, s11
	s_lshl_b32 s10, s43, 1
	v_exp_f32_e32 v79, v0
	s_add_i32 s10, s10, s33
	s_mov_b32 s11, m0
	s_mov_b32 m0, s10
	s_nop 0
	global_load_lds_dwordx4 v[196:197], off
	s_mov_b32 m0, s11
	v_add_u32_e32 v0, s43, v221
	ds_read_b128 v[188:191], v0
	ds_read_b128 v[184:187], v0 offset:512
	ds_read_b128 v[180:183], v0 offset:2048
	ds_read_b128 v[176:179], v0 offset:2560
	ds_read_b128 v[172:175], v0 offset:4096
	ds_read_b128 v[168:171], v0 offset:4608
	ds_read_b128 v[164:167], v0 offset:6144
	ds_read_b128 v[160:163], v0 offset:6656
	v_exp_f32_e32 v80, v18
	v_exp_f32_e32 v81, v19
	v_exp_f32_e32 v82, v20
	v_exp_f32_e32 v83, v21
	v_exp_f32_e32 v84, v22
	v_exp_f32_e32 v85, v23
	v_exp_f32_e32 v86, v24
	v_exp_f32_e32 v87, v25
	v_exp_f32_e32 v88, v26
	v_exp_f32_e32 v89, v27
	v_exp_f32_e32 v90, v28
	v_exp_f32_e32 v91, v29
	v_exp_f32_e32 v92, v30
	v_exp_f32_e32 v93, v31
	v_exp_f32_e32 v94, v32
	v_exp_f32_e32 v95, v33
	v_exp_f32_e32 v66, v4
	v_exp_f32_e32 v67, v5
	v_exp_f32_e32 v68, v6
	v_exp_f32_e32 v69, v7
	v_exp_f32_e32 v70, v8
	v_exp_f32_e32 v71, v9
	v_exp_f32_e32 v72, v10
	v_exp_f32_e32 v73, v11
	v_exp_f32_e32 v74, v12
	v_exp_f32_e32 v75, v13
	v_exp_f32_e32 v76, v14
	v_exp_f32_e32 v77, v15
	v_exp_f32_e32 v78, v16
	s_waitcnt vmcnt(2) lgkmcnt(0)
	s_barrier
	s_cmpk_lg_i32 s43, 0x4000
	s_cselect_b32 s52, s52, 0
	s_andn2_b64 vcc, exec, s[8:9]
	v_cmp_gt_u32_e64 s[8:9], 32, v211
	s_cbranch_vccnz .LBB0_502
	v_mov_b32_e32 v14, v1
	v_mov_b32_e32 v15, v1
	s_mov_b64 s[10:11], 0x168000
	v_mov_b32_e32 v0, v1
	v_mov_b32_e32 v2, v1
	v_mov_b32_e32 v3, v1
	v_mov_b32_e32 v4, v1
	v_mov_b32_e32 v5, v1
	v_mov_b32_e32 v6, v1
	v_mov_b32_e32 v7, v1
	v_mov_b32_e32 v8, v1
	v_mov_b32_e32 v9, v1
	v_mov_b32_e32 v10, v1
	v_mov_b32_e32 v11, v1
	v_mov_b32_e32 v12, v1
	v_mov_b32_e32 v13, v1
	v_mov_b32_e32 v46, v14
	v_mov_b32_e32 v47, v15
	v_mov_b32_e32 v30, v14
	v_mov_b32_e32 v31, v15
	v_lshl_add_u64 v[198:199], v[206:207], 0, s[58:59]
	v_lshl_add_u64 v[200:201], v[204:205], 0, s[10:11]
	v_mov_b32_e32 v225, 0
	s_mov_b32 s67, 6
	v_mov_b32_e32 v44, v12
	v_mov_b32_e32 v45, v13
	v_mov_b32_e32 v42, v10
	v_mov_b32_e32 v43, v11
	v_mov_b32_e32 v40, v8
	v_mov_b32_e32 v41, v9
	v_mov_b32_e32 v38, v6
	v_mov_b32_e32 v39, v7
	v_mov_b32_e32 v36, v4
	v_mov_b32_e32 v37, v5
	v_mov_b32_e32 v34, v2
	v_mov_b32_e32 v35, v3
	v_mov_b32_e32 v32, v0
	v_mov_b32_e32 v33, v1
	v_mov_b32_e32 v28, v12
	v_mov_b32_e32 v29, v13
	v_mov_b32_e32 v26, v10
	v_mov_b32_e32 v27, v11
	v_mov_b32_e32 v24, v8
	v_mov_b32_e32 v25, v9
	v_mov_b32_e32 v22, v6
	v_mov_b32_e32 v23, v7
	v_mov_b32_e32 v20, v4
	v_mov_b32_e32 v21, v5
	v_mov_b32_e32 v18, v2
	v_mov_b32_e32 v19, v3
	v_mov_b32_e32 v16, v0
	v_mov_b32_e32 v17, v1

; template<int MODE,int THRL> __device__ __forceinline__ void attn_unit(const bf16*Qw0,int PQ,const bf16*__restrict__ Kh,int PK,const bf16*__restrict__ Vh,int PV,bf16*Ow0,int PO,int NT,int nabase,int nar0,const float*rpbh,char*shm,int&rot,bool pre,bool hasn,long dKn,long dVn){
;     ...
;   float mhat=0.f,l_reg=0.f;constexpr int ND=(MODE==2)?4:2; f32x16 o[4];o[0]=f32x16{};o[1]=f32x16{};o[2]=f32x16{};o[3]=f32x16{};f32x16 negm=f32x16{};asm volatile("":"+v"(negm));
.LBB0_502:
	v_mov_b32_e32 v14, v1
	v_mov_b32_e32 v15, v1
	v_mov_b32_e32 v0, v1
	v_mov_b32_e32 v2, v1
	v_mov_b32_e32 v3, v1
	v_mov_b32_e32 v4, v1
	v_mov_b32_e32 v5, v1
	v_mov_b32_e32 v6, v1
	v_mov_b32_e32 v7, v1
	v_mov_b32_e32 v8, v1
	v_mov_b32_e32 v9, v1
	v_mov_b32_e32 v10, v1
	v_mov_b32_e32 v11, v1
	v_mov_b32_e32 v12, v1
	v_mov_b32_e32 v13, v1
	v_mov_b32_e32 v30, v14
	v_mov_b32_e32 v31, v15
	v_mov_b32_e32 v46, v14
	v_mov_b32_e32 v47, v15
	v_mov_b32_e32 v225, 0
	v_mov_b32_e32 v28, v12
	v_mov_b32_e32 v29, v13
	v_mov_b32_e32 v26, v10
	v_mov_b32_e32 v27, v11
	v_mov_b32_e32 v24, v8
	v_mov_b32_e32 v25, v9
	v_mov_b32_e32 v22, v6
	v_mov_b32_e32 v23, v7
	v_mov_b32_e32 v20, v4
	v_mov_b32_e32 v21, v5
	v_mov_b32_e32 v18, v2
	v_mov_b32_e32 v19, v3
	v_mov_b32_e32 v16, v0
	v_mov_b32_e32 v17, v1
	v_mov_b32_e32 v44, v12
	v_mov_b32_e32 v45, v13
	v_mov_b32_e32 v42, v10
	v_mov_b32_e32 v43, v11
	v_mov_b32_e32 v40, v8
	v_mov_b32_e32 v41, v9
	v_mov_b32_e32 v38, v6
	v_mov_b32_e32 v39, v7
	v_mov_b32_e32 v36, v4
	v_mov_b32_e32 v37, v5
	v_mov_b32_e32 v34, v2
	v_mov_b32_e32 v35, v3
	v_mov_b32_e32 v32, v0
	v_mov_b32_e32 v33, v1
	s_branch .LBB0_504

; __device__ __forceinline__ unsigned xb_ld(unsigned* p)              { return __hip_atomic_load(p, __ATOMIC_RELAXED, __HIP_MEMORY_SCOPE_AGENT); }
; __device__ __forceinline__ unsigned xb_add(unsigned* p, unsigned v) { return __hip_atomic_fetch_add(p, v, __ATOMIC_RELAXED, __HIP_MEMORY_SCOPE_AGENT); }
; #define XB_SPIN(cond, bar) do { unsigned _sp = 0; while (cond) { __builtin_amdgcn_s_sleep(1); \
;     if ((++_sp & 255u) == 0u) { if (xb_ld(&(bar)[XB_TMO])) break; if (_sp > XB_SPIN_CAP) { atomicAdd(&(bar)[XB_TMO], 1u); break; } } } } while (0)
; __device__ __forceinline__ void xcd_barrier(const XcdBarrier& b) {
;     ...
;             const unsigned og = xb_add(&bar[XB_TOP], 1u);
;             const unsigned tg = og / nx;
;             if (og + 1u == (tg + 1u) * nx) xb_add(&bar[XB_TOPGEN], 1u);
;             else XB_SPIN(xb_ld(&bar[XB_TOPGEN]) == tg, bar);
.LBB0_698:
	s_or_b64 exec, exec, s[52:53]
	v_cvt_f32_u32_e32 v3, v0
	s_waitcnt vmcnt(0)
	v_readfirstlane_b32 s0, v2
	s_add_u32 s52, s30, 0x1bbc3500
	s_addc_u32 s53, s31, 0
	v_rcp_iflag_f32_e32 v3, v3
	v_add_u32_e32 v1, s0, v1
	v_add_u32_e32 v4, 1, v1
	s_mov_b64 s[54:55], -1
	v_mul_f32_e32 v2, 0x4f7ffffe, v3
	v_cvt_u32_f32_e32 v2, v2
	v_sub_u32_e32 v3, 0, v0
	v_mul_lo_u32 v3, v3, v2
	v_mul_hi_u32 v3, v2, v3
	v_add_u32_e32 v2, v2, v3
	v_mul_hi_u32 v2, v1, v2
	v_mul_lo_u32 v3, v2, v0
	v_sub_u32_e32 v1, v1, v3
	v_add_u32_e32 v5, 1, v2
	v_cmp_ge_u32_e32 vcc, v1, v0
	v_sub_u32_e32 v3, v1, v0
	s_nop 0
	v_cndmask_b32_e32 v2, v2, v5, vcc
	v_cndmask_b32_e32 v1, v1, v3, vcc
	v_add_u32_e32 v3, 1, v2
	v_cmp_ge_u32_e32 vcc, v1, v0
	s_nop 1
	v_cndmask_b32_e32 v2, v2, v3, vcc
	v_mul_lo_u32 v1, v0, v2
	v_add_u32_e32 v0, v1, v0
	v_cmp_ne_u32_e32 vcc, v4, v0
	v_mov_b32_e32 v0, s52
	v_mov_b32_e32 v1, s53
	s_and_saveexec_b64 s[36:37], vcc
	s_cbranch_execz .LBB0_710
	v_mov_b32_e32 v0, 0
	global_load_dword v1, v0, s[52:53] sc1
	s_mov_b64 s[58:59], 0
	s_waitcnt vmcnt(0)
	v_cmp_eq_u32_e32 vcc, v1, v2
	s_and_saveexec_b64 s[56:57], vcc
	s_cbranch_execz .LBB0_709
	s_add_u32 s54, s30, 0x1bbc0200
	s_addc_u32 s55, s31, 0
	s_mov_b32 s0, 1
	s_branch .LBB0_702

; __device__ __forceinline__ unsigned xb_ld(unsigned* p)              { return __hip_atomic_load(p, __ATOMIC_RELAXED, __HIP_MEMORY_SCOPE_AGENT); }
; #define XB_SPIN(cond, bar) do { unsigned _sp = 0; while (cond) { __builtin_amdgcn_s_sleep(1); \
;     if ((++_sp & 255u) == 0u) { if (xb_ld(&(bar)[XB_TMO])) break; if (_sp > XB_SPIN_CAP) { atomicAdd(&(bar)[XB_TMO], 1u); break; } } } } while (0)
; __device__ __forceinline__ void xcd_barrier(const XcdBarrier& b) {
;     ...
;             else XB_SPIN(xb_ld(&bar[XB_TOPGEN]) == tg, bar);
.LBB0_709:
	s_or_b64 exec, exec, s[56:57]
	v_mov_b32_e32 v0, s54
	v_mov_b32_e32 v1, s55
	s_orn2_b64 s[54:55], s[58:59], exec

; __device__ __forceinline__ void norm_mod_phase(const float* lat, long lat_bs, const float* cx, long ctx_bs, const float* modl, int shoff, int scoff, bf16* XN, int skip_ctx, int gw, int NGW, float* xcopy, const float* part, int nkc, const float* pgate) {
;     int t_ = threadIdx.x; asm volatile("" : "+v"(t_)); const int lane = t_ & 63;
;     f32x4 vn[4]; int sn = 0;
;     { if (gw < MROWS) { const float* src = row_src(gw, lat, lat_bs, cx, ctx_bs, sn); const f32x4* xr = (const f32x4*)src + lane;
; #pragma unroll
;         for (int j = 0; j < 4; ++j) vn[j] = xr[64 * j]; } }
;     for (int row = gw; row < MROWS; row += NGW) {
;         const int s = sn; f32x4 v[4]; float ss = 0.f;
; #pragma unroll
;         for (int j = 0; j < 4; ++j) v[j] = vn[j];
;         if (row + NGW < MROWS) { const float* srcn = row_src(row + NGW, lat, lat_bs, cx, ctx_bs, sn); const f32x4* xr = (const f32x4*)srcn + lane;
; #pragma unroll
;             for (int j = 0; j < 4; ++j) vn[j] = xr[64 * j]; }
;     ...
;         if (xcopy && s == 4) {
;             const int b_ = row / TPB, cr = b_ * CTXL + (row - b_ * TPB); const f32x4* gp = (const f32x4*)(pgate + 4 * NMOD6) + lane;
;             f32x4 sm[4];
; #pragma unroll
;             for (int j = 0; j < 4; ++j) sm[j] = (f32x4){0.f, 0.f, 0.f, 0.f};
;             for (int kc = 0; kc < nkc; ++kc) { const f32x4* pp = (const f32x4*)(part + ((size_t)kc * 1024 + cr) * DMODEL) + lane;
; #pragma unroll
;                 for (int j = 0; j < 4; ++j) sm[j] += pp[64 * j]; }
.LBB0_720:
	s_lshl_b64 s[6:7], s[52:53], 12
	v_and_b32_e32 v16, 63, v0
	s_add_u32 s6, s36, s6
	s_addc_u32 s7, s37, s7
	v_lshlrev_b32_e32 v32, 4, v16
	global_load_dwordx4 v[12:15], v32, s[6:7]
	global_load_dwordx4 v[8:11], v32, s[6:7] offset:1024
	global_load_dwordx4 v[4:7], v32, s[6:7] offset:2048
	global_load_dwordx4 v[0:3], v32, s[6:7] offset:3072
	v_mov_b32_e32 v33, 0
	v_mbcnt_hi_u32_b32 v17, -1, v223
	v_lshlrev_b32_e32 v18, 3, v16
	v_mov_b32_e32 v19, v33
	v_and_b32_e32 v22, 64, v17
	v_xor_b32_e32 v23, 1, v17
	v_lshl_add_u64 v[36:37], s[46:47], 0, v[18:19]
	v_add_u32_e32 v18, 64, v22
	v_xor_b32_e32 v24, 2, v17
	v_readlane_b32 s38, v254, 8
	v_cmp_lt_i32_e32 vcc, v23, v18
	s_mov_b64 s[54:55], 0x2f9a000
	v_xor_b32_e32 v25, 4, v17
	v_lshl_add_u64 v[20:21], s[30:31], 0, v[32:33]
	v_readlane_b32 s39, v254, 9
	v_cndmask_b32_e32 v19, v17, v23, vcc
	v_cmp_lt_i32_e32 vcc, v24, v18
	v_xor_b32_e32 v26, 8, v17
	s_ashr_i32 s39, s38, 31
	v_lshl_add_u64 v[38:39], v[20:21], 0, s[54:55]
	v_cndmask_b32_e32 v20, v17, v24, vcc
	v_cmp_lt_i32_e32 vcc, v25, v18
	v_xor_b32_e32 v27, 16, v17
	s_ashr_i32 s43, s42, 31
	v_cndmask_b32_e32 v21, v17, v25, vcc
	v_cmp_lt_i32_e32 vcc, v26, v18
	s_lshl_b64 s[56:57], s[38:39], 12
	v_xor_b32_e32 v28, 32, v17
	v_cndmask_b32_e32 v22, v17, v26, vcc
	v_cmp_lt_i32_e32 vcc, v27, v18
	s_add_u32 s60, s30, s56
	s_addc_u32 s61, s31, s57
	v_cndmask_b32_e32 v23, v17, v27, vcc
	v_cmp_lt_i32_e32 vcc, v28, v18
	s_mov_b64 s[58:59], 0x2fc0000
	v_lshlrev_b32_e32 v44, 2, v19
	v_cndmask_b32_e32 v17, v17, v28, vcc
	v_lshl_add_u64 v[18:19], s[60:61], 0, v[32:33]
	s_mov_b32 s9, 0
	v_lshl_add_u64 v[34:35], s[10:11], 0, v[32:33]
	s_mov_b32 s8, s38
	v_lshlrev_b32_e32 v45, 2, v20
	v_lshlrev_b32_e32 v46, 2, v21
	v_lshlrev_b32_e32 v47, 2, v22
	v_lshlrev_b32_e32 v48, 2, v23
	v_lshlrev_b32_e32 v49, 2, v17
	v_lshlrev_b32_e32 v32, 4, v16
	v_lshl_add_u64 v[40:41], v[18:19], 0, s[58:59]
	s_mov_b32 s1, 0x400000
	s_mov_b32 s3, 0x800000
	s_mov_b32 s6, 0xc00000
	v_mov_b32_e32 v42, 0x358637bd
	s_mov_b32 s7, 0xf800000
	v_mov_b32_e32 v43, 0x260
	s_mov_b64 s[36:37], 0x3000
	s_mov_b64 s[52:53], 0x4000
	s_movk_i32 s12, 0x4000
	s_movk_i32 s13, 0x7fff
	s_mov_b32 s14, 0xffff0000
	v_writelane_b32 v254, s8, 8
	s_mov_b64 s[54:55], s[38:39]
	s_lshl_b64 s[56:57], s[42:43], 12
	v_writelane_b32 v254, s9, 9
	s_waitcnt vmcnt(3)
	v_mov_b32_e32 v18, v14
	v_mov_b32_e32 v19, v15
	s_waitcnt vmcnt(2)
	v_mov_b32_e32 v22, v10
	v_mov_b32_e32 v23, v11
	s_waitcnt vmcnt(1)
	v_mov_b32_e32 v26, v6
	v_mov_b32_e32 v27, v7
	s_waitcnt vmcnt(0)
	v_mov_b32_e32 v30, v2
	v_mov_b32_e32 v31, v3
	v_mov_b32_e32 v16, v12
	v_mov_b32_e32 v17, v13
	v_mov_b32_e32 v20, v8
	v_mov_b32_e32 v21, v9
	v_mov_b32_e32 v24, v4
	v_mov_b32_e32 v25, v5
	v_mov_b32_e32 v28, v0
	v_mov_b32_e32 v29, v1
	s_branch .LBB0_722
; __device__ __forceinline__ unsigned pk2(float lo, float hi) { return f2bf(lo) | (f2bf(hi) << 16); }
; __device__ __forceinline__ void norm_mod_phase(const float* lat, long lat_bs, const float* cx, long ctx_bs, const float* modl, int shoff, int scoff, bf16* XN, int skip_ctx, int gw, int NGW, float* xcopy, const float* part, int nkc, const float* pgate) {
;     ...
;     for (int row = gw; row < MROWS; row += NGW) {
;         const int s = sn; f32x4 v[4]; float ss = 0.f;
; #pragma unroll
;         for (int j = 0; j < 4; ++j) v[j] = vn[j];
;         if (row + NGW < MROWS) { const float* srcn = row_src(row + NGW, lat, lat_bs, cx, ctx_bs, sn); const f32x4* xr = (const f32x4*)srcn + lane;
; #pragma unroll
;             for (int j = 0; j < 4; ++j) vn[j] = xr[64 * j]; }
;         if (skip_ctx && s == 4) continue;
; #pragma unroll
;         for (int j = 0; j < 4; ++j) ss += (v[j].x * v[j].x + v[j].y * v[j].y) + (v[j].z * v[j].z + v[j].w * v[j].w);
;         if (xcopy && s == 4) {
;             const int b_ = row / TPB, cr = b_ * CTXL + (row - b_ * TPB); const f32x4* gp = (const f32x4*)(pgate + 4 * NMOD6) + lane;
;             f32x4 sm[4];
; #pragma unroll
;             for (int j = 0; j < 4; ++j) sm[j] = (f32x4){0.f, 0.f, 0.f, 0.f};
;             for (int kc = 0; kc < nkc; ++kc) { const f32x4* pp = (const f32x4*)(part + ((size_t)kc * 1024 + cr) * DMODEL) + lane;
; #pragma unroll
;                 for (int j = 0; j < 4; ++j) sm[j] += pp[64 * j]; }
;             f32x4* xc = (f32x4*)(xcopy + (size_t)row * DMODEL) + lane; ss = 0.f;
; #pragma unroll
;             for (int j = 0; j < 4; ++j) { v[j] += gp[64 * j] * sm[j]; xc[64 * j] = v[j]; ss += (v[j].x * v[j].x + v[j].y * v[j].y) + (v[j].z * v[j].z + v[j].w * v[j].w); } }
;         const float rstd = 1.0f / sqrtf(wave_sum(ss) * (1.0f / DMODEL) + EPS);
;         const f32x4* sh = (const f32x4*)(modl + s * NMOD6 + shoff) + lane; const f32x4* sc = (const f32x4*)(modl + s * NMOD6 + scoff) + lane;
;         v2u* o8 = (v2u*)(XN + (size_t)row * DMODEL) + lane;
; #pragma unroll
;         for (int j = 0; j < 4; ++j) { const f32x4 a = sh[64 * j], m = sc[64 * j]; const f32x4 y = v[j] * rstd * (m + 1.0f) + a; v2u w; w.x = pk2(y.x, y.y); w.y = pk2(y.z, y.w); o8[64 * j] = w; }
.LBB0_721:
	s_add_u32 s54, s54, s42
	s_mulk_i32 s4, 0x1800
	s_addc_u32 s55, s55, s43
	s_ashr_i32 s5, s4, 31
	s_lshl_b64 s[4:5], s[4:5], 2
	s_add_u32 s4, s68, s4
	s_addc_u32 s5, s69, s5
	v_lshl_add_u64 v[60:61], s[4:5], 0, v[32:33]
	v_add_co_u32_e32 v56, vcc, s12, v60
	ds_bpermute_b32 v51, v44, v50
	s_nop 0
	v_addc_co_u32_e32 v57, vcc, 0, v61, vcc
	global_load_dwordx4 v[52:55], v[56:57], off
	s_nop 0
	global_load_dwordx4 v[56:59], v[56:57], off offset:-4096
	s_lshl_b64 s[4:5], s[60:61], 11
	s_waitcnt lgkmcnt(0)
	v_add_f32_e32 v50, v50, v51
	ds_bpermute_b32 v51, v45, v50
	v_lshl_add_u64 v[62:63], v[36:37], 0, s[4:5]
	v_lshl_add_u64 v[40:41], v[40:41], 0, s[56:57]
	s_cmp_lt_i32 s54, 0x8400
	s_waitcnt lgkmcnt(0)
	v_add_f32_e32 v50, v50, v51
	ds_bpermute_b32 v51, v46, v50
	s_waitcnt lgkmcnt(0)
	v_add_f32_e32 v50, v50, v51
	ds_bpermute_b32 v51, v47, v50
	s_waitcnt lgkmcnt(0)
	v_add_f32_e32 v50, v50, v51
	ds_bpermute_b32 v51, v48, v50
	s_waitcnt lgkmcnt(0)
	v_add_f32_e32 v50, v50, v51
	ds_bpermute_b32 v51, v49, v50
	s_waitcnt lgkmcnt(0)
	v_add_f32_e32 v50, v50, v51
	v_fmamk_f32 v50, v50, 0x3a800000, v42
	v_mul_f32_e32 v51, 0x4f800000, v50
	v_cmp_gt_f32_e32 vcc, s7, v50
	s_waitcnt vmcnt(1)
	v_add_f32_e32 v52, 1.0, v52
	v_add_f32_e32 v53, 1.0, v53
	v_cndmask_b32_e32 v50, v50, v51, vcc
	v_sqrt_f32_e32 v51, v50
	s_nop 0
	v_add_u32_e32 v64, -1, v51
	v_add_u32_e32 v65, 1, v51
	v_fma_f32 v66, -v64, v51, v50
	v_fma_f32 v67, -v65, v51, v50
	v_cmp_ge_f32_e64 s[4:5], 0, v66
	s_nop 1
	v_cndmask_b32_e64 v51, v51, v64, s[4:5]
	v_cmp_lt_f32_e64 s[4:5], 0, v67
	s_nop 1
	v_cndmask_b32_e64 v51, v51, v65, s[4:5]
	v_mul_f32_e32 v64, 0x37800000, v51
	v_cndmask_b32_e32 v51, v51, v64, vcc
	v_cmp_class_f32_e32 vcc, v50, v43
	v_lshl_add_u64 v[64:65], v[60:61], 0, s[52:53]
	s_nop 0
	v_cndmask_b32_e32 v50, v51, v50, vcc
	v_div_scale_f32 v51, s[4:5], v50, v50, 1.0
	v_rcp_f32_e32 v66, v51
	v_div_scale_f32 v67, vcc, 1.0, v50, 1.0
	s_mov_b32 s4, s58
	v_fma_f32 v68, -v51, v66, 1.0
	v_fmac_f32_e32 v66, v68, v66
	v_mul_f32_e32 v68, v67, v66
	v_fma_f32 v69, -v51, v68, v67
	v_fmac_f32_e32 v68, v69, v66
	v_fma_f32 v51, -v51, v68, v67
	v_div_fmas_f32 v51, v51, v66, v68
	v_div_fixup_f32 v66, v51, v50, 1.0
	v_mul_f32_e32 v12, v12, v66
	v_mul_f32_e32 v13, v13, v66
	v_mul_f32_e32 v14, v14, v66
	v_mul_f32_e32 v15, v15, v66
	v_add_f32_e32 v50, 1.0, v54
	v_add_f32_e32 v51, 1.0, v55
	s_waitcnt vmcnt(0)
	v_fma_f32 v12, v52, v12, v56
	v_fma_f32 v13, v53, v13, v57
	v_fma_f32 v14, v50, v14, v58
	v_fma_f32 v15, v51, v15, v59
	v_bfe_u32 v50, v12, 16, 1
	v_bfe_u32 v52, v14, 16, 1
	v_bfe_u32 v51, v13, 16, 1
	v_bfe_u32 v53, v15, 16, 1
	v_add3_u32 v12, v12, v50, s13
	v_add3_u32 v14, v14, v52, s13
	v_add3_u32 v13, v13, v51, s13
	v_add3_u32 v15, v15, v53, s13
	v_lshrrev_b32_e32 v12, 16, v12
	v_lshrrev_b32_e32 v14, 16, v14
	v_and_or_b32 v12, v13, s14, v12
	v_and_or_b32 v13, v15, s14, v14
	global_store_dwordx2 v[62:63], v[12:13], off
	global_load_dwordx4 v[12:15], v[64:65], off offset:1024
	v_lshl_add_u64 v[54:55], v[60:61], 0, s[36:37]
	global_load_dwordx4 v[50:53], v[54:55], off offset:1024
	global_load_dwordx4 v[100:103], v[64:65], off offset:2048
	global_load_dwordx4 v[104:107], v[54:55], off offset:2048
	global_load_dwordx4 v[108:111], v[64:65], off offset:3072
	global_load_dwordx4 v[112:115], v[54:55], off offset:3072
	v_mul_f32_e32 v8, v8, v66
	v_mul_f32_e32 v9, v9, v66
	v_mul_f32_e32 v10, v10, v66
	v_mul_f32_e32 v11, v11, v66
	v_mul_f32_e32 v4, v4, v66
	v_mul_f32_e32 v5, v5, v66
	v_mul_f32_e32 v6, v6, v66
	v_mul_f32_e32 v7, v7, v66
	v_mul_f32_e32 v58, v0, v66
	v_mul_f32_e32 v59, v1, v66
	v_mul_f32_e32 v60, v2, v66
	v_mul_f32_e32 v61, v3, v66
	v_mov_b32_e32 v0, v28
	v_mov_b32_e32 v1, v29
	v_mov_b32_e32 v2, v30
	v_mov_b32_e32 v3, v31
	s_waitcnt vmcnt(5)
	v_add_f32_e32 v14, 1.0, v14
	v_add_f32_e32 v15, 1.0, v15
	v_add_f32_e32 v12, 1.0, v12
	v_add_f32_e32 v13, 1.0, v13
	s_waitcnt vmcnt(4)
	v_fma_f32 v10, v14, v10, v52
	v_fma_f32 v11, v15, v11, v53
	v_fma_f32 v8, v12, v8, v50
	v_fma_f32 v9, v13, v9, v51
	v_bfe_u32 v14, v10, 16, 1
	v_bfe_u32 v12, v8, 16, 1
	v_bfe_u32 v13, v9, 16, 1
	v_bfe_u32 v15, v11, 16, 1
	v_add3_u32 v8, v8, v12, s13
	v_add3_u32 v10, v10, v14, s13
	v_add3_u32 v9, v9, v13, s13
	v_add3_u32 v11, v11, v15, s13
	v_lshrrev_b32_e32 v8, 16, v8
	v_lshrrev_b32_e32 v10, 16, v10
	v_and_or_b32 v8, v9, s14, v8
	v_and_or_b32 v9, v11, s14, v10
	global_store_dwordx2 v[62:63], v[8:9], off offset:512
	s_nop 0
	s_waitcnt vmcnt(4)
	v_add_f32_e32 v10, 1.0, v102
	v_add_f32_e32 v11, 1.0, v103
	v_add_f32_e32 v8, 1.0, v100
	v_add_f32_e32 v9, 1.0, v101
	s_waitcnt vmcnt(3)
	v_fma_f32 v6, v6, v10, v106
	v_fma_f32 v7, v7, v11, v107
	v_fma_f32 v4, v4, v8, v104
	v_fma_f32 v5, v5, v9, v105
	v_bfe_u32 v10, v6, 16, 1
	v_bfe_u32 v8, v4, 16, 1
	v_bfe_u32 v9, v5, 16, 1
	v_bfe_u32 v11, v7, 16, 1
	v_add3_u32 v4, v4, v8, s13
	v_add3_u32 v6, v6, v10, s13
	v_add3_u32 v5, v5, v9, s13
	v_add3_u32 v7, v7, v11, s13
	v_lshrrev_b32_e32 v4, 16, v4
	v_lshrrev_b32_e32 v6, 16, v6
	v_and_or_b32 v4, v5, s14, v4
	v_and_or_b32 v5, v7, s14, v6
	global_store_dwordx2 v[62:63], v[4:5], off offset:1024
	s_nop 0
	v_mov_b32_e32 v4, v24
	v_mov_b32_e32 v5, v25
	v_mov_b32_e32 v8, v20
	v_mov_b32_e32 v9, v21
	v_mov_b32_e32 v12, v16
	v_mov_b32_e32 v13, v17
	v_mov_b32_e32 v6, v26
	v_mov_b32_e32 v7, v27
	v_mov_b32_e32 v10, v22
	v_mov_b32_e32 v11, v23
	v_mov_b32_e32 v14, v18
	v_mov_b32_e32 v15, v19
	s_waitcnt vmcnt(3)
	v_add_f32_e32 v52, 1.0, v110
	v_add_f32_e32 v53, 1.0, v111
	v_add_f32_e32 v50, 1.0, v108
	v_add_f32_e32 v51, 1.0, v109
	s_waitcnt vmcnt(2)
	v_fma_f32 v52, v60, v52, v114
	v_fma_f32 v53, v61, v53, v115
	v_fma_f32 v50, v58, v50, v112
	v_fma_f32 v51, v59, v51, v113
	v_bfe_u32 v56, v52, 16, 1
	v_bfe_u32 v54, v50, 16, 1
	v_bfe_u32 v55, v51, 16, 1
	v_bfe_u32 v57, v53, 16, 1
	v_add3_u32 v50, v50, v54, s13
	v_add3_u32 v52, v52, v56, s13
	v_add3_u32 v51, v51, v55, s13
	v_add3_u32 v53, v53, v57, s13
	v_lshrrev_b32_e32 v50, 16, v50
	v_lshrrev_b32_e32 v52, 16, v52
	v_and_or_b32 v50, v51, s14, v50
	v_and_or_b32 v51, v53, s14, v52
	global_store_dwordx2 v[62:63], v[50:51], off offset:1536
	s_cbranch_scc0 .LBB0_732

; __device__ __forceinline__ unsigned xb_ld(unsigned* p)              { return __hip_atomic_load(p, __ATOMIC_RELAXED, __HIP_MEMORY_SCOPE_AGENT); }
; __device__ __forceinline__ unsigned xb_add(unsigned* p, unsigned v) { return __hip_atomic_fetch_add(p, v, __ATOMIC_RELAXED, __HIP_MEMORY_SCOPE_AGENT); }
; #define XB_SPIN(cond, bar) do { unsigned _sp = 0; while (cond) { __builtin_amdgcn_s_sleep(1); \
;     if ((++_sp & 255u) == 0u) { if (xb_ld(&(bar)[XB_TMO])) break; if (_sp > XB_SPIN_CAP) { atomicAdd(&(bar)[XB_TMO], 1u); break; } } } } while (0)
; __device__ __forceinline__ void xcd_barrier(const XcdBarrier& b) {
;     ...
;             const unsigned og = xb_add(&bar[XB_TOP], 1u);
;             const unsigned tg = og / nx;
;             if (og + 1u == (tg + 1u) * nx) xb_add(&bar[XB_TOPGEN], 1u);
;             else XB_SPIN(xb_ld(&bar[XB_TOPGEN]) == tg, bar);
.LBB0_767:
	s_or_b64 exec, exec, s[40:41]
	v_cvt_f32_u32_e32 v3, v0
	s_waitcnt vmcnt(0)
	v_readfirstlane_b32 s1, v2
	s_add_u32 s40, s30, 0x1bbc3500
	s_addc_u32 s41, s31, 0
	v_rcp_iflag_f32_e32 v3, v3
	v_add_u32_e32 v1, s1, v1
	v_add_u32_e32 v4, 1, v1
	s_mov_b64 s[52:53], -1
	v_mul_f32_e32 v2, 0x4f7ffffe, v3
	v_cvt_u32_f32_e32 v2, v2
	v_sub_u32_e32 v3, 0, v0
	v_mul_lo_u32 v3, v3, v2
	v_mul_hi_u32 v3, v2, v3
	v_add_u32_e32 v2, v2, v3
	v_mul_hi_u32 v2, v1, v2
	v_mul_lo_u32 v3, v2, v0
	v_sub_u32_e32 v1, v1, v3
	v_add_u32_e32 v5, 1, v2
	v_cmp_ge_u32_e32 vcc, v1, v0
	v_sub_u32_e32 v3, v1, v0
	s_nop 0
	v_cndmask_b32_e32 v2, v2, v5, vcc
	v_cndmask_b32_e32 v1, v1, v3, vcc
	v_add_u32_e32 v3, 1, v2
	v_cmp_ge_u32_e32 vcc, v1, v0
	s_nop 1
	v_cndmask_b32_e32 v2, v2, v3, vcc
	v_mul_lo_u32 v1, v0, v2
	v_add_u32_e32 v0, v1, v0
	v_cmp_ne_u32_e32 vcc, v4, v0
	v_mov_b32_e32 v0, s40
	v_mov_b32_e32 v1, s41
	s_and_saveexec_b64 s[36:37], vcc
	s_cbranch_execz .LBB0_779
	v_mov_b32_e32 v0, 0
	global_load_dword v1, v0, s[40:41] sc1
	s_mov_b64 s[56:57], 0
	s_waitcnt vmcnt(0)
	v_cmp_eq_u32_e32 vcc, v1, v2
	s_and_saveexec_b64 s[54:55], vcc
	s_cbranch_execz .LBB0_778
	s_add_u32 s52, s30, 0x1bbc0200
	s_addc_u32 s53, s31, 0
	s_mov_b32 s1, 1
	s_branch .LBB0_771

; __device__ __forceinline__ unsigned xb_ld(unsigned* p)              { return __hip_atomic_load(p, __ATOMIC_RELAXED, __HIP_MEMORY_SCOPE_AGENT); }
; #define XB_SPIN(cond, bar) do { unsigned _sp = 0; while (cond) { __builtin_amdgcn_s_sleep(1); \
;     if ((++_sp & 255u) == 0u) { if (xb_ld(&(bar)[XB_TMO])) break; if (_sp > XB_SPIN_CAP) { atomicAdd(&(bar)[XB_TMO], 1u); break; } } } } while (0)
; __device__ __forceinline__ void xcd_barrier(const XcdBarrier& b) {
;     ...
;             else XB_SPIN(xb_ld(&bar[XB_TOPGEN]) == tg, bar);
.LBB0_778:
	s_or_b64 exec, exec, s[54:55]
	v_mov_b32_e32 v0, s52
	v_mov_b32_e32 v1, s53
	s_orn2_b64 s[52:53], s[56:57], exec

; __device__ __forceinline__ unsigned cvt_pk_bf16(float lo, float hi) { unsigned r; asm volatile("v_cvt_pk_bf16_f32 %0, %1, %2" : "=v"(r) : "v"(lo), "v"(hi)); return r; }
;     __device__ __forceinline__ void operator()(const f32x4 (&acc)[2][2][4][2], const Unit& u, int wr, int wc, int fr, int fq) const {
;         const int row0 = u.pm * BM + wr * 64 + fr, col0 = u.pn * HALF + wc * 32 + 8 * fq;
; #pragma unroll
;         for (int ai = 0; ai < 2; ++ai)
; #pragma unroll
;             for (int m = 0; m < 4; ++m) { bf16_t* rowp = H + (size_t)(row0 + ai * HALF + m * 16) * ldh + col0; float hv[8];
; #pragma unroll
;                 for (int n = 0; n < 2; ++n)
; #pragma unroll
;                     for (int e = 0; e < 4; ++e) { const float g = acc[ai][0][m][n][e], up = acc[ai][1][m][n][e]; hv[n * 4 + e] = g * __builtin_amdgcn_rcpf(1.0f + __expf(-g)) * up; }
;                 u32x4 w; w.x = cvt_pk_bf16(hv[0], hv[1]); w.y = cvt_pk_bf16(hv[2], hv[3]); w.z = cvt_pk_bf16(hv[4], hv[5]); w.w = cvt_pk_bf16(hv[6], hv[7]);
;                 *(u32x4*)rowp = w; }
.LBB0_796:
	v_mul_f32_e32 v144, 0xbfb8aa3b, v124
	v_exp_f32_e32 v168, v144
	v_mul_f32_e32 v144, 0xbfb8aa3b, v125
	v_exp_f32_e32 v169, v144
	v_lshl_or_b32 v166, s33, 7, v148
	v_add_f32_e32 v168, 1.0, v168
	v_rcp_f32_e32 v170, v168
	v_add_f32_e32 v168, 1.0, v169
	v_rcp_f32_e32 v171, v168
	v_lshl_add_u32 v165, s60, 8, v146
	v_mul_f32_e32 v124, v124, v170
	v_mul_f32_e32 v116, v124, v116
	v_mul_f32_e32 v124, v125, v171
	v_mul_f32_e32 v125, 0xbfb8aa3b, v126
	v_exp_f32_e32 v125, v125
	v_mul_f32_e32 v170, 0xbfb8aa3b, v127
	v_exp_f32_e32 v170, v170
	v_mul_f32_e32 v117, v124, v117
	v_add_f32_e32 v124, 1.0, v125
	v_rcp_f32_e32 v124, v124
	v_add_f32_e32 v125, 1.0, v170
	v_mul_f32_e32 v170, 0xbfb8aa3b, v120
	v_rcp_f32_e32 v125, v125
	v_exp_f32_e32 v170, v170
	v_mul_f32_e32 v124, v126, v124
	v_mul_f32_e32 v124, v124, v118
	v_mul_f32_e32 v118, v127, v125
	v_add_f32_e32 v125, 1.0, v170
	v_rcp_f32_e32 v125, v125
	v_mul_f32_e32 v126, 0xbfb8aa3b, v121
	v_mul_f32_e32 v127, v118, v119
	v_exp_f32_e32 v126, v126
	v_mul_f32_e32 v118, v120, v125
	v_mul_f32_e32 v120, v118, v112
	v_mul_f32_e32 v118, 0xbfb8aa3b, v122
	v_exp_f32_e32 v118, v118
	v_mul_f32_e32 v119, 0xbfb8aa3b, v123
	v_exp_f32_e32 v119, v119
	v_add_f32_e32 v112, 1.0, v126
	v_rcp_f32_e32 v112, v112
	v_add_f32_e32 v118, 1.0, v118
	v_rcp_f32_e32 v118, v118
	v_add_f32_e32 v119, 1.0, v119
	v_rcp_f32_e32 v119, v119
	v_mul_f32_e32 v112, v121, v112
	v_mul_f32_e32 v121, v112, v113
	v_mul_f32_e32 v112, v122, v118
	v_ashrrev_i32_e32 v167, 31, v166
	v_mov_b32_e32 v144, s44
	v_mov_b32_e32 v145, s45
	v_mul_f32_e32 v122, v112, v114
	v_mul_f32_e32 v112, v123, v119
	v_mad_i64_i32 v[168:169], s[6:7], v165, s81, v[144:145]
	v_mul_f32_e32 v123, v112, v115
	v_lshlrev_b64 v[112:113], 1, v[166:167]
	v_lshl_add_u64 v[118:119], v[168:169], 0, v[112:113]
	v_cvt_pk_bf16_f32 v114, v116, v117
	v_cvt_pk_bf16_f32 v115, v124, v127
	v_cvt_pk_bf16_f32 v116, v120, v121
	v_cvt_pk_bf16_f32 v117, v122, v123
	global_store_dwordx4 v[118:119], v[114:117], off
	s_andn2_b64 vcc, exec, s[4:5]
	s_mov_b64 s[4:5], -1
	v_mul_f32_e32 v114, 0xbfb8aa3b, v108
	v_exp_f32_e32 v114, v114
	v_mul_f32_e32 v115, 0xbfb8aa3b, v109
	v_exp_f32_e32 v115, v115
	v_or_b32_e32 v116, 16, v165
	v_add_f32_e32 v114, 1.0, v114
	v_rcp_f32_e32 v117, v114
	v_add_f32_e32 v114, 1.0, v115
	v_rcp_f32_e32 v118, v114
	v_mad_i64_i32 v[114:115], s[6:7], v116, s81, v[144:145]
	v_mul_f32_e32 v108, v108, v117
	v_mul_f32_e32 v108, v108, v100
	v_mul_f32_e32 v100, v109, v118
	v_mul_f32_e32 v109, 0xbfb8aa3b, v110
	v_exp_f32_e32 v109, v109
	v_mul_f32_e32 v116, 0xbfb8aa3b, v111
	v_exp_f32_e32 v116, v116
	v_mul_f32_e32 v117, v100, v101
	v_add_f32_e32 v100, 1.0, v109
	v_rcp_f32_e32 v100, v100
	v_add_f32_e32 v101, 1.0, v116
	v_mul_f32_e32 v109, 0xbfb8aa3b, v104
	v_rcp_f32_e32 v101, v101
	v_exp_f32_e32 v109, v109
	v_mul_f32_e32 v100, v110, v100
	v_mul_f32_e32 v102, v100, v102
	v_mul_f32_e32 v100, v111, v101
	v_add_f32_e32 v101, 1.0, v109
	v_rcp_f32_e32 v101, v101
	v_mul_f32_e32 v109, 0xbfb8aa3b, v105
	v_mul_f32_e32 v103, v100, v103
	v_exp_f32_e32 v109, v109
	v_mul_f32_e32 v100, v104, v101
	v_mul_f32_e32 v104, v100, v96
	v_mul_f32_e32 v100, 0xbfb8aa3b, v106
	v_exp_f32_e32 v100, v100
	v_mul_f32_e32 v101, 0xbfb8aa3b, v107
	v_exp_f32_e32 v101, v101
	v_add_f32_e32 v96, 1.0, v109
	v_rcp_f32_e32 v96, v96
	v_add_f32_e32 v100, 1.0, v100
	v_rcp_f32_e32 v100, v100
	v_add_f32_e32 v101, 1.0, v101
	v_rcp_f32_e32 v101, v101
	v_mul_f32_e32 v96, v105, v96
	v_mul_f32_e32 v105, v96, v97
	v_mul_f32_e32 v96, v106, v100
	v_mul_f32_e32 v106, v96, v98
	v_mul_f32_e32 v96, v107, v101
	v_mul_f32_e32 v99, v96, v99
	v_lshl_add_u64 v[100:101], v[114:115], 0, v[112:113]
	v_cvt_pk_bf16_f32 v96, v108, v117
	v_cvt_pk_bf16_f32 v97, v102, v103
	v_cvt_pk_bf16_f32 v98, v104, v105
	v_cvt_pk_bf16_f32 v99, v106, v99
	global_store_dwordx4 v[100:101], v[96:99], off
	s_nop 1
	v_mul_f32_e32 v96, 0xbfb8aa3b, v92
	v_exp_f32_e32 v96, v96
	v_mul_f32_e32 v97, 0xbfb8aa3b, v93
	v_exp_f32_e32 v97, v97
	v_or_b32_e32 v98, 32, v165
	v_add_f32_e32 v96, 1.0, v96
	v_rcp_f32_e32 v99, v96
	v_add_f32_e32 v96, 1.0, v97
	v_rcp_f32_e32 v100, v96
	v_mad_i64_i32 v[96:97], s[6:7], v98, s81, v[144:145]
	v_mul_f32_e32 v92, v92, v99
	v_mul_f32_e32 v92, v92, v84
	v_mul_f32_e32 v84, v93, v100
	v_mul_f32_e32 v93, 0xbfb8aa3b, v94
	v_exp_f32_e32 v93, v93
	v_mul_f32_e32 v98, 0xbfb8aa3b, v95
	v_exp_f32_e32 v98, v98
	v_mul_f32_e32 v99, v84, v85
	v_add_f32_e32 v84, 1.0, v93
	v_rcp_f32_e32 v84, v84
	v_add_f32_e32 v85, 1.0, v98
	v_mul_f32_e32 v93, 0xbfb8aa3b, v88
	v_rcp_f32_e32 v85, v85
	v_exp_f32_e32 v93, v93
	v_mul_f32_e32 v84, v94, v84
	v_mul_f32_e32 v86, v84, v86
	v_mul_f32_e32 v84, v95, v85
	v_add_f32_e32 v85, 1.0, v93
	v_rcp_f32_e32 v85, v85
	v_mul_f32_e32 v93, 0xbfb8aa3b, v89
	v_mul_f32_e32 v87, v84, v87
	v_exp_f32_e32 v93, v93
	v_mul_f32_e32 v84, v88, v85
	v_mul_f32_e32 v88, v84, v80
	v_mul_f32_e32 v84, 0xbfb8aa3b, v90
	v_exp_f32_e32 v84, v84
	v_mul_f32_e32 v85, 0xbfb8aa3b, v91
	v_exp_f32_e32 v85, v85
	v_add_f32_e32 v80, 1.0, v93
	v_rcp_f32_e32 v80, v80
	v_add_f32_e32 v84, 1.0, v84
	v_rcp_f32_e32 v84, v84
	v_add_f32_e32 v85, 1.0, v85
	v_rcp_f32_e32 v85, v85
	v_mul_f32_e32 v80, v89, v80
	v_mul_f32_e32 v89, v80, v81
	v_mul_f32_e32 v80, v90, v84
	v_mul_f32_e32 v90, v80, v82
	v_mul_f32_e32 v80, v91, v85
	v_mul_f32_e32 v83, v80, v83
	v_lshl_add_u64 v[84:85], v[96:97], 0, v[112:113]
	v_cvt_pk_bf16_f32 v80, v92, v99
	v_cvt_pk_bf16_f32 v81, v86, v87
	v_cvt_pk_bf16_f32 v82, v88, v89
	v_cvt_pk_bf16_f32 v83, v90, v83
	global_store_dwordx4 v[84:85], v[80:83], off
	s_nop 1
	v_mul_f32_e32 v80, 0xbfb8aa3b, v76
	v_exp_f32_e32 v80, v80
	v_mul_f32_e32 v81, 0xbfb8aa3b, v77
; __device__ __forceinline__ unsigned cvt_pk_bf16(float lo, float hi) { unsigned r; asm volatile("v_cvt_pk_bf16_f32 %0, %1, %2" : "=v"(r) : "v"(lo), "v"(hi)); return r; }
;     __device__ __forceinline__ void operator()(const f32x4 (&acc)[2][2][4][2], const Unit& u, int wr, int wc, int fr, int fq) const {
;     ...
;         for (int ai = 0; ai < 2; ++ai)
; #pragma unroll
;             for (int m = 0; m < 4; ++m) { bf16_t* rowp = H + (size_t)(row0 + ai * HALF + m * 16) * ldh + col0; float hv[8];
; #pragma unroll
;                 for (int n = 0; n < 2; ++n)
; #pragma unroll
;                     for (int e = 0; e < 4; ++e) { const float g = acc[ai][0][m][n][e], up = acc[ai][1][m][n][e]; hv[n * 4 + e] = g * __builtin_amdgcn_rcpf(1.0f + __expf(-g)) * up; }
;                 u32x4 w; w.x = cvt_pk_bf16(hv[0], hv[1]); w.y = cvt_pk_bf16(hv[2], hv[3]); w.z = cvt_pk_bf16(hv[4], hv[5]); w.w = cvt_pk_bf16(hv[6], hv[7]);
;                 *(u32x4*)rowp = w; }
	v_exp_f32_e32 v81, v81
	v_or_b32_e32 v82, 48, v165
	v_add_f32_e32 v80, 1.0, v80
	v_rcp_f32_e32 v83, v80
	v_add_f32_e32 v80, 1.0, v81
	v_rcp_f32_e32 v84, v80
	v_mad_i64_i32 v[80:81], s[6:7], v82, s81, v[144:145]
	v_mul_f32_e32 v76, v76, v83
	v_mul_f32_e32 v76, v76, v68
	v_mul_f32_e32 v68, v77, v84
	v_mul_f32_e32 v77, 0xbfb8aa3b, v78
	v_exp_f32_e32 v77, v77
	v_mul_f32_e32 v82, 0xbfb8aa3b, v79
	v_exp_f32_e32 v82, v82
	v_mul_f32_e32 v83, v68, v69
	v_add_f32_e32 v68, 1.0, v77
	v_rcp_f32_e32 v68, v68
	v_add_f32_e32 v69, 1.0, v82
	v_mul_f32_e32 v77, 0xbfb8aa3b, v72
	v_rcp_f32_e32 v69, v69
	v_exp_f32_e32 v77, v77
	v_mul_f32_e32 v68, v78, v68
	v_mul_f32_e32 v70, v68, v70
	v_mul_f32_e32 v68, v79, v69
	v_add_f32_e32 v69, 1.0, v77
	v_rcp_f32_e32 v69, v69
	v_mul_f32_e32 v77, 0xbfb8aa3b, v73
	v_mul_f32_e32 v71, v68, v71
	v_exp_f32_e32 v77, v77
	v_mul_f32_e32 v68, v72, v69
	v_mul_f32_e32 v72, v68, v64
	v_mul_f32_e32 v68, 0xbfb8aa3b, v74
	v_exp_f32_e32 v68, v68
	v_mul_f32_e32 v69, 0xbfb8aa3b, v75
	v_exp_f32_e32 v69, v69
	v_add_f32_e32 v64, 1.0, v77
	v_rcp_f32_e32 v64, v64
	v_add_f32_e32 v68, 1.0, v68
	v_rcp_f32_e32 v68, v68
	v_add_f32_e32 v69, 1.0, v69
	v_rcp_f32_e32 v69, v69
	v_mul_f32_e32 v64, v73, v64
	v_mul_f32_e32 v73, v64, v65
	v_mul_f32_e32 v64, v74, v68
	v_mul_f32_e32 v74, v64, v66
	v_mul_f32_e32 v64, v75, v69
	v_mul_f32_e32 v67, v64, v67
	v_lshl_add_u64 v[68:69], v[80:81], 0, v[112:113]
	v_cvt_pk_bf16_f32 v64, v76, v83
	v_cvt_pk_bf16_f32 v65, v70, v71
	v_cvt_pk_bf16_f32 v66, v72, v73
	v_cvt_pk_bf16_f32 v67, v74, v67
	global_store_dwordx4 v[68:69], v[64:67], off
	s_nop 1
	v_mul_f32_e32 v64, 0xbfb8aa3b, v60
	v_exp_f32_e32 v64, v64
	v_mul_f32_e32 v65, 0xbfb8aa3b, v61
	v_exp_f32_e32 v65, v65
	v_add_u32_e32 v66, 0x80, v165
	v_add_f32_e32 v64, 1.0, v64
	v_rcp_f32_e32 v67, v64
	v_add_f32_e32 v64, 1.0, v65
	v_rcp_f32_e32 v68, v64
	v_mad_i64_i32 v[64:65], s[6:7], v66, s81, v[144:145]
	v_mul_f32_e32 v60, v60, v67
	v_mul_f32_e32 v60, v60, v52
	v_mul_f32_e32 v52, v61, v68
	v_mul_f32_e32 v61, 0xbfb8aa3b, v62
	v_exp_f32_e32 v61, v61
	v_mul_f32_e32 v66, 0xbfb8aa3b, v63
	v_exp_f32_e32 v66, v66
	v_mul_f32_e32 v67, v52, v53
	v_add_f32_e32 v52, 1.0, v61
	v_rcp_f32_e32 v52, v52
	v_add_f32_e32 v53, 1.0, v66
	v_mul_f32_e32 v61, 0xbfb8aa3b, v56
	v_rcp_f32_e32 v53, v53
	v_exp_f32_e32 v61, v61
	v_mul_f32_e32 v52, v62, v52
	v_mul_f32_e32 v54, v52, v54
	v_mul_f32_e32 v52, v63, v53
	v_add_f32_e32 v53, 1.0, v61
	v_rcp_f32_e32 v53, v53
	v_mul_f32_e32 v61, 0xbfb8aa3b, v57
	v_mul_f32_e32 v55, v52, v55
	v_exp_f32_e32 v61, v61
	v_mul_f32_e32 v52, v56, v53
	v_mul_f32_e32 v56, v52, v48
	v_mul_f32_e32 v52, 0xbfb8aa3b, v58
	v_exp_f32_e32 v52, v52
	v_mul_f32_e32 v53, 0xbfb8aa3b, v59
	v_exp_f32_e32 v53, v53
	v_add_f32_e32 v48, 1.0, v61
	v_rcp_f32_e32 v48, v48
	v_add_f32_e32 v52, 1.0, v52
	v_rcp_f32_e32 v52, v52
	v_add_f32_e32 v53, 1.0, v53
	v_rcp_f32_e32 v53, v53
	v_mul_f32_e32 v48, v57, v48
	v_mul_f32_e32 v57, v48, v49
	v_mul_f32_e32 v48, v58, v52
	v_mul_f32_e32 v58, v48, v50
	v_mul_f32_e32 v48, v59, v53
	v_mul_f32_e32 v51, v48, v51
	v_lshl_add_u64 v[52:53], v[64:65], 0, v[112:113]
	v_cvt_pk_bf16_f32 v48, v60, v67
	v_cvt_pk_bf16_f32 v49, v54, v55
	v_cvt_pk_bf16_f32 v50, v56, v57
	v_cvt_pk_bf16_f32 v51, v58, v51
	global_store_dwordx4 v[52:53], v[48:51], off
	s_nop 1
	v_mul_f32_e32 v48, 0xbfb8aa3b, v44
	v_exp_f32_e32 v48, v48
	v_mul_f32_e32 v49, 0xbfb8aa3b, v45
	v_exp_f32_e32 v49, v49
	v_add_u32_e32 v50, 0x90, v165
	v_add_f32_e32 v48, 1.0, v48
	v_rcp_f32_e32 v51, v48
	v_add_f32_e32 v48, 1.0, v49
	v_rcp_f32_e32 v52, v48
	v_mad_i64_i32 v[48:49], s[6:7], v50, s81, v[144:145]
	v_mul_f32_e32 v44, v44, v51
	v_mul_f32_e32 v44, v44, v36
	v_mul_f32_e32 v36, v45, v52
	v_mul_f32_e32 v45, 0xbfb8aa3b, v46
	v_exp_f32_e32 v45, v45
	v_mul_f32_e32 v50, 0xbfb8aa3b, v47
	v_exp_f32_e32 v50, v50
	v_mul_f32_e32 v51, v36, v37
	v_add_f32_e32 v36, 1.0, v45
	v_rcp_f32_e32 v36, v36
	v_add_f32_e32 v37, 1.0, v50
	v_mul_f32_e32 v45, 0xbfb8aa3b, v40
	v_rcp_f32_e32 v37, v37
	v_exp_f32_e32 v45, v45
	v_mul_f32_e32 v36, v46, v36
	v_mul_f32_e32 v38, v36, v38
	v_mul_f32_e32 v36, v47, v37
	v_add_f32_e32 v37, 1.0, v45
	v_rcp_f32_e32 v37, v37
	v_mul_f32_e32 v45, 0xbfb8aa3b, v41
	v_mul_f32_e32 v39, v36, v39
; __device__ __forceinline__ unsigned cvt_pk_bf16(float lo, float hi) { unsigned r; asm volatile("v_cvt_pk_bf16_f32 %0, %1, %2" : "=v"(r) : "v"(lo), "v"(hi)); return r; }
; #define PG8_BAR __builtin_amdgcn_s_barrier()
;     __device__ __forceinline__ void operator()(const f32x4 (&acc)[2][2][4][2], const Unit& u, int wr, int wc, int fr, int fq) const {
;     ...
;         for (int ai = 0; ai < 2; ++ai)
; #pragma unroll
;             for (int m = 0; m < 4; ++m) { bf16_t* rowp = H + (size_t)(row0 + ai * HALF + m * 16) * ldh + col0; float hv[8];
; #pragma unroll
;                 for (int n = 0; n < 2; ++n)
; #pragma unroll
;                     for (int e = 0; e < 4; ++e) { const float g = acc[ai][0][m][n][e], up = acc[ai][1][m][n][e]; hv[n * 4 + e] = g * __builtin_amdgcn_rcpf(1.0f + __expf(-g)) * up; }
;                 u32x4 w; w.x = cvt_pk_bf16(hv[0], hv[1]); w.y = cvt_pk_bf16(hv[2], hv[3]); w.z = cvt_pk_bf16(hv[4], hv[5]); w.w = cvt_pk_bf16(hv[6], hv[7]);
;                 *(u32x4*)rowp = w; }
; template <class Epi, class Sched, bool ALIGN_EPI = false, bool SP2 = false>
; __device__ __forceinline__ void gemm_phase(PG8_LAS unsigned char* lds, const Gemm g, const Sched& S, const Epi& E) {
;     ...
;         if constexpr (ALIGN_EPI) { if (wr == 0) PG8_BAR; }
;         if constexpr (!Epi::AFTER_DRAIN) { E(acc, cur, wr, wc, fr, fq); S.done(cur); }
;         if (!has_next) break;
; #pragma unroll
;         for (int a = 0; a < 2; ++a)
; #pragma unroll
;             for (int b = 0; b < 2; ++b)
; #pragma unroll
;                 for (int m = 0; m < 4; ++m)
; #pragma unroll
;                     for (int n = 0; n < 2; ++n) acc[a][b][m][n] = (f32x4){0.f, 0.f, 0.f, 0.f};
;         cur = nxt; cA = nA; cB = nB; ++ui;
;         if constexpr (ALIGN_EPI) { if (wr == 1) PG8_BAR; }
	v_exp_f32_e32 v45, v45
	v_mul_f32_e32 v36, v40, v37
	v_mul_f32_e32 v40, v36, v32
	v_mul_f32_e32 v36, 0xbfb8aa3b, v42
	v_exp_f32_e32 v36, v36
	v_mul_f32_e32 v37, 0xbfb8aa3b, v43
	v_exp_f32_e32 v37, v37
	v_add_f32_e32 v32, 1.0, v45
	v_rcp_f32_e32 v32, v32
	v_add_f32_e32 v36, 1.0, v36
	v_rcp_f32_e32 v36, v36
	v_add_f32_e32 v37, 1.0, v37
	v_rcp_f32_e32 v37, v37
	v_mul_f32_e32 v32, v41, v32
	v_mul_f32_e32 v41, v32, v33
	v_mul_f32_e32 v32, v42, v36
	v_mul_f32_e32 v42, v32, v34
	v_mul_f32_e32 v32, v43, v37
	v_mul_f32_e32 v35, v32, v35
	v_lshl_add_u64 v[36:37], v[48:49], 0, v[112:113]
	v_cvt_pk_bf16_f32 v32, v44, v51
	v_cvt_pk_bf16_f32 v33, v38, v39
	v_cvt_pk_bf16_f32 v34, v40, v41
	v_cvt_pk_bf16_f32 v35, v42, v35
	global_store_dwordx4 v[36:37], v[32:35], off
	s_nop 1
	v_mul_f32_e32 v32, 0xbfb8aa3b, v28
	v_exp_f32_e32 v32, v32
	v_mul_f32_e32 v33, 0xbfb8aa3b, v29
	v_exp_f32_e32 v33, v33
	v_add_u32_e32 v34, 0xa0, v165
	v_add_f32_e32 v32, 1.0, v32
	v_rcp_f32_e32 v35, v32
	v_add_f32_e32 v32, 1.0, v33
	v_rcp_f32_e32 v36, v32
	v_mad_i64_i32 v[32:33], s[6:7], v34, s81, v[144:145]
	v_mul_f32_e32 v28, v28, v35
	v_mul_f32_e32 v28, v28, v20
	v_mul_f32_e32 v20, v29, v36
	v_mul_f32_e32 v29, 0xbfb8aa3b, v30
	v_exp_f32_e32 v29, v29
	v_mul_f32_e32 v34, 0xbfb8aa3b, v31
	v_exp_f32_e32 v34, v34
	v_mul_f32_e32 v35, v20, v21
	v_add_f32_e32 v20, 1.0, v29
	v_rcp_f32_e32 v20, v20
	v_add_f32_e32 v21, 1.0, v34
	v_mul_f32_e32 v29, 0xbfb8aa3b, v24
	v_rcp_f32_e32 v21, v21
	v_exp_f32_e32 v29, v29
	v_mul_f32_e32 v20, v30, v20
	v_mul_f32_e32 v22, v20, v22
	v_mul_f32_e32 v20, v31, v21
	v_add_f32_e32 v21, 1.0, v29
	v_rcp_f32_e32 v21, v21
	v_mul_f32_e32 v29, 0xbfb8aa3b, v25
	v_mul_f32_e32 v23, v20, v23
	v_exp_f32_e32 v29, v29
	v_mul_f32_e32 v20, v24, v21
	v_mul_f32_e32 v24, v20, v16
	v_mul_f32_e32 v20, 0xbfb8aa3b, v26
	v_exp_f32_e32 v20, v20
	v_mul_f32_e32 v21, 0xbfb8aa3b, v27
	v_exp_f32_e32 v21, v21
	v_add_f32_e32 v16, 1.0, v29
	v_rcp_f32_e32 v16, v16
	v_add_f32_e32 v20, 1.0, v20
	v_rcp_f32_e32 v20, v20
	v_add_f32_e32 v21, 1.0, v21
	v_rcp_f32_e32 v21, v21
	v_mul_f32_e32 v16, v25, v16
	v_mul_f32_e32 v25, v16, v17
	v_mul_f32_e32 v16, v26, v20
	v_mul_f32_e32 v26, v16, v18
	v_mul_f32_e32 v16, v27, v21
	v_mul_f32_e32 v19, v16, v19
	v_lshl_add_u64 v[20:21], v[32:33], 0, v[112:113]
	v_cvt_pk_bf16_f32 v16, v28, v35
	v_cvt_pk_bf16_f32 v17, v22, v23
	v_cvt_pk_bf16_f32 v18, v24, v25
	v_cvt_pk_bf16_f32 v19, v26, v19
	global_store_dwordx4 v[20:21], v[16:19], off
	s_nop 1
	v_mul_f32_e32 v16, 0xbfb8aa3b, v12
	v_exp_f32_e32 v16, v16
	v_mul_f32_e32 v17, 0xbfb8aa3b, v13
	v_exp_f32_e32 v17, v17
	v_add_u32_e32 v18, 0xb0, v165
	v_add_f32_e32 v16, 1.0, v16
	v_rcp_f32_e32 v19, v16
	v_add_f32_e32 v16, 1.0, v17
	v_rcp_f32_e32 v20, v16
	v_mad_i64_i32 v[16:17], s[6:7], v18, s81, v[144:145]
	v_mul_f32_e32 v12, v12, v19
	v_mul_f32_e32 v12, v12, v4
	v_mul_f32_e32 v4, v13, v20
	v_mul_f32_e32 v13, 0xbfb8aa3b, v14
	v_exp_f32_e32 v13, v13
	v_mul_f32_e32 v18, 0xbfb8aa3b, v15
	v_exp_f32_e32 v18, v18
	v_mul_f32_e32 v19, v4, v5
	v_add_f32_e32 v4, 1.0, v13
	v_rcp_f32_e32 v4, v4
	v_add_f32_e32 v5, 1.0, v18
	v_mul_f32_e32 v13, 0xbfb8aa3b, v8
	v_rcp_f32_e32 v5, v5
	v_exp_f32_e32 v13, v13
	v_mul_f32_e32 v4, v14, v4
	v_mul_f32_e32 v6, v4, v6
	v_mul_f32_e32 v4, v15, v5
	v_add_f32_e32 v5, 1.0, v13
	v_rcp_f32_e32 v5, v5
	v_mul_f32_e32 v13, 0xbfb8aa3b, v9
	v_mul_f32_e32 v7, v4, v7
	v_exp_f32_e32 v13, v13
	v_mul_f32_e32 v4, v8, v5
	v_mul_f32_e32 v8, v4, v0
	v_mul_f32_e32 v4, 0xbfb8aa3b, v10
	v_exp_f32_e32 v4, v4
	v_mul_f32_e32 v5, 0xbfb8aa3b, v11
	v_exp_f32_e32 v5, v5
	v_add_f32_e32 v0, 1.0, v13
	v_rcp_f32_e32 v0, v0
	v_add_f32_e32 v4, 1.0, v4
	v_rcp_f32_e32 v4, v4
	v_add_f32_e32 v5, 1.0, v5
	v_rcp_f32_e32 v5, v5
	v_mul_f32_e32 v0, v9, v0
	v_mul_f32_e32 v9, v0, v1
	v_mul_f32_e32 v0, v10, v4
	v_mul_f32_e32 v10, v0, v2
	v_mul_f32_e32 v0, v11, v5
	v_mul_f32_e32 v3, v0, v3
	v_lshl_add_u64 v[4:5], v[16:17], 0, v[112:113]
	v_cvt_pk_bf16_f32 v0, v12, v19
	v_cvt_pk_bf16_f32 v1, v6, v7
	v_cvt_pk_bf16_f32 v2, v8, v9
	v_cvt_pk_bf16_f32 v3, v10, v3
	global_store_dwordx4 v[4:5], v[0:3], off
	s_cbranch_vccnz .LBB0_789
	s_andn2_b64 vcc, exec, s[8:9]
	s_cbranch_vccnz .LBB0_788
	s_barrier
	s_branch .LBB0_788

; __device__ __forceinline__ const float* row_src(int row, const float* lat, long lat_bs, const float* cx, long ctx_bs, int& s) {
;     const int b = row / TPB, t = row - b * TPB;
;     if (t < CTXL) { s = 4; return cx + (size_t)b * ctx_bs + (size_t)t * DMODEL; }
;     s = b; return lat + (size_t)b * lat_bs + (size_t)(t - CTXL) * DMODEL;
; }
; __device__ __forceinline__ void norm_mod_phase(const float* lat, long lat_bs, const float* cx, long ctx_bs, const float* modl, int shoff, int scoff, bf16* XN, int skip_ctx, int gw, int NGW, float* xcopy, const float* part, int nkc, const float* pgate) {
;     int t_ = threadIdx.x; asm volatile("" : "+v"(t_)); const int lane = t_ & 63;
;     f32x4 vn[4]; int sn = 0;
;     { if (gw < MROWS) { const float* src = row_src(gw, lat, lat_bs, cx, ctx_bs, sn); const f32x4* xr = (const f32x4*)src + lane;
; #pragma unroll
;         for (int j = 0; j < 4; ++j) vn[j] = xr[64 * j]; } }
;     for (int row = gw; row < MROWS; row += NGW) {
;         const int s = sn; f32x4 v[4]; float ss = 0.f;
; #pragma unroll
;         for (int j = 0; j < 4; ++j) v[j] = vn[j];
;         if (row + NGW < MROWS) { const float* srcn = row_src(row + NGW, lat, lat_bs, cx, ctx_bs, sn); const f32x4* xr = (const f32x4*)srcn + lane;
; #pragma unroll
;             for (int j = 0; j < 4; ++j) vn[j] = xr[64 * j]; }
.LBB0_958:
	s_or_b64 exec, exec, s[6:7]
	v_readlane_b32 s4, v254, 6
	s_add_u32 s86, s30, 0x2f9e000
	v_readlane_b32 s5, v254, 7
	s_addc_u32 s38, s31, 0
	s_waitcnt lgkmcnt(0)
	v_mov_b32_e32 v0, v222
	s_and_b64 vcc, exec, s[4:5]
	s_barrier
	s_cbranch_vccnz .LBB0_967
	v_readlane_b32 s3, v254, 5
	s_lshr_b32 s1, s3, 31
	s_ashr_i32 s3, s3, 11
	s_add_i32 s1, s3, s1
	s_mul_i32 s3, s1, 0xffffdf00
	v_readlane_b32 s36, v254, 8
	s_add_i32 s3, s3, s36
	s_cmpk_lt_i32 s3, 0x100
	s_cselect_b64 s[4:5], -1, 0
	s_add_i32 s12, s3, 0xffffff00
	s_ashr_i32 s13, s3, 31
	s_and_b64 s[6:7], s[4:5], exec
	s_mul_i32 s9, s1, 0x2100000
	s_cselect_b32 s6, s3, s12
	s_cselect_b32 s12, s48, s90
	s_mul_hi_i32 s8, s1, 0x2100000
	s_cselect_b32 s7, s13, 0
	s_cselect_b32 s3, s49, s0
	s_add_u32 s9, s12, s9
	s_addc_u32 s3, s3, s8
	s_and_b64 s[4:5], s[4:5], exec
	s_cselect_b32 s57, 4, s1
	s_lshl_b64 s[4:5], s[6:7], 12
	v_and_b32_e32 v12, 63, v0
	s_add_u32 s4, s9, s4
	s_addc_u32 s5, s3, s5
	v_lshlrev_b32_e32 v40, 4, v12
	global_load_dwordx4 v[0:3], v40, s[4:5] offset:3072
	global_load_dwordx4 v[4:7], v40, s[4:5] offset:2048
	global_load_dwordx4 v[8:11], v40, s[4:5] offset:1024
	global_load_dwordx4 v[28:31], v40, s[4:5]
	v_mov_b32_e32 v41, 0
	v_lshl_add_u64 v[14:15], s[30:31], 0, v[40:41]
	s_mov_b64 s[4:5], 0x2f9d000
	v_lshl_add_u64 v[42:43], v[14:15], 0, s[4:5]
	v_lshlrev_b32_e32 v14, 3, v12
	v_mov_b32_e32 v15, v41
	v_mbcnt_hi_u32_b32 v13, -1, v223
	v_lshl_add_u64 v[46:47], s[46:47], 0, v[14:15]
	v_and_b32_e32 v14, 64, v13
	v_add_u32_e32 v14, 64, v14
	v_xor_b32_e32 v15, 1, v13
	v_cmp_lt_i32_e32 vcc, v15, v14
	v_readlane_b32 s37, v254, 9
	s_ashr_i32 s37, s36, 31
	v_cndmask_b32_e32 v15, v13, v15, vcc
	v_lshlrev_b32_e32 v52, 2, v15
	v_xor_b32_e32 v15, 2, v13
	v_cmp_lt_i32_e32 vcc, v15, v14
	s_ashr_i32 s43, s42, 31
	s_lshl_b64 s[4:5], s[36:37], 12
	v_cndmask_b32_e32 v15, v13, v15, vcc
	v_lshlrev_b32_e32 v53, 2, v15
	v_xor_b32_e32 v15, 4, v13
	v_cmp_lt_i32_e32 vcc, v15, v14
	s_add_u32 s4, s30, s4
	s_addc_u32 s5, s31, s5
	v_cndmask_b32_e32 v15, v13, v15, vcc
	v_lshlrev_b32_e32 v54, 2, v15
	v_xor_b32_e32 v15, 8, v13
	v_cmp_lt_i32_e32 vcc, v15, v14
	v_lshl_add_u64 v[44:45], s[10:11], 0, v[40:41]
	s_mov_b32 s6, s36
	v_cndmask_b32_e32 v15, v13, v15, vcc
	v_lshlrev_b32_e32 v55, 2, v15
	v_xor_b32_e32 v15, 16, v13
	v_cmp_lt_i32_e32 vcc, v15, v14
	s_lshl_b64 s[8:9], s[42:43], 12
	s_mov_b32 s1, 0x400000
	v_cndmask_b32_e32 v15, v13, v15, vcc
	v_lshlrev_b32_e32 v56, 2, v15
	v_xor_b32_e32 v15, 32, v13
	v_cmp_lt_i32_e32 vcc, v15, v14
	s_mov_b32 s3, 0x800000
	s_mov_b32 s12, 0x1400000
	v_cndmask_b32_e32 v13, v13, v15, vcc
	v_lshl_add_u64 v[14:15], s[4:5], 0, v[40:41]
	s_mov_b64 s[4:5], 0x2fc0000
	v_lshlrev_b32_e32 v57, 2, v13
	v_lshl_add_u64 v[48:49], v[14:15], 0, s[4:5]
	v_lshlrev_b32_e32 v40, 4, v12
	s_mov_b32 s4, 0xc00000
	s_mov_b32 s5, 0x1000000
	s_mov_b32 s13, 0x1800000
	s_mov_b32 s14, 0x1c00000
	s_brev_b32 s15, 64
	s_mov_b32 s33, 0x2400000
	s_mov_b32 s52, 0x2800000
	v_mov_b32_e32 v58, 0x358637bd
	s_mov_b32 s53, 0xf800000
	v_mov_b32_e32 v59, 0x260
	s_mov_b64 s[10:11], 0x1000
	s_movk_i32 s54, 0x1000
	s_movk_i32 s55, 0x7fff
	s_mov_b32 s56, 0xffff0000
	v_writelane_b32 v254, s6, 8
	s_mov_b32 s39, s57
	s_waitcnt vmcnt(3)
	v_mov_b32_e32 v14, v2
	v_mov_b32_e32 v15, v3
	s_waitcnt vmcnt(2)
	v_mov_b32_e32 v18, v6
	v_mov_b32_e32 v19, v7
	s_waitcnt vmcnt(1)
	v_mov_b32_e32 v22, v10
	v_mov_b32_e32 v23, v11
	s_waitcnt vmcnt(0)
	v_mov_b32_e32 v24, v28
	v_mov_b32_e32 v25, v29
	v_mov_b32_e32 v12, v0
	v_mov_b32_e32 v13, v1
	v_mov_b32_e32 v16, v4
	v_mov_b32_e32 v17, v5
	v_mov_b32_e32 v20, v8
	v_mov_b32_e32 v21, v9
	v_mov_b32_e32 v26, v30
	v_mov_b32_e32 v27, v31
	v_writelane_b32 v254, s7, 9
	s_branch .LBB0_961
; __device__ __forceinline__ unsigned pk2(float lo, float hi) { return f2bf(lo) | (f2bf(hi) << 16); }
; __device__ __forceinline__ void norm_mod_phase(const float* lat, long lat_bs, const float* cx, long ctx_bs, const float* modl, int shoff, int scoff, bf16* XN, int skip_ctx, int gw, int NGW, float* xcopy, const float* part, int nkc, const float* pgate) {
;     ...
;     for (int row = gw; row < MROWS; row += NGW) {
;         const int s = sn; f32x4 v[4]; float ss = 0.f;
; #pragma unroll
;         for (int j = 0; j < 4; ++j) v[j] = vn[j];
;         if (row + NGW < MROWS) { const float* srcn = row_src(row + NGW, lat, lat_bs, cx, ctx_bs, sn); const f32x4* xr = (const f32x4*)srcn + lane;
; #pragma unroll
;             for (int j = 0; j < 4; ++j) vn[j] = xr[64 * j]; }
;         if (skip_ctx && s == 4) continue;
; #pragma unroll
;         for (int j = 0; j < 4; ++j) ss += (v[j].x * v[j].x + v[j].y * v[j].y) + (v[j].z * v[j].z + v[j].w * v[j].w);
;         if (xcopy && s == 4) {
;             const int b_ = row / TPB, cr = b_ * CTXL + (row - b_ * TPB); const f32x4* gp = (const f32x4*)(pgate + 4 * NMOD6) + lane;
;             f32x4 sm[4];
; #pragma unroll
;             for (int j = 0; j < 4; ++j) sm[j] = (f32x4){0.f, 0.f, 0.f, 0.f};
;             for (int kc = 0; kc < nkc; ++kc) { const f32x4* pp = (const f32x4*)(part + ((size_t)kc * 1024 + cr) * DMODEL) + lane;
; #pragma unroll
;                 for (int j = 0; j < 4; ++j) sm[j] += pp[64 * j]; }
;             f32x4* xc = (f32x4*)(xcopy + (size_t)row * DMODEL) + lane; ss = 0.f;
; #pragma unroll
;             for (int j = 0; j < 4; ++j) { v[j] += gp[64 * j] * sm[j]; xc[64 * j] = v[j]; ss += (v[j].x * v[j].x + v[j].y * v[j].y) + (v[j].z * v[j].z + v[j].w * v[j].w); } }
;         const float rstd = 1.0f / sqrtf(wave_sum(ss) * (1.0f / DMODEL) + EPS);
;         const f32x4* sh = (const f32x4*)(modl + s * NMOD6 + shoff) + lane; const f32x4* sc = (const f32x4*)(modl + s * NMOD6 + scoff) + lane;
;         v2u* o8 = (v2u*)(XN + (size_t)row * DMODEL) + lane;
; #pragma unroll
;         for (int j = 0; j < 4; ++j) { const f32x4 a = sh[64 * j], m = sc[64 * j]; const f32x4 y = v[j] * rstd * (m + 1.0f) + a; v2u w; w.x = pk2(y.x, y.y); w.y = pk2(y.z, y.w); o8[64 * j] = w; }
.LBB0_960:
	s_add_u32 s36, s36, s42
	s_mul_i32 s40, s57, 0x1800
	s_addc_u32 s37, s37, s43
	s_ashr_i32 s41, s40, 31
	s_lshl_b64 s[40:41], s[40:41], 2
	s_add_u32 s40, s86, s40
	s_addc_u32 s41, s38, s41
	v_lshl_add_u64 v[38:39], s[40:41], 0, v[40:41]
	v_add_co_u32_e32 v34, vcc, s54, v38
	ds_bpermute_b32 v33, v52, v32
	s_nop 0
	v_addc_co_u32_e32 v35, vcc, 0, v39, vcc
	global_load_dwordx4 v[34:37], v[34:35], off
	s_nop 0
	global_load_dwordx4 v[60:63], v40, s[40:41]
	s_lshl_b64 s[6:7], s[6:7], 11
	s_waitcnt lgkmcnt(0)
	v_add_f32_e32 v32, v32, v33
	ds_bpermute_b32 v33, v53, v32
	v_lshl_add_u64 v[50:51], v[46:47], 0, s[6:7]
	v_lshl_add_u64 v[38:39], v[38:39], 0, s[10:11]
	v_lshl_add_u64 v[48:49], v[48:49], 0, s[8:9]
	s_cmp_lt_i32 s36, 0x8400
	s_waitcnt lgkmcnt(0)
	v_add_f32_e32 v32, v32, v33
	ds_bpermute_b32 v33, v54, v32
	s_mov_b32 s57, s39
	s_waitcnt lgkmcnt(0)
	v_add_f32_e32 v32, v32, v33
	ds_bpermute_b32 v33, v55, v32
	s_waitcnt lgkmcnt(0)
	v_add_f32_e32 v32, v32, v33
	ds_bpermute_b32 v33, v56, v32
	s_waitcnt lgkmcnt(0)
	v_add_f32_e32 v32, v32, v33
	ds_bpermute_b32 v33, v57, v32
	s_waitcnt lgkmcnt(0)
	v_add_f32_e32 v32, v32, v33
	v_fmamk_f32 v32, v32, 0x3a800000, v58
	v_mul_f32_e32 v33, 0x4f800000, v32
	v_cmp_gt_f32_e32 vcc, s53, v32
	s_waitcnt vmcnt(1)
	v_add_f32_e32 v34, 1.0, v34
	v_add_f32_e32 v35, 1.0, v35
	v_cndmask_b32_e32 v32, v32, v33, vcc
	v_sqrt_f32_e32 v33, v32
	s_nop 0
	v_add_u32_e32 v64, -1, v33
	v_add_u32_e32 v65, 1, v33
	v_fma_f32 v66, -v64, v33, v32
	v_fma_f32 v67, -v65, v33, v32
	v_cmp_ge_f32_e64 s[6:7], 0, v66
	s_nop 1
	v_cndmask_b32_e64 v33, v33, v64, s[6:7]
	v_cmp_lt_f32_e64 s[6:7], 0, v67
	s_nop 1
	v_cndmask_b32_e64 v33, v33, v65, s[6:7]
	v_mul_f32_e32 v64, 0x37800000, v33
	v_cndmask_b32_e32 v33, v33, v64, vcc
	v_cmp_class_f32_e32 vcc, v32, v59
	s_nop 1
	v_cndmask_b32_e32 v32, v33, v32, vcc
	v_div_scale_f32 v33, s[6:7], v32, v32, 1.0
	v_rcp_f32_e32 v64, v33
	v_div_scale_f32 v65, vcc, 1.0, v32, 1.0
	v_fma_f32 v66, -v33, v64, 1.0
	v_fmac_f32_e32 v64, v66, v64
	v_mul_f32_e32 v66, v65, v64
	v_fma_f32 v67, -v33, v66, v65
	v_fmac_f32_e32 v66, v67, v64
	v_fma_f32 v33, -v33, v66, v65
	v_div_fmas_f32 v33, v33, v64, v66
	v_div_fixup_f32 v64, v33, v32, 1.0
	v_mul_f32_e32 v28, v28, v64
	v_mul_f32_e32 v29, v29, v64
	v_mul_f32_e32 v30, v30, v64
	v_mul_f32_e32 v31, v31, v64
	v_add_f32_e32 v32, 1.0, v36
	v_add_f32_e32 v33, 1.0, v37
	s_waitcnt vmcnt(0)
	v_fma_f32 v28, v34, v28, v60
	v_fma_f32 v29, v35, v29, v61
	v_fma_f32 v30, v32, v30, v62
	v_fma_f32 v31, v33, v31, v63
	v_bfe_u32 v32, v28, 16, 1
	v_bfe_u32 v34, v30, 16, 1
	v_bfe_u32 v33, v29, 16, 1
	v_bfe_u32 v35, v31, 16, 1
	v_add3_u32 v28, v28, v32, s55
	v_add3_u32 v30, v30, v34, s55
	v_add3_u32 v29, v29, v33, s55
	v_add3_u32 v31, v31, v35, s55
	v_lshrrev_b32_e32 v28, 16, v28
	v_lshrrev_b32_e32 v30, 16, v30
	v_and_or_b32 v28, v29, s56, v28
	v_and_or_b32 v29, v31, s56, v30
	global_store_dwordx2 v[50:51], v[28:29], off
	global_load_dwordx4 v[28:31], v[38:39], off offset:1024
	s_nop 0
	global_load_dwordx4 v[32:35], v40, s[40:41] offset:1024
	global_load_dwordx4 v[100:103], v[38:39], off offset:2048
	global_load_dwordx4 v[104:107], v40, s[40:41] offset:2048
	global_load_dwordx4 v[108:111], v[38:39], off offset:3072
	global_load_dwordx4 v[112:115], v40, s[40:41] offset:3072
	v_mul_f32_e32 v8, v8, v64
	v_mul_f32_e32 v9, v9, v64
	v_mul_f32_e32 v10, v10, v64
	v_mul_f32_e32 v11, v11, v64
	v_mul_f32_e32 v4, v4, v64
	v_mul_f32_e32 v5, v5, v64
	v_mul_f32_e32 v6, v6, v64
	v_mul_f32_e32 v7, v7, v64
	v_mul_f32_e32 v60, v0, v64
	v_mul_f32_e32 v61, v1, v64
	v_mul_f32_e32 v62, v2, v64
	v_mul_f32_e32 v63, v3, v64
	v_mov_b32_e32 v0, v12
	v_mov_b32_e32 v1, v13
	v_mov_b32_e32 v2, v14
	v_mov_b32_e32 v3, v15
	s_waitcnt vmcnt(5)
	v_add_f32_e32 v30, 1.0, v30
	v_add_f32_e32 v31, 1.0, v31
	v_add_f32_e32 v28, 1.0, v28
	v_add_f32_e32 v29, 1.0, v29
	s_waitcnt vmcnt(4)
	v_fma_f32 v10, v30, v10, v34
	v_fma_f32 v11, v31, v11, v35
	v_fma_f32 v8, v28, v8, v32
	v_fma_f32 v9, v29, v9, v33
	v_bfe_u32 v30, v10, 16, 1
	v_bfe_u32 v28, v8, 16, 1
	v_bfe_u32 v29, v9, 16, 1
	v_bfe_u32 v31, v11, 16, 1
	v_add3_u32 v8, v8, v28, s55
	v_add3_u32 v10, v10, v30, s55
	v_add3_u32 v9, v9, v29, s55
	v_add3_u32 v11, v11, v31, s55
	v_lshrrev_b32_e32 v8, 16, v8
	v_lshrrev_b32_e32 v10, 16, v10
	v_and_or_b32 v8, v9, s56, v8
	v_and_or_b32 v9, v11, s56, v10
	global_store_dwordx2 v[50:51], v[8:9], off offset:512
	s_nop 0
	s_waitcnt vmcnt(4)
	v_add_f32_e32 v10, 1.0, v102
	v_add_f32_e32 v11, 1.0, v103
	v_add_f32_e32 v8, 1.0, v100
	v_add_f32_e32 v9, 1.0, v101
	s_waitcnt vmcnt(3)
	v_fma_f32 v6, v6, v10, v106
	v_fma_f32 v7, v7, v11, v107
	v_fma_f32 v4, v4, v8, v104
	v_fma_f32 v5, v5, v9, v105
	v_bfe_u32 v10, v6, 16, 1
	v_bfe_u32 v8, v4, 16, 1
	v_bfe_u32 v9, v5, 16, 1
	v_bfe_u32 v11, v7, 16, 1
	v_add3_u32 v4, v4, v8, s55
	v_add3_u32 v6, v6, v10, s55
	v_add3_u32 v5, v5, v9, s55
	v_add3_u32 v7, v7, v11, s55
	v_lshrrev_b32_e32 v4, 16, v4
	v_lshrrev_b32_e32 v6, 16, v6
	v_and_or_b32 v4, v5, s56, v4
	v_and_or_b32 v5, v7, s56, v6
	global_store_dwordx2 v[50:51], v[4:5], off offset:1024
	s_nop 0
	v_mov_b32_e32 v4, v16
	v_mov_b32_e32 v5, v17
	v_mov_b32_e32 v8, v20
	v_mov_b32_e32 v9, v21
	v_mov_b32_e32 v30, v26
	v_mov_b32_e32 v31, v27
	v_mov_b32_e32 v6, v18
	v_mov_b32_e32 v7, v19
	v_mov_b32_e32 v10, v22
	v_mov_b32_e32 v11, v23
	v_mov_b32_e32 v28, v24
	v_mov_b32_e32 v29, v25
	s_waitcnt vmcnt(3)
	v_add_f32_e32 v34, 1.0, v110
	v_add_f32_e32 v35, 1.0, v111
	v_add_f32_e32 v32, 1.0, v108
	v_add_f32_e32 v33, 1.0, v109
	s_waitcnt vmcnt(2)
	v_fma_f32 v34, v62, v34, v114
	v_fma_f32 v35, v63, v35, v115
	v_fma_f32 v32, v60, v32, v112
	v_fma_f32 v33, v61, v33, v113
	v_bfe_u32 v38, v34, 16, 1
	v_bfe_u32 v36, v32, 16, 1
	v_bfe_u32 v37, v33, 16, 1
	v_bfe_u32 v39, v35, 16, 1
	v_add3_u32 v32, v32, v36, s55
	v_add3_u32 v34, v34, v38, s55
	v_add3_u32 v33, v33, v37, s55
	v_add3_u32 v35, v35, v39, s55
	v_lshrrev_b32_e32 v32, 16, v32
	v_lshrrev_b32_e32 v34, 16, v34
	v_and_or_b32 v32, v33, s56, v32
	v_and_or_b32 v33, v35, s56, v34
	global_store_dwordx2 v[50:51], v[32:33], off offset:1536
	s_cbranch_scc0 .LBB0_967

; __device__ __forceinline__ unsigned xb_ld(unsigned* p)              { return __hip_atomic_load(p, __ATOMIC_RELAXED, __HIP_MEMORY_SCOPE_AGENT); }
; __device__ __forceinline__ unsigned xb_add(unsigned* p, unsigned v) { return __hip_atomic_fetch_add(p, v, __ATOMIC_RELAXED, __HIP_MEMORY_SCOPE_AGENT); }
; #define XB_SPIN(cond, bar) do { unsigned _sp = 0; while (cond) { __builtin_amdgcn_s_sleep(1); \
;     if ((++_sp & 255u) == 0u) { if (xb_ld(&(bar)[XB_TMO])) break; if (_sp > XB_SPIN_CAP) { atomicAdd(&(bar)[XB_TMO], 1u); break; } } } } while (0)
; __device__ __forceinline__ void xcd_barrier(const XcdBarrier& b) {
;     ...
;             const unsigned og = xb_add(&bar[XB_TOP], 1u);
;             const unsigned tg = og / nx;
;             if (og + 1u == (tg + 1u) * nx) xb_add(&bar[XB_TOPGEN], 1u);
;             else XB_SPIN(xb_ld(&bar[XB_TOPGEN]) == tg, bar);
.LBB0_1002:
	s_or_b64 exec, exec, s[36:37]
	v_cvt_f32_u32_e32 v3, v0
	s_waitcnt vmcnt(0)
	v_readfirstlane_b32 s1, v2
	s_add_u32 s36, s30, 0x1bbc3500
	s_addc_u32 s37, s31, 0
	v_rcp_iflag_f32_e32 v3, v3
	v_add_u32_e32 v1, s1, v1
	v_add_u32_e32 v4, 1, v1
	s_mov_b64 s[40:41], -1
	v_mul_f32_e32 v2, 0x4f7ffffe, v3
	v_cvt_u32_f32_e32 v2, v2
	v_sub_u32_e32 v3, 0, v0
	v_mul_lo_u32 v3, v3, v2
	v_mul_hi_u32 v3, v2, v3
	v_add_u32_e32 v2, v2, v3
	v_mul_hi_u32 v2, v1, v2
	v_mul_lo_u32 v3, v2, v0
	v_sub_u32_e32 v1, v1, v3
	v_add_u32_e32 v5, 1, v2
	v_cmp_ge_u32_e32 vcc, v1, v0
	v_sub_u32_e32 v3, v1, v0
	s_nop 0
	v_cndmask_b32_e32 v2, v2, v5, vcc
	v_cndmask_b32_e32 v1, v1, v3, vcc
	v_add_u32_e32 v3, 1, v2
	v_cmp_ge_u32_e32 vcc, v1, v0
	s_nop 1
	v_cndmask_b32_e32 v2, v2, v3, vcc
	v_mul_lo_u32 v1, v0, v2
	v_add_u32_e32 v0, v1, v0
	v_cmp_ne_u32_e32 vcc, v4, v0
	v_mov_b32_e32 v0, s36
	v_mov_b32_e32 v1, s37
	s_and_saveexec_b64 s[10:11], vcc
	s_cbranch_execz .LBB0_1014
	v_mov_b32_e32 v0, 0
	global_load_dword v1, v0, s[36:37] sc1
	s_mov_b64 s[54:55], 0
	s_waitcnt vmcnt(0)
	v_cmp_eq_u32_e32 vcc, v1, v2
	s_and_saveexec_b64 s[52:53], vcc
	s_cbranch_execz .LBB0_1013
	s_add_u32 s40, s30, 0x1bbc0200
	s_addc_u32 s41, s31, 0
	s_mov_b32 s1, 1
	s_branch .LBB0_1006

; __device__ __forceinline__ unsigned xb_ld(unsigned* p)              { return __hip_atomic_load(p, __ATOMIC_RELAXED, __HIP_MEMORY_SCOPE_AGENT); }
; #define XB_SPIN(cond, bar) do { unsigned _sp = 0; while (cond) { __builtin_amdgcn_s_sleep(1); \
;     if ((++_sp & 255u) == 0u) { if (xb_ld(&(bar)[XB_TMO])) break; if (_sp > XB_SPIN_CAP) { atomicAdd(&(bar)[XB_TMO], 1u); break; } } } } while (0)
; __device__ __forceinline__ void xcd_barrier(const XcdBarrier& b) {
;     ...
;             else XB_SPIN(xb_ld(&bar[XB_TOPGEN]) == tg, bar);
.LBB0_1013:
	s_or_b64 exec, exec, s[52:53]
	v_mov_b32_e32 v0, s40
	v_mov_b32_e32 v1, s41
	s_orn2_b64 s[40:41], s[54:55], exec

; __device__ __forceinline__ unsigned cvt_pk_bf16(float lo, float hi) { unsigned r; asm volatile("v_cvt_pk_bf16_f32 %0, %1, %2" : "=v"(r) : "v"(lo), "v"(hi)); return r; }
;     __device__ __forceinline__ void operator()(const f32x4 (&acc)[2][2][4][2], const Unit& u, int wr, int wc, int fr, int fq) const {
;         const int b = u.pm / 33, tt = u.pm - b * 33; const bool dorope = (tt != 0) && (u.pn < 8); const float sc = (u.pn < 4) ? qscale : 1.0f;
;         const int rl = wr * 64 + fr, col0 = u.pn * BM + wc * 32 + 8 * fq, i0 = (wc & 1) * 16 + 4 * fq;
; #pragma unroll
;         for (int ai = 0; ai < 2; ++ai)
; #pragma unroll
;             for (int m = 0; m < 4; ++m) { const int r = rl + ai * HALF + m * 16; bf16_t* rowp = O + (size_t)(u.pm * BM + r) * ldc + col0;
;                 f32x4 t0 = (f32x4){1.f, 0.f, 1.f, 0.f}, t1 = t0;
;                 if (dorope) { const int pos = tt * 256 - 256 + r; const int pp = (i0 < 16) ? (pos >> 6) : (pos & 63); const f32x4* tb = (const f32x4*)(rope + (pp * 16 + (i0 & 15)) * 2); t0 = tb[0]; t1 = tb[1]; }
; #pragma unroll
;                 for (int bj = 0; bj < 2; ++bj) { const f32x4 v0 = acc[ai][bj][m][0], v1 = acc[ai][bj][m][1]; u32x4 w;
;                     w.x = cvt_pk_bf16((v0[0] * t0[0] - v0[1] * t0[1]) * sc, (v0[0] * t0[1] + v0[1] * t0[0]) * sc);
;                     w.y = cvt_pk_bf16((v0[2] * t0[2] - v0[3] * t0[3]) * sc, (v0[2] * t0[3] + v0[3] * t0[2]) * sc);
;                     w.z = cvt_pk_bf16((v1[0] * t1[0] - v1[1] * t1[1]) * sc, (v1[0] * t1[1] + v1[1] * t1[0]) * sc);
;                     w.w = cvt_pk_bf16((v1[2] * t1[2] - v1[3] * t1[3]) * sc, (v1[2] * t1[3] + v1[3] * t1[2]) * sc);
;                     *(u32x4*)(rowp + bj * HALF) = w; } }
.Lrope_skip_1:
.LBB0_1035:
	s_cmp_lt_i32 s62, 4
	s_cselect_b64 vcc, -1, 0
	s_lshl_b32 s55, s64, 8
	v_add_u32_e32 v189, s55, v157
	v_mov_b32_e32 v190, s44
	v_mov_b32_e32 v191, s45
	s_waitcnt vmcnt(2)
	v_mul_f32_e32 v192, v124, v198
	v_mul_f32_e32 v193, v125, v199
	v_mad_i64_i32 v[190:191], s[66:67], v189, s79, v[190:191]
	v_sub_f32_e32 v189, v192, v193
	v_mul_f32_e32 v124, v124, v199
	v_mul_f32_e32 v125, v125, v198
	v_mul_f32_e32 v192, v126, v200
	v_mul_f32_e32 v193, v127, v201
	v_mul_f32_e32 v126, v126, v201
	v_mul_f32_e32 v127, v127, v200
	v_cndmask_b32_e32 v188, 1.0, v187, vcc
	s_and_b64 vcc, exec, s[10:11]
	s_cbranch_vccnz .Lrope_skip_2
	v_add_u32_e32 v210, s33, v164
	v_ashrrev_i32_e32 v210, 6, v210
	v_cndmask_b32_e64 v210, v161, v210, s[6:7]
	v_lshl_or_b32 v210, v210, 5, v158
	v_ashrrev_i32_e32 v211, 31, v210
	v_lshl_add_u64 v[214:215], v[210:211], 2, s[50:51]
	global_load_dwordx4 v[210:213], v[214:215], off offset:16
	s_nop 0
	global_load_dwordx4 v[214:217], v[214:215], off

;     __device__ __forceinline__ void operator()(const f32x4 (&acc)[2][2][4][2], const Unit& u, int wr, int wc, int fr, int fq) const {
;     ...
;             for (int m = 0; m < 4; ++m) { const int r = rl + ai * HALF + m * 16; bf16_t* rowp = O + (size_t)(u.pm * BM + r) * ldc + col0;
;                 f32x4 t0 = (f32x4){1.f, 0.f, 1.f, 0.f}, t1 = t0;
;                 if (dorope) { const int pos = tt * 256 - 256 + r; const int pp = (i0 < 16) ? (pos >> 6) : (pos & 63); const f32x4* tb = (const f32x4*)(rope + (pp * 16 + (i0 & 15)) * 2); t0 = tb[0]; t1 = tb[1]; }
.LBB0_1037:
	s_nop 0
	v_add_u32_e32 v118, s55, v163
	v_mov_b32_e32 v116, s44
	v_mov_b32_e32 v117, s45
	v_mad_i64_i32 v[116:117], s[66:67], v118, s79, v[116:117]
	s_waitcnt vmcnt(4)
	s_and_b64 vcc, exec, s[10:11]
	s_cbranch_vccnz .Lrope_skip_3
	v_add_u32_e32 v198, s33, v165
	v_ashrrev_i32_e32 v198, 6, v198
	v_cndmask_b32_e64 v198, v162, v198, s[6:7]
	v_lshl_or_b32 v198, v198, 5, v158
	v_ashrrev_i32_e32 v199, 31, v198
	v_lshl_add_u64 v[198:199], v[198:199], 2, s[50:51]
	global_load_dwordx4 v[194:197], v[198:199], off offset:16
	s_nop 0
	global_load_dwordx4 v[198:201], v[198:199], off

;     __device__ __forceinline__ void operator()(const f32x4 (&acc)[2][2][4][2], const Unit& u, int wr, int wc, int fr, int fq) const {
;     ...
;             for (int m = 0; m < 4; ++m) { const int r = rl + ai * HALF + m * 16; bf16_t* rowp = O + (size_t)(u.pm * BM + r) * ldc + col0;
;                 f32x4 t0 = (f32x4){1.f, 0.f, 1.f, 0.f}, t1 = t0;
;                 if (dorope) { const int pos = tt * 256 - 256 + r; const int pp = (i0 < 16) ? (pos >> 6) : (pos & 63); const f32x4* tb = (const f32x4*)(rope + (pp * 16 + (i0 & 15)) * 2); t0 = tb[0]; t1 = tb[1]; }
.LBB0_1039:
	v_add_u32_e32 v108, s55, v164
	v_mov_b32_e32 v106, s44
	v_mov_b32_e32 v107, s45
	v_mad_i64_i32 v[106:107], s[66:67], v108, s79, v[106:107]
	s_waitcnt vmcnt(6)
	s_and_b64 vcc, exec, s[10:11]
	s_cbranch_vccnz .Lrope_skip_4
	v_add_u32_e32 v202, s33, v166
	v_ashrrev_i32_e32 v202, 6, v202
	v_cndmask_b32_e64 v202, v156, v202, s[6:7]
	v_lshl_or_b32 v202, v202, 5, v158
	v_ashrrev_i32_e32 v203, 31, v202
	v_lshl_add_u64 v[206:207], v[202:203], 2, s[50:51]
	global_load_dwordx4 v[202:205], v[206:207], off offset:16
	s_nop 0
	global_load_dwordx4 v[206:209], v[206:207], off

;     __device__ __forceinline__ void operator()(const f32x4 (&acc)[2][2][4][2], const Unit& u, int wr, int wc, int fr, int fq) const {
;     ...
;             for (int m = 0; m < 4; ++m) { const int r = rl + ai * HALF + m * 16; bf16_t* rowp = O + (size_t)(u.pm * BM + r) * ldc + col0;
;                 f32x4 t0 = (f32x4){1.f, 0.f, 1.f, 0.f}, t1 = t0;
;                 if (dorope) { const int pos = tt * 256 - 256 + r; const int pp = (i0 < 16) ? (pos >> 6) : (pos & 63); const f32x4* tb = (const f32x4*)(rope + (pp * 16 + (i0 & 15)) * 2); t0 = tb[0]; t1 = tb[1]; }
.LBB0_1041:
	s_nop 0
	v_add_u32_e32 v86, s55, v165
	v_mov_b32_e32 v84, s44
	v_mov_b32_e32 v85, s45
	v_mad_i64_i32 v[84:85], s[66:67], v86, s79, v[84:85]
	s_waitcnt vmcnt(6)
	s_and_b64 vcc, exec, s[10:11]
	s_cbranch_vccnz .Lrope_skip_5
	v_add_u32_e32 v214, s33, v167
	v_ashrrev_i32_e32 v214, 6, v214
	v_cndmask_b32_e64 v214, v160, v214, s[6:7]
	v_lshl_or_b32 v214, v214, 5, v158
	v_ashrrev_i32_e32 v215, 31, v214
	v_lshl_add_u64 v[214:215], v[214:215], 2, s[50:51]
	global_load_dwordx4 v[210:213], v[214:215], off offset:16
	s_nop 0
	global_load_dwordx4 v[214:217], v[214:215], off

;     __device__ __forceinline__ void operator()(const f32x4 (&acc)[2][2][4][2], const Unit& u, int wr, int wc, int fr, int fq) const {
;     ...
;             for (int m = 0; m < 4; ++m) { const int r = rl + ai * HALF + m * 16; bf16_t* rowp = O + (size_t)(u.pm * BM + r) * ldc + col0;
;                 f32x4 t0 = (f32x4){1.f, 0.f, 1.f, 0.f}, t1 = t0;
;                 if (dorope) { const int pos = tt * 256 - 256 + r; const int pp = (i0 < 16) ? (pos >> 6) : (pos & 63); const f32x4* tb = (const f32x4*)(rope + (pp * 16 + (i0 & 15)) * 2); t0 = tb[0]; t1 = tb[1]; }
.LBB0_1043:
	v_add_u32_e32 v76, s55, v166
	v_mov_b32_e32 v74, s44
	v_mov_b32_e32 v75, s45
	v_mad_i64_i32 v[74:75], s[66:67], v76, s79, v[74:75]
	s_waitcnt vmcnt(6)
	s_and_b64 vcc, exec, s[10:11]
	s_cbranch_vccnz .Lrope_skip_6
	v_add_u32_e32 v194, s33, v168
	v_ashrrev_i32_e32 v194, 6, v194
	v_cndmask_b32_e64 v194, v161, v194, s[6:7]
	v_lshl_or_b32 v194, v194, 5, v158
	v_ashrrev_i32_e32 v195, 31, v194
	v_lshl_add_u64 v[198:199], v[194:195], 2, s[50:51]
	global_load_dwordx4 v[194:197], v[198:199], off offset:16
	s_nop 0
	global_load_dwordx4 v[198:201], v[198:199], off

;     __device__ __forceinline__ void operator()(const f32x4 (&acc)[2][2][4][2], const Unit& u, int wr, int wc, int fr, int fq) const {
;     ...
;             for (int m = 0; m < 4; ++m) { const int r = rl + ai * HALF + m * 16; bf16_t* rowp = O + (size_t)(u.pm * BM + r) * ldc + col0;
;                 f32x4 t0 = (f32x4){1.f, 0.f, 1.f, 0.f}, t1 = t0;
;                 if (dorope) { const int pos = tt * 256 - 256 + r; const int pp = (i0 < 16) ? (pos >> 6) : (pos & 63); const f32x4* tb = (const f32x4*)(rope + (pp * 16 + (i0 & 15)) * 2); t0 = tb[0]; t1 = tb[1]; }
.LBB0_1045:
	s_nop 0
	v_add_u32_e32 v54, s55, v167
	v_mov_b32_e32 v52, s44
	v_mov_b32_e32 v53, s45
	v_mad_i64_i32 v[52:53], s[66:67], v54, s79, v[52:53]
	s_waitcnt vmcnt(6)
	s_and_b64 vcc, exec, s[10:11]
	s_cbranch_vccnz .Lrope_skip_7
	v_add_u32_e32 v206, s33, v169
	v_ashrrev_i32_e32 v206, 6, v206
	v_cndmask_b32_e64 v206, v162, v206, s[6:7]
	v_lshl_or_b32 v206, v206, 5, v158
	v_ashrrev_i32_e32 v207, 31, v206
	v_lshl_add_u64 v[206:207], v[206:207], 2, s[50:51]
	global_load_dwordx4 v[202:205], v[206:207], off offset:16
	s_nop 0
	global_load_dwordx4 v[206:209], v[206:207], off

; __device__ __forceinline__ unsigned cvt_pk_bf16(float lo, float hi) { unsigned r; asm volatile("v_cvt_pk_bf16_f32 %0, %1, %2" : "=v"(r) : "v"(lo), "v"(hi)); return r; }
;     __device__ __forceinline__ void operator()(const f32x4 (&acc)[2][2][4][2], const Unit& u, int wr, int wc, int fr, int fq) const {
;     ...
;             for (int m = 0; m < 4; ++m) { const int r = rl + ai * HALF + m * 16; bf16_t* rowp = O + (size_t)(u.pm * BM + r) * ldc + col0;
;                 f32x4 t0 = (f32x4){1.f, 0.f, 1.f, 0.f}, t1 = t0;
;                 if (dorope) { const int pos = tt * 256 - 256 + r; const int pp = (i0 < 16) ? (pos >> 6) : (pos & 63); const f32x4* tb = (const f32x4*)(rope + (pp * 16 + (i0 & 15)) * 2); t0 = tb[0]; t1 = tb[1]; }
; #pragma unroll
;                 for (int bj = 0; bj < 2; ++bj) { const f32x4 v0 = acc[ai][bj][m][0], v1 = acc[ai][bj][m][1]; u32x4 w;
;                     w.x = cvt_pk_bf16((v0[0] * t0[0] - v0[1] * t0[1]) * sc, (v0[0] * t0[1] + v0[1] * t0[0]) * sc);
;                     w.y = cvt_pk_bf16((v0[2] * t0[2] - v0[3] * t0[3]) * sc, (v0[2] * t0[3] + v0[3] * t0[2]) * sc);
;                     w.z = cvt_pk_bf16((v1[0] * t1[0] - v1[1] * t1[1]) * sc, (v1[0] * t1[1] + v1[1] * t1[0]) * sc);
;                     w.w = cvt_pk_bf16((v1[2] * t1[2] - v1[3] * t1[3]) * sc, (v1[2] * t1[3] + v1[3] * t1[2]) * sc);
;                     *(u32x4*)(rowp + bj * HALF) = w; } }
.LBB0_1047:
	v_add_u32_e32 v44, s55, v168
	v_mov_b32_e32 v42, s44
	v_mov_b32_e32 v43, s45
	v_mad_i64_i32 v[42:43], s[66:67], v44, s79, v[42:43]
	s_waitcnt vmcnt(6)
	v_mul_f32_e32 v44, v28, v198
	v_mul_f32_e32 v45, v29, v199
	v_mul_f32_e32 v28, v28, v199
	v_mul_f32_e32 v29, v29, v198
	v_sub_f32_e32 v44, v44, v45
	v_add_f32_e32 v28, v28, v29
	v_mul_f32_e32 v44, v188, v44
	v_mul_f32_e32 v28, v188, v28
	v_cvt_pk_bf16_f32 v28, v44, v28
	v_mul_f32_e32 v44, v30, v200
	v_mul_f32_e32 v45, v31, v201
	v_mul_f32_e32 v30, v30, v201
	v_mul_f32_e32 v31, v31, v200
	v_sub_f32_e32 v29, v44, v45
	v_add_f32_e32 v30, v30, v31
	v_mul_f32_e32 v29, v188, v29
	v_mul_f32_e32 v30, v188, v30
	v_cvt_pk_bf16_f32 v29, v29, v30
	v_mul_f32_e32 v30, v24, v194
	v_mul_f32_e32 v31, v25, v195
	v_mul_f32_e32 v24, v24, v195
	v_mul_f32_e32 v25, v25, v194
	v_sub_f32_e32 v30, v30, v31
	v_add_f32_e32 v24, v24, v25
	v_mul_f32_e32 v30, v188, v30
	v_mul_f32_e32 v24, v188, v24
	v_cvt_pk_bf16_f32 v30, v30, v24
	v_mul_f32_e32 v24, v26, v196
	v_mul_f32_e32 v25, v27, v197
	v_lshl_add_u64 v[42:43], v[154:155], 1, v[42:43]
	v_sub_f32_e32 v24, v24, v25
	v_mul_f32_e32 v31, v188, v24
	v_mul_f32_e32 v24, v26, v197
	v_mul_f32_e32 v25, v27, v196
	s_and_b64 vcc, exec, s[10:11]
	v_add_f32_e32 v24, v24, v25
	v_mul_f32_e32 v24, v188, v24
	v_cvt_pk_bf16_f32 v31, v31, v24
	v_mul_f32_e32 v24, v20, v198
	v_mul_f32_e32 v25, v21, v199
	v_mul_f32_e32 v20, v20, v199
	v_mul_f32_e32 v21, v21, v198
	v_sub_f32_e32 v24, v24, v25
	v_add_f32_e32 v20, v20, v21
	v_mul_f32_e32 v24, v188, v24
	v_mul_f32_e32 v20, v188, v20
	global_store_dwordx4 v[42:43], v[28:31], off
	v_cvt_pk_bf16_f32 v20, v24, v20
	v_mul_f32_e32 v24, v22, v200
	v_mul_f32_e32 v25, v23, v201
	v_mul_f32_e32 v22, v22, v201
	v_mul_f32_e32 v23, v23, v200
	v_sub_f32_e32 v21, v24, v25
	v_add_f32_e32 v22, v22, v23
	v_mul_f32_e32 v21, v188, v21
	v_mul_f32_e32 v22, v188, v22
	v_cvt_pk_bf16_f32 v21, v21, v22
	v_mul_f32_e32 v22, v16, v194
	v_mul_f32_e32 v23, v17, v195
	v_mul_f32_e32 v16, v16, v195
	v_mul_f32_e32 v17, v17, v194
	v_sub_f32_e32 v22, v22, v23
	v_add_f32_e32 v16, v16, v17
	v_mul_f32_e32 v22, v188, v22
	v_mul_f32_e32 v16, v188, v16
	v_cvt_pk_bf16_f32 v22, v22, v16
	v_mul_f32_e32 v16, v18, v196
	v_mul_f32_e32 v17, v19, v197
	v_mov_b32_e32 v34, 1.0
	v_sub_f32_e32 v16, v16, v17
	v_mul_f32_e32 v23, v188, v16
	v_mul_f32_e32 v16, v18, v197
	v_mul_f32_e32 v17, v19, v196
	v_mov_b32_e32 v35, 0
	v_add_f32_e32 v16, v16, v17
	v_mul_f32_e32 v16, v188, v16
	v_cvt_pk_bf16_f32 v23, v23, v16
	v_mov_b32_e32 v16, 1.0
	v_mov_b32_e32 v17, 0
	v_mov_b32_e32 v18, 1.0
	v_mov_b32_e32 v19, 0
	global_store_dwordx4 v[42:43], v[20:23], off offset:256
	s_nop 1
.LBB0_1049:
	s_nop 0
	v_add_u32_e32 v22, s55, v169
	v_mov_b32_e32 v20, s44
	v_mov_b32_e32 v21, s45
	v_mad_i64_i32 v[20:21], s[10:11], v22, s79, v[20:21]
	s_waitcnt vmcnt(4)
	v_mul_f32_e32 v22, v12, v206
	v_mul_f32_e32 v23, v13, v207
	v_mul_f32_e32 v12, v12, v207
	v_mul_f32_e32 v13, v13, v206
	v_sub_f32_e32 v22, v22, v23
	v_add_f32_e32 v12, v12, v13
	v_mul_f32_e32 v22, v188, v22
	v_mul_f32_e32 v12, v188, v12
	v_cvt_pk_bf16_f32 v12, v22, v12
	v_mul_f32_e32 v22, v14, v208
	v_mul_f32_e32 v23, v15, v209
	v_mul_f32_e32 v14, v14, v209
	v_mul_f32_e32 v15, v15, v208
	v_sub_f32_e32 v13, v22, v23
	v_add_f32_e32 v14, v14, v15
	v_mul_f32_e32 v13, v188, v13
	v_mul_f32_e32 v14, v188, v14
	v_cvt_pk_bf16_f32 v13, v13, v14
	v_mul_f32_e32 v14, v8, v202
	v_mul_f32_e32 v15, v9, v203
	v_mul_f32_e32 v8, v8, v203
	v_mul_f32_e32 v9, v9, v202
	v_sub_f32_e32 v14, v14, v15
	v_add_f32_e32 v8, v8, v9
	v_mul_f32_e32 v14, v188, v14
	v_mul_f32_e32 v8, v188, v8
	v_cvt_pk_bf16_f32 v14, v14, v8
	v_mul_f32_e32 v8, v10, v204
	v_mul_f32_e32 v9, v11, v205
	v_lshl_add_u64 v[20:21], v[154:155], 1, v[20:21]
	v_sub_f32_e32 v8, v8, v9
	v_mul_f32_e32 v15, v188, v8
	v_mul_f32_e32 v8, v10, v205
	v_mul_f32_e32 v9, v11, v204
	s_andn2_b64 vcc, exec, s[8:9]
	v_add_f32_e32 v8, v8, v9
	v_mul_f32_e32 v8, v188, v8
	v_cvt_pk_bf16_f32 v15, v15, v8
	v_mul_f32_e32 v8, v4, v206
	v_mul_f32_e32 v9, v5, v207
	v_mul_f32_e32 v4, v4, v207
	v_mul_f32_e32 v5, v5, v206
	v_sub_f32_e32 v8, v8, v9
	v_add_f32_e32 v4, v4, v5
	v_mul_f32_e32 v8, v188, v8
	v_mul_f32_e32 v4, v188, v4
	global_store_dwordx4 v[20:21], v[12:15], off
	v_cvt_pk_bf16_f32 v4, v8, v4
	v_mul_f32_e32 v8, v6, v208
	v_mul_f32_e32 v9, v7, v209
	v_mul_f32_e32 v6, v6, v209
	v_mul_f32_e32 v7, v7, v208
	v_sub_f32_e32 v5, v8, v9
	v_add_f32_e32 v6, v6, v7
	v_mul_f32_e32 v5, v188, v5
	v_mul_f32_e32 v6, v188, v6
	v_cvt_pk_bf16_f32 v5, v5, v6
	v_mul_f32_e32 v6, v0, v202
	v_mul_f32_e32 v7, v1, v203
	v_mul_f32_e32 v0, v0, v203
	v_mul_f32_e32 v1, v1, v202
	v_sub_f32_e32 v6, v6, v7
	v_add_f32_e32 v0, v0, v1
	v_mul_f32_e32 v6, v188, v6
	v_mul_f32_e32 v0, v188, v0
	v_cvt_pk_bf16_f32 v6, v6, v0
	v_mul_f32_e32 v0, v2, v204
	v_mul_f32_e32 v1, v3, v205
	s_mov_b64 s[8:9], -1
	v_sub_f32_e32 v0, v0, v1
	v_mul_f32_e32 v7, v188, v0
	v_mul_f32_e32 v0, v2, v205
	v_mul_f32_e32 v1, v3, v204
	s_nop 0
	v_add_f32_e32 v0, v0, v1
	v_mul_f32_e32 v0, v188, v0
	v_cvt_pk_bf16_f32 v7, v7, v0
	global_store_dwordx4 v[20:21], v[4:7], off offset:256
	s_cbranch_vccnz .LBB0_1026
	s_andn2_b64 vcc, exec, s[36:37]
	s_cbranch_vccnz .LBB0_1025
	s_barrier
	s_branch .LBB0_1025

; __device__ __forceinline__ unsigned xb_ld(unsigned* p)              { return __hip_atomic_load(p, __ATOMIC_RELAXED, __HIP_MEMORY_SCOPE_AGENT); }
; __device__ __forceinline__ unsigned xb_add(unsigned* p, unsigned v) { return __hip_atomic_fetch_add(p, v, __ATOMIC_RELAXED, __HIP_MEMORY_SCOPE_AGENT); }
; #define XB_SPIN(cond, bar) do { unsigned _sp = 0; while (cond) { __builtin_amdgcn_s_sleep(1); \
;     if ((++_sp & 255u) == 0u) { if (xb_ld(&(bar)[XB_TMO])) break; if (_sp > XB_SPIN_CAP) { atomicAdd(&(bar)[XB_TMO], 1u); break; } } } } while (0)
; __device__ __forceinline__ void xcd_barrier(const XcdBarrier& b) {
;     ...
;             const unsigned og = xb_add(&bar[XB_TOP], 1u);
;             const unsigned tg = og / nx;
;             if (og + 1u == (tg + 1u) * nx) xb_add(&bar[XB_TOPGEN], 1u);
;             else XB_SPIN(xb_ld(&bar[XB_TOPGEN]) == tg, bar);
.LBB0_1088:
	s_or_b64 exec, exec, s[36:37]
	v_cvt_f32_u32_e32 v3, v0
	s_waitcnt vmcnt(0)
	v_readfirstlane_b32 s1, v2
	s_add_u32 s36, s30, 0x1bbc3500
	s_addc_u32 s37, s31, 0
	v_rcp_iflag_f32_e32 v3, v3
	v_add_u32_e32 v1, s1, v1
	v_add_u32_e32 v4, 1, v1
	s_mov_b64 s[40:41], -1
	v_mul_f32_e32 v2, 0x4f7ffffe, v3
	v_cvt_u32_f32_e32 v2, v2
	v_sub_u32_e32 v3, 0, v0
	v_mul_lo_u32 v3, v3, v2
	v_mul_hi_u32 v3, v2, v3
	v_add_u32_e32 v2, v2, v3
	v_mul_hi_u32 v2, v1, v2
	v_mul_lo_u32 v3, v2, v0
	v_sub_u32_e32 v1, v1, v3
	v_add_u32_e32 v5, 1, v2
	v_cmp_ge_u32_e32 vcc, v1, v0
	v_sub_u32_e32 v3, v1, v0
	s_nop 0
	v_cndmask_b32_e32 v2, v2, v5, vcc
	v_cndmask_b32_e32 v1, v1, v3, vcc
	v_add_u32_e32 v3, 1, v2
	v_cmp_ge_u32_e32 vcc, v1, v0
	s_nop 1
	v_cndmask_b32_e32 v2, v2, v3, vcc
	v_mul_lo_u32 v1, v0, v2
	v_add_u32_e32 v0, v1, v0
	v_cmp_ne_u32_e32 vcc, v4, v0
	v_mov_b32_e32 v0, s36
	v_mov_b32_e32 v1, s37
	s_and_saveexec_b64 s[10:11], vcc
	s_cbranch_execz .LBB0_1100
	v_mov_b32_e32 v0, 0
	global_load_dword v1, v0, s[36:37] sc1
	s_mov_b64 s[52:53], 0
	s_waitcnt vmcnt(0)
	v_cmp_eq_u32_e32 vcc, v1, v2
	s_and_saveexec_b64 s[50:51], vcc
	s_cbranch_execz .LBB0_1099
	s_add_u32 s40, s30, 0x1bbc0200
	s_addc_u32 s41, s31, 0
	s_mov_b32 s1, 1
	s_branch .LBB0_1092

; __device__ __forceinline__ unsigned xb_ld(unsigned* p)              { return __hip_atomic_load(p, __ATOMIC_RELAXED, __HIP_MEMORY_SCOPE_AGENT); }
; #define XB_SPIN(cond, bar) do { unsigned _sp = 0; while (cond) { __builtin_amdgcn_s_sleep(1); \
;     if ((++_sp & 255u) == 0u) { if (xb_ld(&(bar)[XB_TMO])) break; if (_sp > XB_SPIN_CAP) { atomicAdd(&(bar)[XB_TMO], 1u); break; } } } } while (0)
; __device__ __forceinline__ void xcd_barrier(const XcdBarrier& b) {
;     ...
;             else XB_SPIN(xb_ld(&bar[XB_TOPGEN]) == tg, bar);
.LBB0_1099:
	s_or_b64 exec, exec, s[50:51]
	v_mov_b32_e32 v0, s40
	v_mov_b32_e32 v1, s41
	s_orn2_b64 s[40:41], s[52:53], exec

; #define WAIT_BAR(N) asm volatile("s_waitcnt vmcnt(" #N ") lgkmcnt(0)\n\ts_barrier":::"memory")
;   #define DMA_K(t,slot) glds16(ksrc+(long)KROW(t)*PK,(unsigned)__builtin_amdgcn_readfirstlane(kdst+(slot)))
;   #define DMA_V(t,slot) do{ glds16(vsrc+(long)KROW(t)*PV,(unsigned)__builtin_amdgcn_readfirstlane(vdst+2*(slot))); if(MODE==2)glds16(vsrc+(long)KROW(t)*PV+64,(unsigned)__builtin_amdgcn_readfirstlane(vdst+2*(slot)+SLOTB)); }while(0)
; template<int MODE,int THRL> __device__ __forceinline__ void attn_unit(const bf16*Qw0,int PQ,const bf16*__restrict__ Kh,int PK,const bf16*__restrict__ Vh,int PV,bf16*Ow0,int PO,int NT,int nabase,int nar0,const float*rpbh,char*shm,int&rot,bool pre,bool hasn,long dKn,long dVn){
;     ...
;   if(!pre){ DMA_K(0,rot);DMA_V(0,rot);DMA_K(1,NXT(rot)); }
;   bf16x8 qr[4];
;   #pragma unroll
;   for(int d0=0;d0<4;++d0)qr[d0]=*reinterpret_cast<const bf16x8*>(&Qw[(long)r32*PQ+d0*16+hi*8]);
;   float mhat=0.f,l_reg=0.f;constexpr int ND=(MODE==2)?4:2; f32x16 o[4];o[0]=f32x16{};o[1]=f32x16{};o[2]=f32x16{};o[3]=f32x16{};f32x16 negm=f32x16{};asm volatile("":"+v"(negm));
;     ...
;   bool resc=false;
;     ...
;   f32x16 pA0,pA1,pB0,pB1;
;   int sl_prev=rot,sl_cur=rot,sl_next=NXT(rot);
;   bool pfnow=false;
;     ...
;   if(!pre){ DMA_K(2,NXT(sl_next)); }
;   if(pre){WAIT_BAR(0);}else if(MODE==2){WAIT_BAR(4);}else{WAIT_BAR(3);}
; template <int l> __device__ __forceinline__ void layer_body(const Args& a, unsigned char* lds, const XcdBarrier& bar, int G, int bx, int vcu, int gw, int NGW, int lane_, int tid_k, int wave) {
;     ...
;                     if (ok) { const int bh = g >> 6, b = bh >> 3, h = bh & 7, sub = g & 63, map = sub >> 5, qb = sub & 31;
;                         const size_t rb = (size_t)b * TPB, rq = rb + CTXL + (size_t)qb * 256;
;                         attn_body::attn_unit<2, 8>(qkv + rq * DIFF_IN + h * 128 + map * 64, DIFF_IN, qkv + rb * DIFF_IN + 1024 + h * 128 + map * 64, DIFF_IN, qkv + rb * DIFF_IN + 2048 + h * 128, DIFF_IN,
;                                                    (abf*)OP + ((size_t)b * SEQ + (size_t)qb * 256) * 2048 + map * 1024 + h * 128, 2048, TPB / 64, 0, 0, nullptr, (char*)lds,
;                                                    rot, pre, ok2, (long)(rb2 * DIFF_IN + h2 * 128 + map2 * 64) - (long)(rb * DIFF_IN + h * 128 + map * 64), (long)(rb2 * DIFF_IN + h2 * 128) - (long)(rb * DIFF_IN + h * 128));
.LBB0_1121:
	s_lshl_b32 s15, s96, 8
	s_ashr_i32 s77, s76, 31
	s_lshl_b32 s10, s73, 6
	s_mul_i32 s11, s76, 0x2100
	s_and_b32 s78, s15, 0x1f00
	s_mul_hi_i32 s8, s76, 0x2100
	s_add_u32 s11, s11, s78
	s_addc_u32 s8, s8, 0
	s_add_u32 s70, s11, 0x100
	s_addc_u32 s71, s8, 0
	s_mul_i32 s8, s71, 0x1800
	s_mul_hi_u32 s11, s70, 0x1800
	s_add_i32 s11, s11, s8
	s_mul_i32 s8, s70, 0x1800
	s_add_u32 s8, s44, s8
	s_addc_u32 s11, s45, s11
	s_lshl_b32 s72, s80, 1
	s_add_u32 s8, s8, s72
	s_addc_u32 s11, s11, 0
	s_lshl_b32 s15, s10, 1
	s_add_u32 s8, s8, s15
	v_and_b32_e32 v239, 31, v40
	s_addc_u32 s11, s11, 0
	s_mul_i32 s33, s74, 0x30000
	v_mul_u32_u24_e32 v1, 0xc00, v239
	v_lshrrev_b32_e32 v240, 5, v237
	s_mul_hi_i32 s15, s74, 0x30000
	s_add_u32 s90, s8, s33
	v_lshlrev_b32_e32 v1, 1, v1
	s_addc_u32 s91, s11, s15
	v_lshl_or_b32 v1, v240, 4, v1
	global_load_dwordx4 v[174:177], v1, s[90:91]
	global_load_dwordx4 v[170:173], v1, s[90:91] offset:32
	global_load_dwordx4 v[166:169], v1, s[90:91] offset:64
	global_load_dwordx4 v[162:165], v1, s[90:91] offset:96
	v_mov_b32_e32 v2, v0
	v_mov_b32_e32 v3, v0
	v_mov_b32_e32 v4, v0
	v_mov_b32_e32 v5, v0
	v_mov_b32_e32 v6, v0
	v_mov_b32_e32 v7, v0
	v_mov_b32_e32 v8, v0
	v_mov_b32_e32 v9, v0
	v_mov_b32_e32 v10, v0
	v_mov_b32_e32 v11, v0
	v_mov_b32_e32 v12, v0
	v_mov_b32_e32 v13, v0
	v_mov_b32_e32 v14, v0
	v_mov_b32_e32 v15, v0
	v_mov_b32_e32 v1, v0
	v_mov_b32_e32 v16, v14
	v_mov_b32_e32 v17, v15
	s_cmpk_lg_i32 s9, 0x4000
	s_mov_b32 s81, s85
	s_mov_b32 s11, s85
	s_mov_b32 s79, s85
	v_mov_b32_e32 v14, v12
	v_mov_b32_e32 v15, v13
	v_mov_b32_e32 v12, v10
	v_mov_b32_e32 v13, v11
	v_mov_b32_e32 v10, v8
	v_mov_b32_e32 v11, v9
	v_mov_b32_e32 v8, v6
	v_mov_b32_e32 v9, v7
	v_mov_b32_e32 v6, v4
	v_mov_b32_e32 v7, v5
	v_mov_b32_e32 v4, v2
	v_mov_b32_e32 v5, v3
	v_mov_b32_e32 v2, v0
	v_mov_b32_e32 v3, v1
	s_cselect_b32 s15, s4, 0
	s_andn2_b64 vcc, exec, s[6:7]
	s_mov_b64 s[6:7], -1
	s_cbranch_vccnz .LBB0_1123
	s_add_i32 s4, s15, 0x2000
	s_cmpk_lg_i32 s15, 0x4000
	s_cselect_b32 s6, s4, 0
	v_lshl_add_u64 v[18:19], v[38:39], 0, s[60:61]
	s_add_i32 s6, s6, s55
	s_mov_b32 s7, m0
	s_mov_b32 m0, s6
	s_nop 0
	global_load_lds_dwordx4 v[18:19], off
	s_mov_b32 m0, s7
	s_waitcnt vmcnt(4) lgkmcnt(0)
	s_barrier
	s_mov_b64 s[6:7], 0

;   #define CMASK(P0,P1,t) do{ if(MODE==1&&(t)>=4)na_apply(P0,P1,mf,na_rowok((t),nabase,nar)); }while(0)
;   #define START(P0,P1) do{ const float rm=rowmax(P0,P1); resc=false; \
;     { const float dl=rm; mhat=fadd_s(mhat,dl); \
;       _Pragma("unroll") for(int r=0;r<16;++r){P0[r]=fsub_s(P0[r],dl);P1[r]=fsub_s(P1[r],dl);} \
;       _Pragma("unroll") for(int r=0;r<16;++r)negm[r]=-mhat; asm volatile("":"+v"(negm)); } \
;     _Pragma("unroll") for(int r=0;r<16;++r)P0[r]=__builtin_amdgcn_exp2f(P0[r]); }while(0)
; template<int MODE,int THRL> __device__ __forceinline__ void attn_unit(const bf16*Qw0,int PQ,const bf16*__restrict__ Kh,int PK,const bf16*__restrict__ Vh,int PV,bf16*Ow0,int PO,int NT,int nabase,int nar0,const float*rpbh,char*shm,int&rot,bool pre,bool hasn,long dKn,long dVn){
;     ...
;   qkt(pA0,pA1,Kbase+sl_cur,qr,negm,r32,hi);asm volatile("s_nop 15\n\ts_nop 7":"+v"(pA0),"+v"(pA1));CMASK(pA0,pA1,0);
;   START(pA0,pA1);
.LBB0_1125:
	v_lshlrev_b32_e32 v1, 10, v240
	v_lshlrev_b32_e32 v35, 4, v239
	v_add3_u32 v37, s9, v1, v35
	ds_read_b128 v[42:45], v37
	v_or_b32_e32 v248, v1, v35
	s_add_i32 s6, s55, s9
	s_and_b32 s3, s3, 0x3fffffc0
	s_lshl_b32 s3, s3, 2
	s_ashr_i32 s75, s74, 31
	s_add_i32 s3, s3, 0x12000
	s_mul_i32 s8, s76, 0x3180000
	s_waitcnt vmcnt(3) lgkmcnt(0)
	v_mfma_f32_32x32x16_bf16 v[18:33], v[42:45], v[174:177], v[2:17]
	ds_read_b128 v[42:45], v37 offset:512
	v_lshl_or_b32 v243, v239, 2, s3
	v_lshlrev_b32_e32 v245, 4, v240
	v_mov_b32_e32 v249, 0
	s_waitcnt lgkmcnt(0)
	v_mfma_f32_32x32x16_bf16 v[2:17], v[42:45], v[174:177], v[2:17]
	ds_read_b128 v[42:45], v37 offset:2048
	s_waitcnt vmcnt(2) lgkmcnt(0)
	v_mfma_f32_32x32x16_bf16 v[18:33], v[42:45], v[170:173], v[18:33]
	ds_read_b128 v[42:45], v37 offset:2560
	s_waitcnt lgkmcnt(0)
	v_mfma_f32_32x32x16_bf16 v[2:17], v[42:45], v[170:173], v[2:17]
	ds_read_b128 v[42:45], v37 offset:4096
	s_waitcnt vmcnt(1) lgkmcnt(0)
	v_mfma_f32_32x32x16_bf16 v[18:33], v[42:45], v[166:169], v[18:33]
	ds_read_b128 v[42:45], v37 offset:4608
	s_waitcnt lgkmcnt(0)
	v_mfma_f32_32x32x16_bf16 v[2:17], v[42:45], v[166:169], v[2:17]
	ds_read_b128 v[42:45], v37 offset:6144
	ds_read_b128 v[46:49], v37 offset:6656
	v_lshlrev_b32_e32 v37, 1, v40
	v_and_b32_e32 v244, 32, v37
	v_lshlrev_b32_e32 v37, 4, v40
	v_and_b32_e32 v37, 0xc0, v37
	v_lshl_or_b32 v242, v240, 8, v37
	v_mov_b32_e32 v37, v0
	s_waitcnt vmcnt(0) lgkmcnt(1)
	v_mfma_f32_32x32x16_bf16 v[18:33], v[42:45], v[162:165], v[18:33]
	v_or3_b32 v247, v244, v241, v242
	s_waitcnt lgkmcnt(0)
	v_mfma_f32_32x32x16_bf16 v[2:17], v[46:49], v[162:165], v[2:17]
	s_nop 15
	s_nop 7
	s_nop 0
	v_max3_f32 v1, v18, v19, v2
	v_max3_f32 v35, v20, v21, v3
	s_nop 0
	v_max3_f32 v1, v1, v4, v5
	v_max3_f32 v35, v35, v24, v25
	s_nop 0
	v_max3_f32 v1, v1, v22, v23
	v_max3_f32 v35, v35, v8, v9
	s_nop 0
	v_max3_f32 v1, v1, v6, v7
	v_max3_f32 v35, v35, v28, v29
	s_nop 0
	v_max3_f32 v1, v1, v26, v27
	v_max3_f32 v35, v35, v12, v13
	s_nop 0
	v_max3_f32 v1, v1, v10, v11
	v_max3_f32 v35, v35, v32, v33
	s_nop 0
	v_max3_f32 v1, v1, v30, v31
	v_max3_f32 v35, v35, v16, v17
	s_nop 0
	v_max3_f32 v1, v1, v14, v15
	s_nop 0
	v_max_f32_e32 v1, v1, v35
	s_nop 0
	v_mov_b32_e32 v35, v1
	s_nop 1
	v_permlane32_swap_b32_e32 v1, v35
	v_max_f32_e32 v1, v1, v35
	v_mov_b32_e32 v35, v0
	v_add_f32_e32 v246, v0, v1
	v_sub_f32_e32 v2, v2, v1
	v_sub_f32_e32 v3, v3, v1
	v_sub_f32_e32 v18, v18, v1
	v_sub_f32_e32 v19, v19, v1
	v_sub_f32_e32 v20, v20, v1
	s_nop 0
	v_xor_b32_e32 v66, 0x80000000, v246
	v_mov_b32_e32 v67, v66
	v_mov_b32_e32 v68, v66
	v_mov_b32_e32 v69, v66
	v_mov_b32_e32 v70, v66
	v_mov_b32_e32 v71, v66
	v_mov_b32_e32 v72, v66
	v_mov_b32_e32 v73, v66
	v_mov_b32_e32 v74, v66
	v_mov_b32_e32 v75, v66
	v_mov_b32_e32 v76, v66
	v_mov_b32_e32 v77, v66
	v_mov_b32_e32 v78, v66
	v_mov_b32_e32 v79, v66
	v_mov_b32_e32 v80, v66
	v_mov_b32_e32 v81, v66
	s_waitcnt vmcnt(0) lgkmcnt(0)
	s_barrier
; #define WAIT_BAR(N) asm volatile("s_waitcnt vmcnt(" #N ") lgkmcnt(0)\n\ts_barrier":::"memory")
;   #define DMA_K(t,slot) glds16(ksrc+(long)KROW(t)*PK,(unsigned)__builtin_amdgcn_readfirstlane(kdst+(slot)))
;   #define DMA_V(t,slot) do{ glds16(vsrc+(long)KROW(t)*PV,(unsigned)__builtin_amdgcn_readfirstlane(vdst+2*(slot))); if(MODE==2)glds16(vsrc+(long)KROW(t)*PV+64,(unsigned)__builtin_amdgcn_readfirstlane(vdst+2*(slot)+SLOTB)); }while(0)
;   #define START(P0,P1) do{ const float rm=rowmax(P0,P1); resc=false; \
;     { const float dl=rm; mhat=fadd_s(mhat,dl); \
;       _Pragma("unroll") for(int r=0;r<16;++r){P0[r]=fsub_s(P0[r],dl);P1[r]=fsub_s(P1[r],dl);} \
;       _Pragma("unroll") for(int r=0;r<16;++r)negm[r]=-mhat; asm volatile("":"+v"(negm)); } \
;     _Pragma("unroll") for(int r=0;r<16;++r)P0[r]=__builtin_amdgcn_exp2f(P0[r]); }while(0)
;   #define ROT() do{sl_prev=sl_cur;sl_cur=sl_next;sl_next=(sl_next==(NSLOT-1)*SLOTB)?0:sl_next+SLOTB;}while(0)
; template<int MODE,int THRL> __device__ __forceinline__ void attn_unit(const bf16*Qw0,int PQ,const bf16*__restrict__ Kh,int PK,const bf16*__restrict__ Vh,int PV,bf16*Ow0,int PO,int NT,int nabase,int nar0,const float*rpbh,char*shm,int&rot,bool pre,bool hasn,long dKn,long dVn){
;     ...
;   float mhat=0.f,l_reg=0.f;constexpr int ND=(MODE==2)?4:2; f32x16 o[4];o[0]=f32x16{};o[1]=f32x16{};o[2]=f32x16{};o[3]=f32x16{};f32x16 negm=f32x16{};asm volatile("":"+v"(negm));
;     ...
;   START(pA0,pA1);
;   _Pragma("unroll") for(int r=0;r<16;++r)pA1[r]=__builtin_amdgcn_exp2f(pA1[r]);
;   WAIT_BAR(0);
;   DMA_K(3,sl_cur);DMA_V(1,sl_next);
;   ROT();
;   kload8(kf,kp0+sl_cur);
;   if(MODE==2){WAIT_BAR(3);}else{WAIT_BAR(2);}
	v_exp_f32_e32 v82, v2
	v_exp_f32_e32 v83, v3
	v_lshl_add_u64 v[2:3], v[38:39], 0, s[62:63]
	s_mov_b32 s7, m0
	s_mov_b32 m0, s6
	s_nop 0
	global_load_lds_dwordx4 v[2:3], off
	s_mov_b32 m0, s7
	s_lshl_b32 s6, s15, 1
	s_add_i32 s6, s6, s1
	v_lshl_add_u64 v[2:3], v[224:225], 0, s[58:59]
	s_mov_b32 s7, m0
	s_mov_b32 m0, s6
	s_nop 0
	global_load_lds_dwordx4 v[2:3], off
	s_mov_b32 m0, s7
	s_addk_i32 s6, 0x2000
	s_cmpk_lg_i32 s15, 0x4000
	s_cselect_b32 s84, s4, 0
	s_lshl_b32 s33, s96, 2
	v_sub_f32_e32 v4, v4, v1
	v_sub_f32_e32 v21, v21, v1
	v_sub_f32_e32 v5, v5, v1
	v_sub_f32_e32 v22, v22, v1
	v_sub_f32_e32 v6, v6, v1
	v_sub_f32_e32 v23, v23, v1
	v_sub_f32_e32 v7, v7, v1
	v_sub_f32_e32 v24, v24, v1
	v_sub_f32_e32 v8, v8, v1
	v_sub_f32_e32 v25, v25, v1
	v_sub_f32_e32 v9, v9, v1
	v_sub_f32_e32 v26, v26, v1
	v_sub_f32_e32 v10, v10, v1
	v_sub_f32_e32 v27, v27, v1
	v_sub_f32_e32 v11, v11, v1
	v_sub_f32_e32 v28, v28, v1
	v_sub_f32_e32 v12, v12, v1
	v_sub_f32_e32 v29, v29, v1
	v_sub_f32_e32 v13, v13, v1
	v_sub_f32_e32 v30, v30, v1
	v_sub_f32_e32 v14, v14, v1
	v_sub_f32_e32 v31, v31, v1
	v_sub_f32_e32 v15, v15, v1
	v_sub_f32_e32 v32, v32, v1
	v_sub_f32_e32 v16, v16, v1
	v_sub_f32_e32 v33, v33, v1
	v_sub_f32_e32 v1, v17, v1
	s_and_b32 s90, s33, 0x700
	v_exp_f32_e32 v97, v1
	v_lshl_add_u64 v[2:3], v[224:225], 0, s[64:65]
	s_mov_b32 s7, m0
	s_mov_b32 m0, s6
	s_nop 0
	global_load_lds_dwordx4 v[2:3], off
	s_mov_b32 m0, s7
	v_add_u32_e32 v1, s15, v248
	s_or_b32 s8, s8, s90
	s_and_b32 s33, s33, 0x80
	ds_read_b128 v[206:209], v1
	ds_read_b128 v[198:201], v1 offset:512
	ds_read_b128 v[202:205], v1 offset:2048
	ds_read_b128 v[194:197], v1 offset:2560
	ds_read_b128 v[190:193], v1 offset:4096
	ds_read_b128 v[186:189], v1 offset:4608
	ds_read_b128 v[182:185], v1 offset:6144
	ds_read_b128 v[178:181], v1 offset:6656
	s_or_b32 s33, s8, s33
	s_lshl_b64 s[86:87], s[86:87], 1
	s_mul_hi_i32 s4, s76, 0x3180000
	s_add_u32 s86, s33, s86
	s_addc_u32 s87, s4, s87
	v_lshl_add_u64 v[210:211], s[86:87], 0, v[34:35]
	s_lshl_b64 s[86:87], s[88:89], 1
	v_and_b32_e32 v1, 3, v40
	s_add_u32 s86, s86, s8
	v_lshlrev_b32_e32 v2, 4, v1
	v_mov_b32_e32 v3, v0
	s_addc_u32 s87, s87, s4
	v_lshl_add_u64 v[2:3], s[86:87], 0, v[2:3]
	v_exp_f32_e32 v98, v18
	v_exp_f32_e32 v99, v19
	v_exp_f32_e32 v100, v20
	v_exp_f32_e32 v101, v21
	v_exp_f32_e32 v102, v22
	v_exp_f32_e32 v103, v23
	v_exp_f32_e32 v104, v24
	v_exp_f32_e32 v105, v25
	v_exp_f32_e32 v106, v26
	v_exp_f32_e32 v107, v27
	v_exp_f32_e32 v108, v28
	v_exp_f32_e32 v109, v29
	v_exp_f32_e32 v110, v30
	v_exp_f32_e32 v111, v31
	v_exp_f32_e32 v112, v32
	v_exp_f32_e32 v113, v33
	v_exp_f32_e32 v84, v4
	v_exp_f32_e32 v85, v5
	v_exp_f32_e32 v86, v6
	v_exp_f32_e32 v87, v7
	v_exp_f32_e32 v88, v8
	v_exp_f32_e32 v89, v9
	v_exp_f32_e32 v90, v10
	v_exp_f32_e32 v91, v11
	v_exp_f32_e32 v92, v12
	v_exp_f32_e32 v93, v13
	v_exp_f32_e32 v94, v14
	v_exp_f32_e32 v95, v15
	v_exp_f32_e32 v96, v16
	v_lshl_add_u64 v[2:3], v[2:3], 0, v[36:37]
	v_mov_b32_e32 v14, v0
	v_mov_b32_e32 v15, v0
	s_waitcnt vmcnt(3) lgkmcnt(0)
	s_barrier
	v_lshl_add_u64 v[214:215], s[50:51], 0, v[2:3]
	v_mov_b32_e32 v1, v0
	v_mov_b32_e32 v2, v0
	v_mov_b32_e32 v3, v0
	v_mov_b32_e32 v4, v0
	v_mov_b32_e32 v5, v0
	v_mov_b32_e32 v6, v0
	v_mov_b32_e32 v7, v0
	v_mov_b32_e32 v8, v0
	v_mov_b32_e32 v9, v0
	v_mov_b32_e32 v10, v0
	v_mov_b32_e32 v11, v0
	v_mov_b32_e32 v12, v0
	v_mov_b32_e32 v13, v0
	v_mov_b32_e32 v64, v14
	v_mov_b32_e32 v65, v15
	v_mov_b32_e32 v48, v14
	v_mov_b32_e32 v49, v15
	v_mov_b32_e32 v32, v14
	v_mov_b32_e32 v33, v15
	v_mov_b32_e32 v62, v12
	v_mov_b32_e32 v63, v13
	v_mov_b32_e32 v60, v10
	v_mov_b32_e32 v61, v11
	v_mov_b32_e32 v58, v8
	v_mov_b32_e32 v59, v9
	v_mov_b32_e32 v56, v6
	v_mov_b32_e32 v57, v7
	v_mov_b32_e32 v54, v4
	v_mov_b32_e32 v55, v5
	v_mov_b32_e32 v52, v2
	v_mov_b32_e32 v53, v3
	v_mov_b32_e32 v50, v0
	v_mov_b32_e32 v51, v1
	v_mov_b32_e32 v46, v12
	v_mov_b32_e32 v47, v13
	v_mov_b32_e32 v44, v10
	v_mov_b32_e32 v45, v11
	v_mov_b32_e32 v42, v8
	v_mov_b32_e32 v43, v9
	v_mov_b32_e32 v40, v6
	v_mov_b32_e32 v41, v7
	v_mov_b32_e32 v38, v4
	v_mov_b32_e32 v39, v5
	v_mov_b32_e32 v36, v2
	v_mov_b32_e32 v37, v3
	v_mov_b32_e32 v34, v0
	v_mov_b32_e32 v35, v1
	v_mov_b32_e32 v30, v12
	v_mov_b32_e32 v31, v13
	v_mov_b32_e32 v28, v10
	v_mov_b32_e32 v29, v11
	v_mov_b32_e32 v26, v8
	v_mov_b32_e32 v27, v9
	v_mov_b32_e32 v24, v6
	v_mov_b32_e32 v25, v7
	v_mov_b32_e32 v22, v4
	v_mov_b32_e32 v23, v5
	v_mov_b32_e32 v20, v2
	v_mov_b32_e32 v21, v3
	v_mov_b32_e32 v18, v0
	v_mov_b32_e32 v19, v1
	v_mov_b32_e32 v16, v14
	v_mov_b32_e32 v17, v15
	v_cmp_gt_u32_e64 s[6:7], 32, v237
	v_lshl_add_u64 v[212:213], s[40:41], 0, v[210:211]
	s_mov_b32 s90, -1
	v_mov_b32_e32 v14, v12
	v_mov_b32_e32 v15, v13
	v_mov_b32_e32 v12, v10
	v_mov_b32_e32 v13, v11
	v_mov_b32_e32 v10, v8
	v_mov_b32_e32 v11, v9
	v_mov_b32_e32 v8, v6
	v_mov_b32_e32 v9, v7
	v_mov_b32_e32 v6, v4
	v_mov_b32_e32 v7, v5
	v_mov_b32_e32 v4, v2
	v_mov_b32_e32 v5, v3
	v_mov_b32_e32 v2, v0
	v_mov_b32_e32 v3, v1

; #define WAIT_BAR(N) asm volatile("s_waitcnt vmcnt(" #N ") lgkmcnt(0)\n\ts_barrier":::"memory")
;   #define RESC() do{ if(resc){ asm volatile("s_waitcnt lgkmcnt(0)":::"memory"); \
;       _Pragma("unroll") for(int d_=0;d_<ND;++d_) _Pragma("unroll") for(int r=0;r<16;++r)o[d_][r]*=wsf[crow(r,hi)]; } }while(0)
;   #define ROT() do{sl_prev=sl_cur;sl_cur=sl_next;sl_next=(sl_next==(NSLOT-1)*SLOTB)?0:sl_next+SLOTB;}while(0)
; template<int MODE,int THRL> __device__ __forceinline__ void attn_unit(const bf16*Qw0,int PQ,const bf16*__restrict__ Kh,int PK,const bf16*__restrict__ Vh,int PV,bf16*Ow0,int PO,int NT,int nabase,int nar0,const float*rpbh,char*shm,int&rot,bool pre,bool hasn,long dKn,long dVn){
;     ...
;   for(;t+5<NT;t+=2){
;     STEP(pB0,pB1,pA0,pA1,t,true,true,true);     if(MODE==2){WAIT_BAR(3);}else{WAIT_BAR(2);} RESC(); ROT();
;     STEP(pA0,pA1,pB0,pB1,t+1,true,true,true);   if(MODE==2){WAIT_BAR(3);}else{WAIT_BAR(2);} RESC(); ROT();
;   }
.LBB0_1132:
	s_add_i32 s8, s4, 0x2000
	s_cmpk_lg_i32 s4, 0x4000
	s_cselect_b32 s8, s8, 0
	s_add_i32 s90, s90, 2
	s_cmpk_lt_u32 s90, 0x7d
	v_lshl_add_u64 v[212:213], v[212:213], 0, s[60:61]
	s_cbranch_scc0 .LBB0_1140
	v_mov_b32_e32 v214, v216
	v_mov_b32_e32 v215, v217
	s_mov_b32 s9, s84
	s_mov_b32 s15, s4
	s_mov_b32 s84, s8
	s_branch .LBB0_1126

; __device__ __forceinline__ unsigned xb_ld(unsigned* p)              { return __hip_atomic_load(p, __ATOMIC_RELAXED, __HIP_MEMORY_SCOPE_AGENT); }
; __device__ __forceinline__ unsigned xb_add(unsigned* p, unsigned v) { return __hip_atomic_fetch_add(p, v, __ATOMIC_RELAXED, __HIP_MEMORY_SCOPE_AGENT); }
; #define XB_SPIN(cond, bar) do { unsigned _sp = 0; while (cond) { __builtin_amdgcn_s_sleep(1); \
;     if ((++_sp & 255u) == 0u) { if (xb_ld(&(bar)[XB_TMO])) break; if (_sp > XB_SPIN_CAP) { atomicAdd(&(bar)[XB_TMO], 1u); break; } } } } while (0)
; __device__ __forceinline__ void xcd_barrier(const XcdBarrier& b) {
;     ...
;             const unsigned og = xb_add(&bar[XB_TOP], 1u);
;             const unsigned tg = og / nx;
;             if (og + 1u == (tg + 1u) * nx) xb_add(&bar[XB_TOPGEN], 1u);
;             else XB_SPIN(xb_ld(&bar[XB_TOPGEN]) == tg, bar);
.LBB0_1272:
	s_or_b64 exec, exec, s[16:17]
	v_cvt_f32_u32_e32 v3, v0
	s_waitcnt vmcnt(0)
	v_readfirstlane_b32 s1, v2
	s_add_u32 s16, s30, 0x1bbc3500
	s_addc_u32 s17, s31, 0
	v_rcp_iflag_f32_e32 v3, v3
	v_add_u32_e32 v1, s1, v1
	v_add_u32_e32 v4, 1, v1
	s_mov_b64 s[18:19], -1
	v_mul_f32_e32 v2, 0x4f7ffffe, v3
	v_cvt_u32_f32_e32 v2, v2
	v_sub_u32_e32 v3, 0, v0
	v_mul_lo_u32 v3, v3, v2
	v_mul_hi_u32 v3, v2, v3
	v_add_u32_e32 v2, v2, v3
	v_mul_hi_u32 v2, v1, v2
	v_mul_lo_u32 v3, v2, v0
	v_sub_u32_e32 v1, v1, v3
	v_add_u32_e32 v5, 1, v2
	v_cmp_ge_u32_e32 vcc, v1, v0
	v_sub_u32_e32 v3, v1, v0
	s_nop 0
	v_cndmask_b32_e32 v2, v2, v5, vcc
	v_cndmask_b32_e32 v1, v1, v3, vcc
	v_add_u32_e32 v3, 1, v2
	v_cmp_ge_u32_e32 vcc, v1, v0
	s_nop 1
	v_cndmask_b32_e32 v2, v2, v3, vcc
	v_mul_lo_u32 v1, v0, v2
	v_add_u32_e32 v0, v1, v0
	v_cmp_ne_u32_e32 vcc, v4, v0
	v_mov_b32_e32 v0, s16
	v_mov_b32_e32 v1, s17
	s_and_saveexec_b64 s[10:11], vcc
	s_cbranch_execz .LBB0_1284
	v_mov_b32_e32 v0, 0
	global_load_dword v1, v0, s[16:17] sc1
	s_mov_b64 s[22:23], 0
	s_waitcnt vmcnt(0)
	v_cmp_eq_u32_e32 vcc, v1, v2
	s_and_saveexec_b64 s[20:21], vcc
	s_cbranch_execz .LBB0_1283
	s_add_u32 s18, s30, 0x1bbc0200
	s_addc_u32 s19, s31, 0
	s_mov_b32 s1, 1
	s_branch .LBB0_1276

; __device__ __forceinline__ unsigned xb_ld(unsigned* p)              { return __hip_atomic_load(p, __ATOMIC_RELAXED, __HIP_MEMORY_SCOPE_AGENT); }
; #define XB_SPIN(cond, bar) do { unsigned _sp = 0; while (cond) { __builtin_amdgcn_s_sleep(1); \
;     if ((++_sp & 255u) == 0u) { if (xb_ld(&(bar)[XB_TMO])) break; if (_sp > XB_SPIN_CAP) { atomicAdd(&(bar)[XB_TMO], 1u); break; } } } } while (0)
; __device__ __forceinline__ void xcd_barrier(const XcdBarrier& b) {
;     ...
;             else XB_SPIN(xb_ld(&bar[XB_TOPGEN]) == tg, bar);
.LBB0_1283:
	s_or_b64 exec, exec, s[20:21]
	v_mov_b32_e32 v0, s18
	v_mov_b32_e32 v1, s19
	s_orn2_b64 s[18:19], s[22:23], exec

; __device__ __forceinline__ void norm_mod_phase(const float* lat, long lat_bs, const float* cx, long ctx_bs, const float* modl, int shoff, int scoff, bf16* XN, int skip_ctx, int gw, int NGW, float* xcopy, const float* part, int nkc, const float* pgate) {
;     int t_ = threadIdx.x; asm volatile("" : "+v"(t_)); const int lane = t_ & 63;
;     f32x4 vn[4]; int sn = 0;
;     { if (gw < MROWS) { const float* src = row_src(gw, lat, lat_bs, cx, ctx_bs, sn); const f32x4* xr = (const f32x4*)src + lane;
; #pragma unroll
;         for (int j = 0; j < 4; ++j) vn[j] = xr[64 * j]; } }
;     for (int row = gw; row < MROWS; row += NGW) {
;         const int s = sn; f32x4 v[4]; float ss = 0.f;
; #pragma unroll
;         for (int j = 0; j < 4; ++j) v[j] = vn[j];
;         if (row + NGW < MROWS) { const float* srcn = row_src(row + NGW, lat, lat_bs, cx, ctx_bs, sn); const f32x4* xr = (const f32x4*)srcn + lane;
; #pragma unroll
;             for (int j = 0; j < 4; ++j) vn[j] = xr[64 * j]; }
.LBB0_1370:
	s_or_b64 exec, exec, s[6:7]
	v_readlane_b32 s4, v254, 6
	v_readlane_b32 s5, v254, 7
	s_waitcnt lgkmcnt(0)
	v_mov_b32_e32 v0, v222
	s_and_b64 vcc, exec, s[4:5]
	s_barrier
	s_cbranch_vccnz .LBB0_1377
	v_readlane_b32 s3, v254, 5
	s_lshr_b32 s1, s3, 31
	s_ashr_i32 s3, s3, 11
	s_add_i32 s1, s3, s1
	s_mul_i32 s3, s1, 0xffffdf00
	v_readlane_b32 s4, v254, 8
	s_add_i32 s3, s3, s4
	v_readlane_b32 s5, v254, 9
	s_cmpk_lt_i32 s3, 0x100
	s_mov_b32 s18, s4
	s_cselect_b64 s[4:5], -1, 0
	s_add_i32 s8, s3, 0xffffff00
	s_ashr_i32 s9, s3, 31
	s_and_b64 s[6:7], s[4:5], exec
	s_mul_i32 s11, s1, 0x2100000
	s_cselect_b32 s6, s48, s82
	s_mul_hi_i32 s10, s1, 0x2100000
	s_cselect_b32 s9, s9, 0
	s_cselect_b32 s8, s3, s8
	s_cselect_b32 s3, s49, s0
	s_add_u32 s7, s6, s11
	s_addc_u32 s3, s3, s10
	s_and_b64 s[4:5], s[4:5], exec
	s_cselect_b32 s6, 4, s1
	s_lshl_b64 s[4:5], s[8:9], 12
	v_and_b32_e32 v8, 63, v0
	s_add_u32 s4, s7, s4
	s_addc_u32 s5, s3, s5
	v_lshlrev_b32_e32 v9, 4, v8
	global_load_dwordx4 v[0:3], v9, s[4:5] offset:3072
	global_load_dwordx4 v[4:7], v9, s[4:5] offset:2048
	global_load_dwordx4 v[24:27], v9, s[4:5] offset:1024
	global_load_dwordx4 v[28:31], v9, s[4:5]
	s_mov_b32 s12, s18
	s_ashr_i32 s19, s18, 31
	v_writelane_b32 v254, s12, 8
	v_mov_b32_e32 v33, 0
	v_lshlrev_b32_e32 v32, 3, v8
	v_writelane_b32 v254, s13, 9
	s_lshl_b64 s[12:13], s[18:19], 11
	s_add_u32 s12, s30, s12
	s_addc_u32 s13, s31, s13
	s_mov_b64 s[16:17], 0xb3c0000
	v_lshl_add_u64 v[10:11], s[12:13], 0, v[32:33]
	s_ashr_i32 s43, s42, 31
	v_lshlrev_b32_e32 v32, 4, v8
	v_lshl_add_u64 v[34:35], v[10:11], 0, s[16:17]
	v_mov_b32_e32 v36, 0x358637bd
	s_mov_b32 s1, 0xf800000
	v_mov_b32_e32 v37, 0x260
	s_mov_b64 s[8:9], 0x3000
	s_mov_b64 s[10:11], 0x4000
	s_movk_i32 s3, 0x4000
	s_movk_i32 s4, 0x7fff
	s_mov_b32 s5, 0xffff0000
	s_mov_b32 s14, s18
	s_lshl_b64 s[12:13], s[42:43], 11
	s_mov_b32 s15, s6
	s_waitcnt vmcnt(3)
	v_mov_b32_e32 v10, v2
	v_mov_b32_e32 v11, v3
	s_waitcnt vmcnt(2)
	v_mov_b32_e32 v14, v6
	v_mov_b32_e32 v15, v7
	s_waitcnt vmcnt(1)
	v_mov_b32_e32 v16, v24
	v_mov_b32_e32 v17, v25
	s_waitcnt vmcnt(0)
	v_mov_b32_e32 v20, v28
	v_mov_b32_e32 v21, v29
	v_mov_b32_e32 v8, v0
	v_mov_b32_e32 v9, v1
	v_mov_b32_e32 v12, v4
	v_mov_b32_e32 v13, v5
	v_mov_b32_e32 v18, v26
	v_mov_b32_e32 v19, v27
	v_mov_b32_e32 v22, v30
	v_mov_b32_e32 v23, v31
	s_branch .LBB0_1373
.LBB0_1372:
	s_waitcnt vmcnt(0)
	v_mov_b32_e32 v0, v8
	v_mov_b32_e32 v1, v9
	v_mov_b32_e32 v4, v12
	v_mov_b32_e32 v5, v13
	v_mov_b32_e32 v26, v18
	v_mov_b32_e32 v27, v19
	v_mov_b32_e32 v30, v22
	v_mov_b32_e32 v31, v23
	v_lshl_add_u64 v[34:35], v[34:35], 0, s[12:13]
	s_andn2_b64 vcc, exec, s[16:17]
	v_mov_b32_e32 v2, v10
	v_mov_b32_e32 v3, v11
	v_mov_b32_e32 v6, v14
	v_mov_b32_e32 v7, v15
	v_mov_b32_e32 v24, v16
	v_mov_b32_e32 v25, v17
	v_mov_b32_e32 v28, v20
	v_mov_b32_e32 v29, v21
	s_mov_b32 s6, s15
	s_cbranch_vccz .LBB0_1377

; __device__ __forceinline__ unsigned xb_ld(unsigned* p)              { return __hip_atomic_load(p, __ATOMIC_RELAXED, __HIP_MEMORY_SCOPE_AGENT); }
; __device__ __forceinline__ unsigned xb_add(unsigned* p, unsigned v) { return __hip_atomic_fetch_add(p, v, __ATOMIC_RELAXED, __HIP_MEMORY_SCOPE_AGENT); }
; #define XB_SPIN(cond, bar) do { unsigned _sp = 0; while (cond) { __builtin_amdgcn_s_sleep(1); \
;     if ((++_sp & 255u) == 0u) { if (xb_ld(&(bar)[XB_TMO])) break; if (_sp > XB_SPIN_CAP) { atomicAdd(&(bar)[XB_TMO], 1u); break; } } } } while (0)
; __device__ __forceinline__ void xcd_barrier(const XcdBarrier& b) {
;     ...
;             const unsigned og = xb_add(&bar[XB_TOP], 1u);
;             const unsigned tg = og / nx;
;             if (og + 1u == (tg + 1u) * nx) xb_add(&bar[XB_TOPGEN], 1u);
;             else XB_SPIN(xb_ld(&bar[XB_TOPGEN]) == tg, bar);
.LBB0_1412:
	s_or_b64 exec, exec, s[12:13]
	v_cvt_f32_u32_e32 v3, v0
	s_waitcnt vmcnt(0)
	v_readfirstlane_b32 s1, v2
	s_add_u32 s12, s30, 0x1bbc3500
	s_addc_u32 s13, s31, 0
	v_rcp_iflag_f32_e32 v3, v3
	v_add_u32_e32 v1, s1, v1
	v_add_u32_e32 v4, 1, v1
	s_mov_b64 s[16:17], -1
	v_mul_f32_e32 v2, 0x4f7ffffe, v3
	v_cvt_u32_f32_e32 v2, v2
	v_sub_u32_e32 v3, 0, v0
	v_mul_lo_u32 v3, v3, v2
	v_mul_hi_u32 v3, v2, v3
	v_add_u32_e32 v2, v2, v3
	v_mul_hi_u32 v2, v1, v2
	v_mul_lo_u32 v3, v2, v0
	v_sub_u32_e32 v1, v1, v3
	v_add_u32_e32 v5, 1, v2
	v_cmp_ge_u32_e32 vcc, v1, v0
	v_sub_u32_e32 v3, v1, v0
	s_nop 0
	v_cndmask_b32_e32 v2, v2, v5, vcc
	v_cndmask_b32_e32 v1, v1, v3, vcc
	v_add_u32_e32 v3, 1, v2
	v_cmp_ge_u32_e32 vcc, v1, v0
	s_nop 1
	v_cndmask_b32_e32 v2, v2, v3, vcc
	v_mul_lo_u32 v1, v0, v2
	v_add_u32_e32 v0, v1, v0
	v_cmp_ne_u32_e32 vcc, v4, v0
	v_mov_b32_e32 v0, s12
	v_mov_b32_e32 v1, s13
	s_and_saveexec_b64 s[10:11], vcc
	s_cbranch_execz .LBB0_1424
	v_mov_b32_e32 v0, 0
	global_load_dword v1, v0, s[12:13] sc1
	s_mov_b64 s[20:21], 0
	s_waitcnt vmcnt(0)
	v_cmp_eq_u32_e32 vcc, v1, v2
	s_and_saveexec_b64 s[18:19], vcc
	s_cbranch_execz .LBB0_1423
	s_add_u32 s16, s30, 0x1bbc0200
	s_addc_u32 s17, s31, 0
	s_mov_b32 s1, 1
	s_branch .LBB0_1416

; __device__ __forceinline__ unsigned xb_ld(unsigned* p)              { return __hip_atomic_load(p, __ATOMIC_RELAXED, __HIP_MEMORY_SCOPE_AGENT); }
; #define XB_SPIN(cond, bar) do { unsigned _sp = 0; while (cond) { __builtin_amdgcn_s_sleep(1); \
;     if ((++_sp & 255u) == 0u) { if (xb_ld(&(bar)[XB_TMO])) break; if (_sp > XB_SPIN_CAP) { atomicAdd(&(bar)[XB_TMO], 1u); break; } } } } while (0)
; __device__ __forceinline__ void xcd_barrier(const XcdBarrier& b) {
;     ...
;             else XB_SPIN(xb_ld(&bar[XB_TOPGEN]) == tg, bar);
.LBB0_1423:
	s_or_b64 exec, exec, s[18:19]
	v_mov_b32_e32 v0, s16
	v_mov_b32_e32 v1, s17
	s_orn2_b64 s[16:17], s[20:21], exec

; __device__ __forceinline__ unsigned cvt_pk_bf16(float lo, float hi) { unsigned r; asm volatile("v_cvt_pk_bf16_f32 %0, %1, %2" : "=v"(r) : "v"(lo), "v"(hi)); return r; }
;     __device__ __forceinline__ void operator()(const f32x4 (&acc)[2][2][4][2], const Unit& u, int wr, int wc, int fr, int fq) const {
;         const int row0 = u.pm * BM + wr * 64 + fr, col0 = u.pn * HALF + wc * 32 + 8 * fq;
; #pragma unroll
;         for (int ai = 0; ai < 2; ++ai)
; #pragma unroll
;             for (int m = 0; m < 4; ++m) { bf16_t* rowp = H + (size_t)(row0 + ai * HALF + m * 16) * ldh + col0; float hv[8];
; #pragma unroll
;                 for (int n = 0; n < 2; ++n)
; #pragma unroll
;                     for (int e = 0; e < 4; ++e) { const float g = acc[ai][0][m][n][e], up = acc[ai][1][m][n][e]; hv[n * 4 + e] = g * __builtin_amdgcn_rcpf(1.0f + __expf(-g)) * up; }
;                 u32x4 w; w.x = cvt_pk_bf16(hv[0], hv[1]); w.y = cvt_pk_bf16(hv[2], hv[3]); w.z = cvt_pk_bf16(hv[4], hv[5]); w.w = cvt_pk_bf16(hv[6], hv[7]);
;                 *(u32x4*)rowp = w; }
.LBB0_1441:
	v_mul_f32_e32 v144, 0xbfb8aa3b, v124
	v_exp_f32_e32 v168, v144
	v_mul_f32_e32 v144, 0xbfb8aa3b, v125
	v_exp_f32_e32 v169, v144
	v_lshl_or_b32 v166, s33, 7, v148
	v_add_f32_e32 v168, 1.0, v168
	v_rcp_f32_e32 v170, v168
	v_add_f32_e32 v168, 1.0, v169
	v_rcp_f32_e32 v171, v168
	v_lshl_add_u32 v165, s24, 8, v146
	v_mul_f32_e32 v124, v124, v170
	v_mul_f32_e32 v116, v124, v116
	v_mul_f32_e32 v124, v125, v171
	v_mul_f32_e32 v125, 0xbfb8aa3b, v126
	v_exp_f32_e32 v125, v125
	v_mul_f32_e32 v170, 0xbfb8aa3b, v127
	v_exp_f32_e32 v170, v170
	v_mul_f32_e32 v117, v124, v117
	v_add_f32_e32 v124, 1.0, v125
	v_rcp_f32_e32 v124, v124
	v_add_f32_e32 v125, 1.0, v170
	v_mul_f32_e32 v170, 0xbfb8aa3b, v120
	v_rcp_f32_e32 v125, v125
	v_exp_f32_e32 v170, v170
	v_mul_f32_e32 v124, v126, v124
	v_mul_f32_e32 v124, v124, v118
	v_mul_f32_e32 v118, v127, v125
	v_add_f32_e32 v125, 1.0, v170
	v_rcp_f32_e32 v125, v125
	v_mul_f32_e32 v126, 0xbfb8aa3b, v121
	v_mul_f32_e32 v127, v118, v119
	v_exp_f32_e32 v126, v126
	v_mul_f32_e32 v118, v120, v125
	v_mul_f32_e32 v120, v118, v112
	v_mul_f32_e32 v118, 0xbfb8aa3b, v122
	v_exp_f32_e32 v118, v118
	v_mul_f32_e32 v119, 0xbfb8aa3b, v123
	v_exp_f32_e32 v119, v119
	v_add_f32_e32 v112, 1.0, v126
	v_rcp_f32_e32 v112, v112
	v_add_f32_e32 v118, 1.0, v118
	v_rcp_f32_e32 v118, v118
	v_add_f32_e32 v119, 1.0, v119
	v_rcp_f32_e32 v119, v119
	v_mul_f32_e32 v112, v121, v112
	v_mul_f32_e32 v121, v112, v113
	v_mul_f32_e32 v112, v122, v118
	v_ashrrev_i32_e32 v167, 31, v166
	v_mov_b32_e32 v144, s44
	v_mov_b32_e32 v145, s45
	v_mul_f32_e32 v122, v112, v114
	v_mul_f32_e32 v112, v123, v119
	v_mad_i64_i32 v[168:169], s[36:37], v165, s65, v[144:145]
	v_mul_f32_e32 v123, v112, v115
	v_lshlrev_b64 v[112:113], 1, v[166:167]
	v_lshl_add_u64 v[118:119], v[168:169], 0, v[112:113]
	v_cvt_pk_bf16_f32 v114, v116, v117
	v_cvt_pk_bf16_f32 v115, v124, v127
	v_cvt_pk_bf16_f32 v116, v120, v121
	v_cvt_pk_bf16_f32 v117, v122, v123
	global_store_dwordx4 v[118:119], v[114:117], off
	s_andn2_b64 vcc, exec, s[6:7]
	s_mov_b64 s[6:7], -1
	v_mul_f32_e32 v114, 0xbfb8aa3b, v108
	v_exp_f32_e32 v114, v114
	v_mul_f32_e32 v115, 0xbfb8aa3b, v109
	v_exp_f32_e32 v115, v115
	v_or_b32_e32 v116, 16, v165
	v_add_f32_e32 v114, 1.0, v114
	v_rcp_f32_e32 v117, v114
	v_add_f32_e32 v114, 1.0, v115
	v_rcp_f32_e32 v118, v114
	v_mad_i64_i32 v[114:115], s[36:37], v116, s65, v[144:145]
	v_mul_f32_e32 v108, v108, v117
	v_mul_f32_e32 v108, v108, v100
	v_mul_f32_e32 v100, v109, v118
	v_mul_f32_e32 v109, 0xbfb8aa3b, v110
	v_exp_f32_e32 v109, v109
	v_mul_f32_e32 v116, 0xbfb8aa3b, v111
	v_exp_f32_e32 v116, v116
	v_mul_f32_e32 v117, v100, v101
	v_add_f32_e32 v100, 1.0, v109
	v_rcp_f32_e32 v100, v100
	v_add_f32_e32 v101, 1.0, v116
	v_mul_f32_e32 v109, 0xbfb8aa3b, v104
	v_rcp_f32_e32 v101, v101
	v_exp_f32_e32 v109, v109
	v_mul_f32_e32 v100, v110, v100
	v_mul_f32_e32 v102, v100, v102
	v_mul_f32_e32 v100, v111, v101
	v_add_f32_e32 v101, 1.0, v109
	v_rcp_f32_e32 v101, v101
	v_mul_f32_e32 v109, 0xbfb8aa3b, v105
	v_mul_f32_e32 v103, v100, v103
	v_exp_f32_e32 v109, v109
	v_mul_f32_e32 v100, v104, v101
	v_mul_f32_e32 v104, v100, v96
	v_mul_f32_e32 v100, 0xbfb8aa3b, v106
	v_exp_f32_e32 v100, v100
	v_mul_f32_e32 v101, 0xbfb8aa3b, v107
	v_exp_f32_e32 v101, v101
	v_add_f32_e32 v96, 1.0, v109
	v_rcp_f32_e32 v96, v96
	v_add_f32_e32 v100, 1.0, v100
	v_rcp_f32_e32 v100, v100
	v_add_f32_e32 v101, 1.0, v101
	v_rcp_f32_e32 v101, v101
	v_mul_f32_e32 v96, v105, v96
	v_mul_f32_e32 v105, v96, v97
	v_mul_f32_e32 v96, v106, v100
	v_mul_f32_e32 v106, v96, v98
	v_mul_f32_e32 v96, v107, v101
	v_mul_f32_e32 v99, v96, v99
	v_lshl_add_u64 v[100:101], v[114:115], 0, v[112:113]
	v_cvt_pk_bf16_f32 v96, v108, v117
	v_cvt_pk_bf16_f32 v97, v102, v103
	v_cvt_pk_bf16_f32 v98, v104, v105
	v_cvt_pk_bf16_f32 v99, v106, v99
	global_store_dwordx4 v[100:101], v[96:99], off
	s_nop 1
	v_mul_f32_e32 v96, 0xbfb8aa3b, v92
	v_exp_f32_e32 v96, v96
	v_mul_f32_e32 v97, 0xbfb8aa3b, v93
	v_exp_f32_e32 v97, v97
	v_or_b32_e32 v98, 32, v165
	v_add_f32_e32 v96, 1.0, v96
	v_rcp_f32_e32 v99, v96
	v_add_f32_e32 v96, 1.0, v97
	v_rcp_f32_e32 v100, v96
	v_mad_i64_i32 v[96:97], s[36:37], v98, s65, v[144:145]
	v_mul_f32_e32 v92, v92, v99
	v_mul_f32_e32 v92, v92, v84
	v_mul_f32_e32 v84, v93, v100
	v_mul_f32_e32 v93, 0xbfb8aa3b, v94
	v_exp_f32_e32 v93, v93
	v_mul_f32_e32 v98, 0xbfb8aa3b, v95
	v_exp_f32_e32 v98, v98
	v_mul_f32_e32 v99, v84, v85
	v_add_f32_e32 v84, 1.0, v93
	v_rcp_f32_e32 v84, v84
	v_add_f32_e32 v85, 1.0, v98
	v_mul_f32_e32 v93, 0xbfb8aa3b, v88
	v_rcp_f32_e32 v85, v85
	v_exp_f32_e32 v93, v93
	v_mul_f32_e32 v84, v94, v84
	v_mul_f32_e32 v86, v84, v86
	v_mul_f32_e32 v84, v95, v85
	v_add_f32_e32 v85, 1.0, v93
	v_rcp_f32_e32 v85, v85
	v_mul_f32_e32 v93, 0xbfb8aa3b, v89
	v_mul_f32_e32 v87, v84, v87
	v_exp_f32_e32 v93, v93
	v_mul_f32_e32 v84, v88, v85
	v_mul_f32_e32 v88, v84, v80
	v_mul_f32_e32 v84, 0xbfb8aa3b, v90
	v_exp_f32_e32 v84, v84
	v_mul_f32_e32 v85, 0xbfb8aa3b, v91
	v_exp_f32_e32 v85, v85
	v_add_f32_e32 v80, 1.0, v93
	v_rcp_f32_e32 v80, v80
	v_add_f32_e32 v84, 1.0, v84
	v_rcp_f32_e32 v84, v84
	v_add_f32_e32 v85, 1.0, v85
	v_rcp_f32_e32 v85, v85
	v_mul_f32_e32 v80, v89, v80
	v_mul_f32_e32 v89, v80, v81
	v_mul_f32_e32 v80, v90, v84
	v_mul_f32_e32 v90, v80, v82
	v_mul_f32_e32 v80, v91, v85
	v_mul_f32_e32 v83, v80, v83
	v_lshl_add_u64 v[84:85], v[96:97], 0, v[112:113]
	v_cvt_pk_bf16_f32 v80, v92, v99
	v_cvt_pk_bf16_f32 v81, v86, v87
	v_cvt_pk_bf16_f32 v82, v88, v89
	v_cvt_pk_bf16_f32 v83, v90, v83
	global_store_dwordx4 v[84:85], v[80:83], off
	s_nop 1
	v_mul_f32_e32 v80, 0xbfb8aa3b, v76
	v_exp_f32_e32 v80, v80
	v_mul_f32_e32 v81, 0xbfb8aa3b, v77
; __device__ __forceinline__ unsigned cvt_pk_bf16(float lo, float hi) { unsigned r; asm volatile("v_cvt_pk_bf16_f32 %0, %1, %2" : "=v"(r) : "v"(lo), "v"(hi)); return r; }
;     __device__ __forceinline__ void operator()(const f32x4 (&acc)[2][2][4][2], const Unit& u, int wr, int wc, int fr, int fq) const {
;     ...
;         for (int ai = 0; ai < 2; ++ai)
; #pragma unroll
;             for (int m = 0; m < 4; ++m) { bf16_t* rowp = H + (size_t)(row0 + ai * HALF + m * 16) * ldh + col0; float hv[8];
; #pragma unroll
;                 for (int n = 0; n < 2; ++n)
; #pragma unroll
;                     for (int e = 0; e < 4; ++e) { const float g = acc[ai][0][m][n][e], up = acc[ai][1][m][n][e]; hv[n * 4 + e] = g * __builtin_amdgcn_rcpf(1.0f + __expf(-g)) * up; }
;                 u32x4 w; w.x = cvt_pk_bf16(hv[0], hv[1]); w.y = cvt_pk_bf16(hv[2], hv[3]); w.z = cvt_pk_bf16(hv[4], hv[5]); w.w = cvt_pk_bf16(hv[6], hv[7]);
;                 *(u32x4*)rowp = w; }
	v_exp_f32_e32 v81, v81
	v_or_b32_e32 v82, 48, v165
	v_add_f32_e32 v80, 1.0, v80
	v_rcp_f32_e32 v83, v80
	v_add_f32_e32 v80, 1.0, v81
	v_rcp_f32_e32 v84, v80
	v_mad_i64_i32 v[80:81], s[36:37], v82, s65, v[144:145]
	v_mul_f32_e32 v76, v76, v83
	v_mul_f32_e32 v76, v76, v68
	v_mul_f32_e32 v68, v77, v84
	v_mul_f32_e32 v77, 0xbfb8aa3b, v78
	v_exp_f32_e32 v77, v77
	v_mul_f32_e32 v82, 0xbfb8aa3b, v79
	v_exp_f32_e32 v82, v82
	v_mul_f32_e32 v83, v68, v69
	v_add_f32_e32 v68, 1.0, v77
	v_rcp_f32_e32 v68, v68
	v_add_f32_e32 v69, 1.0, v82
	v_mul_f32_e32 v77, 0xbfb8aa3b, v72
	v_rcp_f32_e32 v69, v69
	v_exp_f32_e32 v77, v77
	v_mul_f32_e32 v68, v78, v68
	v_mul_f32_e32 v70, v68, v70
	v_mul_f32_e32 v68, v79, v69
	v_add_f32_e32 v69, 1.0, v77
	v_rcp_f32_e32 v69, v69
	v_mul_f32_e32 v77, 0xbfb8aa3b, v73
	v_mul_f32_e32 v71, v68, v71
	v_exp_f32_e32 v77, v77
	v_mul_f32_e32 v68, v72, v69
	v_mul_f32_e32 v72, v68, v64
	v_mul_f32_e32 v68, 0xbfb8aa3b, v74
	v_exp_f32_e32 v68, v68
	v_mul_f32_e32 v69, 0xbfb8aa3b, v75
	v_exp_f32_e32 v69, v69
	v_add_f32_e32 v64, 1.0, v77
	v_rcp_f32_e32 v64, v64
	v_add_f32_e32 v68, 1.0, v68
	v_rcp_f32_e32 v68, v68
	v_add_f32_e32 v69, 1.0, v69
	v_rcp_f32_e32 v69, v69
	v_mul_f32_e32 v64, v73, v64
	v_mul_f32_e32 v73, v64, v65
	v_mul_f32_e32 v64, v74, v68
	v_mul_f32_e32 v74, v64, v66
	v_mul_f32_e32 v64, v75, v69
	v_mul_f32_e32 v67, v64, v67
	v_lshl_add_u64 v[68:69], v[80:81], 0, v[112:113]
	v_cvt_pk_bf16_f32 v64, v76, v83
	v_cvt_pk_bf16_f32 v65, v70, v71
	v_cvt_pk_bf16_f32 v66, v72, v73
	v_cvt_pk_bf16_f32 v67, v74, v67
	global_store_dwordx4 v[68:69], v[64:67], off
	s_nop 1
	v_mul_f32_e32 v64, 0xbfb8aa3b, v60
	v_exp_f32_e32 v64, v64
	v_mul_f32_e32 v65, 0xbfb8aa3b, v61
	v_exp_f32_e32 v65, v65
	v_add_u32_e32 v66, 0x80, v165
	v_add_f32_e32 v64, 1.0, v64
	v_rcp_f32_e32 v67, v64
	v_add_f32_e32 v64, 1.0, v65
	v_rcp_f32_e32 v68, v64
	v_mad_i64_i32 v[64:65], s[36:37], v66, s65, v[144:145]
	v_mul_f32_e32 v60, v60, v67
	v_mul_f32_e32 v60, v60, v52
	v_mul_f32_e32 v52, v61, v68
	v_mul_f32_e32 v61, 0xbfb8aa3b, v62
	v_exp_f32_e32 v61, v61
	v_mul_f32_e32 v66, 0xbfb8aa3b, v63
	v_exp_f32_e32 v66, v66
	v_mul_f32_e32 v67, v52, v53
	v_add_f32_e32 v52, 1.0, v61
	v_rcp_f32_e32 v52, v52
	v_add_f32_e32 v53, 1.0, v66
	v_mul_f32_e32 v61, 0xbfb8aa3b, v56
	v_rcp_f32_e32 v53, v53
	v_exp_f32_e32 v61, v61
	v_mul_f32_e32 v52, v62, v52
	v_mul_f32_e32 v54, v52, v54
	v_mul_f32_e32 v52, v63, v53
	v_add_f32_e32 v53, 1.0, v61
	v_rcp_f32_e32 v53, v53
	v_mul_f32_e32 v61, 0xbfb8aa3b, v57
	v_mul_f32_e32 v55, v52, v55
	v_exp_f32_e32 v61, v61
	v_mul_f32_e32 v52, v56, v53
	v_mul_f32_e32 v56, v52, v48
	v_mul_f32_e32 v52, 0xbfb8aa3b, v58
	v_exp_f32_e32 v52, v52
	v_mul_f32_e32 v53, 0xbfb8aa3b, v59
	v_exp_f32_e32 v53, v53
	v_add_f32_e32 v48, 1.0, v61
	v_rcp_f32_e32 v48, v48
	v_add_f32_e32 v52, 1.0, v52
	v_rcp_f32_e32 v52, v52
	v_add_f32_e32 v53, 1.0, v53
	v_rcp_f32_e32 v53, v53
	v_mul_f32_e32 v48, v57, v48
	v_mul_f32_e32 v57, v48, v49
	v_mul_f32_e32 v48, v58, v52
	v_mul_f32_e32 v58, v48, v50
	v_mul_f32_e32 v48, v59, v53
	v_mul_f32_e32 v51, v48, v51
	v_lshl_add_u64 v[52:53], v[64:65], 0, v[112:113]
	v_cvt_pk_bf16_f32 v48, v60, v67
	v_cvt_pk_bf16_f32 v49, v54, v55
	v_cvt_pk_bf16_f32 v50, v56, v57
	v_cvt_pk_bf16_f32 v51, v58, v51
	global_store_dwordx4 v[52:53], v[48:51], off
	s_nop 1
	v_mul_f32_e32 v48, 0xbfb8aa3b, v44
	v_exp_f32_e32 v48, v48
	v_mul_f32_e32 v49, 0xbfb8aa3b, v45
	v_exp_f32_e32 v49, v49
	v_add_u32_e32 v50, 0x90, v165
	v_add_f32_e32 v48, 1.0, v48
	v_rcp_f32_e32 v51, v48
	v_add_f32_e32 v48, 1.0, v49
	v_rcp_f32_e32 v52, v48
	v_mad_i64_i32 v[48:49], s[36:37], v50, s65, v[144:145]
	v_mul_f32_e32 v44, v44, v51
	v_mul_f32_e32 v44, v44, v36
	v_mul_f32_e32 v36, v45, v52
	v_mul_f32_e32 v45, 0xbfb8aa3b, v46
	v_exp_f32_e32 v45, v45
	v_mul_f32_e32 v50, 0xbfb8aa3b, v47
	v_exp_f32_e32 v50, v50
	v_mul_f32_e32 v51, v36, v37
	v_add_f32_e32 v36, 1.0, v45
	v_rcp_f32_e32 v36, v36
	v_add_f32_e32 v37, 1.0, v50
	v_mul_f32_e32 v45, 0xbfb8aa3b, v40
	v_rcp_f32_e32 v37, v37
	v_exp_f32_e32 v45, v45
	v_mul_f32_e32 v36, v46, v36
	v_mul_f32_e32 v38, v36, v38
	v_mul_f32_e32 v36, v47, v37
	v_add_f32_e32 v37, 1.0, v45
	v_rcp_f32_e32 v37, v37
	v_mul_f32_e32 v45, 0xbfb8aa3b, v41
	v_mul_f32_e32 v39, v36, v39
; __device__ __forceinline__ unsigned cvt_pk_bf16(float lo, float hi) { unsigned r; asm volatile("v_cvt_pk_bf16_f32 %0, %1, %2" : "=v"(r) : "v"(lo), "v"(hi)); return r; }
; #define PG8_BAR __builtin_amdgcn_s_barrier()
;     __device__ __forceinline__ void operator()(const f32x4 (&acc)[2][2][4][2], const Unit& u, int wr, int wc, int fr, int fq) const {
;     ...
;         for (int ai = 0; ai < 2; ++ai)
; #pragma unroll
;             for (int m = 0; m < 4; ++m) { bf16_t* rowp = H + (size_t)(row0 + ai * HALF + m * 16) * ldh + col0; float hv[8];
; #pragma unroll
;                 for (int n = 0; n < 2; ++n)
; #pragma unroll
;                     for (int e = 0; e < 4; ++e) { const float g = acc[ai][0][m][n][e], up = acc[ai][1][m][n][e]; hv[n * 4 + e] = g * __builtin_amdgcn_rcpf(1.0f + __expf(-g)) * up; }
;                 u32x4 w; w.x = cvt_pk_bf16(hv[0], hv[1]); w.y = cvt_pk_bf16(hv[2], hv[3]); w.z = cvt_pk_bf16(hv[4], hv[5]); w.w = cvt_pk_bf16(hv[6], hv[7]);
;                 *(u32x4*)rowp = w; }
; template <class Epi, class Sched, bool ALIGN_EPI = false, bool SP2 = false>
; __device__ __forceinline__ void gemm_phase(PG8_LAS unsigned char* lds, const Gemm g, const Sched& S, const Epi& E) {
;     ...
;         if constexpr (ALIGN_EPI) { if (wr == 0) PG8_BAR; }
;         if constexpr (!Epi::AFTER_DRAIN) { E(acc, cur, wr, wc, fr, fq); S.done(cur); }
;         if (!has_next) break;
; #pragma unroll
;         for (int a = 0; a < 2; ++a)
; #pragma unroll
;             for (int b = 0; b < 2; ++b)
; #pragma unroll
;                 for (int m = 0; m < 4; ++m)
; #pragma unroll
;                     for (int n = 0; n < 2; ++n) acc[a][b][m][n] = (f32x4){0.f, 0.f, 0.f, 0.f};
;         cur = nxt; cA = nA; cB = nB; ++ui;
;         if constexpr (ALIGN_EPI) { if (wr == 1) PG8_BAR; }
	v_exp_f32_e32 v45, v45
	v_mul_f32_e32 v36, v40, v37
	v_mul_f32_e32 v40, v36, v32
	v_mul_f32_e32 v36, 0xbfb8aa3b, v42
	v_exp_f32_e32 v36, v36
	v_mul_f32_e32 v37, 0xbfb8aa3b, v43
	v_exp_f32_e32 v37, v37
	v_add_f32_e32 v32, 1.0, v45
	v_rcp_f32_e32 v32, v32
	v_add_f32_e32 v36, 1.0, v36
	v_rcp_f32_e32 v36, v36
	v_add_f32_e32 v37, 1.0, v37
	v_rcp_f32_e32 v37, v37
	v_mul_f32_e32 v32, v41, v32
	v_mul_f32_e32 v41, v32, v33
	v_mul_f32_e32 v32, v42, v36
	v_mul_f32_e32 v42, v32, v34
	v_mul_f32_e32 v32, v43, v37
	v_mul_f32_e32 v35, v32, v35
	v_lshl_add_u64 v[36:37], v[48:49], 0, v[112:113]
	v_cvt_pk_bf16_f32 v32, v44, v51
	v_cvt_pk_bf16_f32 v33, v38, v39
	v_cvt_pk_bf16_f32 v34, v40, v41
	v_cvt_pk_bf16_f32 v35, v42, v35
	global_store_dwordx4 v[36:37], v[32:35], off
	s_nop 1
	v_mul_f32_e32 v32, 0xbfb8aa3b, v28
	v_exp_f32_e32 v32, v32
	v_mul_f32_e32 v33, 0xbfb8aa3b, v29
	v_exp_f32_e32 v33, v33
	v_add_u32_e32 v34, 0xa0, v165
	v_add_f32_e32 v32, 1.0, v32
	v_rcp_f32_e32 v35, v32
	v_add_f32_e32 v32, 1.0, v33
	v_rcp_f32_e32 v36, v32
	v_mad_i64_i32 v[32:33], s[36:37], v34, s65, v[144:145]
	v_mul_f32_e32 v28, v28, v35
	v_mul_f32_e32 v28, v28, v20
	v_mul_f32_e32 v20, v29, v36
	v_mul_f32_e32 v29, 0xbfb8aa3b, v30
	v_exp_f32_e32 v29, v29
	v_mul_f32_e32 v34, 0xbfb8aa3b, v31
	v_exp_f32_e32 v34, v34
	v_mul_f32_e32 v35, v20, v21
	v_add_f32_e32 v20, 1.0, v29
	v_rcp_f32_e32 v20, v20
	v_add_f32_e32 v21, 1.0, v34
	v_mul_f32_e32 v29, 0xbfb8aa3b, v24
	v_rcp_f32_e32 v21, v21
	v_exp_f32_e32 v29, v29
	v_mul_f32_e32 v20, v30, v20
	v_mul_f32_e32 v22, v20, v22
	v_mul_f32_e32 v20, v31, v21
	v_add_f32_e32 v21, 1.0, v29
	v_rcp_f32_e32 v21, v21
	v_mul_f32_e32 v29, 0xbfb8aa3b, v25
	v_mul_f32_e32 v23, v20, v23
	v_exp_f32_e32 v29, v29
	v_mul_f32_e32 v20, v24, v21
	v_mul_f32_e32 v24, v20, v16
	v_mul_f32_e32 v20, 0xbfb8aa3b, v26
	v_exp_f32_e32 v20, v20
	v_mul_f32_e32 v21, 0xbfb8aa3b, v27
	v_exp_f32_e32 v21, v21
	v_add_f32_e32 v16, 1.0, v29
	v_rcp_f32_e32 v16, v16
	v_add_f32_e32 v20, 1.0, v20
	v_rcp_f32_e32 v20, v20
	v_add_f32_e32 v21, 1.0, v21
	v_rcp_f32_e32 v21, v21
	v_mul_f32_e32 v16, v25, v16
	v_mul_f32_e32 v25, v16, v17
	v_mul_f32_e32 v16, v26, v20
	v_mul_f32_e32 v26, v16, v18
	v_mul_f32_e32 v16, v27, v21
	v_mul_f32_e32 v19, v16, v19
	v_lshl_add_u64 v[20:21], v[32:33], 0, v[112:113]
	v_cvt_pk_bf16_f32 v16, v28, v35
	v_cvt_pk_bf16_f32 v17, v22, v23
	v_cvt_pk_bf16_f32 v18, v24, v25
	v_cvt_pk_bf16_f32 v19, v26, v19
	global_store_dwordx4 v[20:21], v[16:19], off
	s_nop 1
	v_mul_f32_e32 v16, 0xbfb8aa3b, v12
	v_exp_f32_e32 v16, v16
	v_mul_f32_e32 v17, 0xbfb8aa3b, v13
	v_exp_f32_e32 v17, v17
	v_add_u32_e32 v18, 0xb0, v165
	v_add_f32_e32 v16, 1.0, v16
	v_rcp_f32_e32 v19, v16
	v_add_f32_e32 v16, 1.0, v17
	v_rcp_f32_e32 v20, v16
	v_mad_i64_i32 v[16:17], s[36:37], v18, s65, v[144:145]
	v_mul_f32_e32 v12, v12, v19
	v_mul_f32_e32 v12, v12, v4
	v_mul_f32_e32 v4, v13, v20
	v_mul_f32_e32 v13, 0xbfb8aa3b, v14
	v_exp_f32_e32 v13, v13
	v_mul_f32_e32 v18, 0xbfb8aa3b, v15
	v_exp_f32_e32 v18, v18
	v_mul_f32_e32 v19, v4, v5
	v_add_f32_e32 v4, 1.0, v13
	v_rcp_f32_e32 v4, v4
	v_add_f32_e32 v5, 1.0, v18
	v_mul_f32_e32 v13, 0xbfb8aa3b, v8
	v_rcp_f32_e32 v5, v5
	v_exp_f32_e32 v13, v13
	v_mul_f32_e32 v4, v14, v4
	v_mul_f32_e32 v6, v4, v6
	v_mul_f32_e32 v4, v15, v5
	v_add_f32_e32 v5, 1.0, v13
	v_rcp_f32_e32 v5, v5
	v_mul_f32_e32 v13, 0xbfb8aa3b, v9
	v_mul_f32_e32 v7, v4, v7
	v_exp_f32_e32 v13, v13
	v_mul_f32_e32 v4, v8, v5
	v_mul_f32_e32 v8, v4, v0
	v_mul_f32_e32 v4, 0xbfb8aa3b, v10
	v_exp_f32_e32 v4, v4
	v_mul_f32_e32 v5, 0xbfb8aa3b, v11
	v_exp_f32_e32 v5, v5
	v_add_f32_e32 v0, 1.0, v13
	v_rcp_f32_e32 v0, v0
	v_add_f32_e32 v4, 1.0, v4
	v_rcp_f32_e32 v4, v4
	v_add_f32_e32 v5, 1.0, v5
	v_rcp_f32_e32 v5, v5
	v_mul_f32_e32 v0, v9, v0
	v_mul_f32_e32 v9, v0, v1
	v_mul_f32_e32 v0, v10, v4
	v_mul_f32_e32 v10, v0, v2
	v_mul_f32_e32 v0, v11, v5
	v_mul_f32_e32 v3, v0, v3
	v_lshl_add_u64 v[4:5], v[16:17], 0, v[112:113]
	v_cvt_pk_bf16_f32 v0, v12, v19
	v_cvt_pk_bf16_f32 v1, v6, v7
	v_cvt_pk_bf16_f32 v2, v8, v9
	v_cvt_pk_bf16_f32 v3, v10, v3
	global_store_dwordx4 v[4:5], v[0:3], off
	s_cbranch_vccnz .LBB0_1434
	s_andn2_b64 vcc, exec, s[8:9]
	s_cbranch_vccnz .LBB0_1433
	s_barrier
	s_branch .LBB0_1433

; __device__ __forceinline__ unsigned xb_ld(unsigned* p)              { return __hip_atomic_load(p, __ATOMIC_RELAXED, __HIP_MEMORY_SCOPE_AGENT); }
; __device__ __forceinline__ unsigned xb_add(unsigned* p, unsigned v) { return __hip_atomic_fetch_add(p, v, __ATOMIC_RELAXED, __HIP_MEMORY_SCOPE_AGENT); }
; #define XB_SPIN(cond, bar) do { unsigned _sp = 0; while (cond) { __builtin_amdgcn_s_sleep(1); \
;     if ((++_sp & 255u) == 0u) { if (xb_ld(&(bar)[XB_TMO])) break; if (_sp > XB_SPIN_CAP) { atomicAdd(&(bar)[XB_TMO], 1u); break; } } } } while (0)
; __device__ __forceinline__ void xcd_barrier(const XcdBarrier& b) {
;     ...
;             const unsigned og = xb_add(&bar[XB_TOP], 1u);
;             const unsigned tg = og / nx;
;             if (og + 1u == (tg + 1u) * nx) xb_add(&bar[XB_TOPGEN], 1u);
;             else XB_SPIN(xb_ld(&bar[XB_TOPGEN]) == tg, bar);
.LBB0_1564:
	s_or_b64 exec, exec, s[6:7]
	v_cvt_f32_u32_e32 v3, v0
	s_waitcnt vmcnt(0)
	v_readfirstlane_b32 s4, v2
	s_add_u32 s6, s30, 0x1bbc3500
	s_addc_u32 s7, s31, 0
	v_rcp_iflag_f32_e32 v3, v3
	v_add_u32_e32 v1, s4, v1
	v_add_u32_e32 v4, 1, v1
	s_mov_b64 s[8:9], -1
	v_mul_f32_e32 v2, 0x4f7ffffe, v3
	v_cvt_u32_f32_e32 v2, v2
	v_sub_u32_e32 v3, 0, v0
	v_mul_lo_u32 v3, v3, v2
	v_mul_hi_u32 v3, v2, v3
	v_add_u32_e32 v2, v2, v3
	v_mul_hi_u32 v2, v1, v2
	v_mul_lo_u32 v3, v2, v0
	v_sub_u32_e32 v1, v1, v3
	v_add_u32_e32 v5, 1, v2
	v_cmp_ge_u32_e32 vcc, v1, v0
	v_sub_u32_e32 v3, v1, v0
	s_nop 0
	v_cndmask_b32_e32 v2, v2, v5, vcc
	v_cndmask_b32_e32 v1, v1, v3, vcc
	v_add_u32_e32 v3, 1, v2
	v_cmp_ge_u32_e32 vcc, v1, v0
	s_nop 1
	v_cndmask_b32_e32 v2, v2, v3, vcc
	v_mul_lo_u32 v1, v0, v2
	v_add_u32_e32 v0, v1, v0
	v_cmp_ne_u32_e32 vcc, v4, v0
	v_mov_b32_e32 v0, s6
	v_mov_b32_e32 v1, s7
	s_and_saveexec_b64 s[4:5], vcc
	s_cbranch_execz .LBB0_1576
	v_mov_b32_e32 v0, 0
	global_load_dword v1, v0, s[6:7] sc1
	s_mov_b64 s[12:13], 0
	s_waitcnt vmcnt(0)
	v_cmp_eq_u32_e32 vcc, v1, v2
	s_and_saveexec_b64 s[10:11], vcc
	s_cbranch_execz .LBB0_1575
	s_add_u32 s8, s30, 0x1bbc0200
	s_addc_u32 s9, s31, 0
	s_mov_b32 s22, 1
	s_branch .LBB0_1568

; __device__ __forceinline__ unsigned xb_ld(unsigned* p)              { return __hip_atomic_load(p, __ATOMIC_RELAXED, __HIP_MEMORY_SCOPE_AGENT); }
; #define XB_SPIN(cond, bar) do { unsigned _sp = 0; while (cond) { __builtin_amdgcn_s_sleep(1); \
;     if ((++_sp & 255u) == 0u) { if (xb_ld(&(bar)[XB_TMO])) break; if (_sp > XB_SPIN_CAP) { atomicAdd(&(bar)[XB_TMO], 1u); break; } } } } while (0)
; __device__ __forceinline__ void xcd_barrier(const XcdBarrier& b) {
;     ...
;             else XB_SPIN(xb_ld(&bar[XB_TOPGEN]) == tg, bar);
.LBB0_1575:
	s_or_b64 exec, exec, s[10:11]
	v_mov_b32_e32 v0, s8
	v_mov_b32_e32 v1, s9
	s_orn2_b64 s[8:9], s[12:13], exec
